# K-loop: the 6-piece load segments run at setprio 2 (above the partner's MFMA block at 1)
# speedup vs baseline: 1.0042x; 1.0042x over previous
.LBB0_322:
	s_ashr_i32 s43, s42, 31
	s_lshl_b64 s[46:47], s[42:43], 19
	s_add_u32 s46, s12, s46
	s_addc_u32 s47, s13, s47
	s_and_b64 s[48:49], s[4:5], exec
	s_cselect_b32 s18, s47, s7
	s_cselect_b32 s43, s46, s6
	s_ashr_i32 s45, s44, 31
	s_lshl_b64 s[48:49], s[44:45], 19
	s_add_u32 s48, s59, s48
	s_addc_u32 s49, s60, s49
	s_and_b64 s[50:51], s[4:5], exec
	s_cselect_b32 s45, s49, s9
	s_cselect_b32 s55, s48, s8
	s_add_u32 s6, s6, 0x40080
	s_addc_u32 s7, s7, 0
	s_add_u32 s56, s8, 0x100
	s_addc_u32 s57, s9, 0
	s_mov_b32 s78, -2
	ds_read_b128 v[96:99], v209
	ds_read_b128 v[100:103], v209 offset:1024
	ds_read_b128 v[120:123], v209 offset:2048
	ds_read_b128 v[124:127], v209 offset:3072
	ds_read_b128 v[144:147], v210
	ds_read_b128 v[148:151], v210 offset:1024
	ds_read_b128 v[152:155], v210 offset:2048
	ds_read_b128 v[156:159], v210 offset:3072
	s_add_u32 s8, s6, 0xfffc0080
	s_addc_u32 s9, s7, -1
	s_cmp_eq_u32 s78, 12
	s_cselect_b32 s51, s18, s9
	s_cselect_b32 s50, s43, s8
	s_cselect_b32 s9, s45, s57
	s_cselect_b32 s8, s55, s56
	v_lshl_add_u64 v[206:207], s[6:7], 0, v[170:171]
	s_add_i32 m0, s17, 0xc000
	ds_read_b128 v[178:181], v211
	ds_read_b128 v[182:185], v211 offset:1024
	ds_read_b128 v[186:189], v211 offset:2048
	ds_read_b128 v[190:193], v211 offset:3072
	ds_read_b128 v[194:197], v211 offset:4096
	ds_read_b128 v[198:201], v211 offset:5120
	ds_read_b128 v[202:205], v211 offset:6144
	ds_read_b128 v[218:221], v211 offset:7168
	global_load_lds_dwordx4 v[206:207], off
	s_add_i32 m0, s17, 0xe000
	v_lshl_add_u64 v[206:207], s[6:7], 0, v[172:173]
	global_load_lds_dwordx4 v[206:207], off
	s_waitcnt vmcnt(8)
	s_waitcnt lgkmcnt(0)
	s_barrier
	s_setprio 1
	s_waitcnt lgkmcnt(0)
	v_mfma_f32_16x16x32_bf16 v[140:143], v[96:99], v[178:181], 0
	v_mfma_f32_16x16x32_bf16 v[136:139], v[120:123], v[178:181], 0
	v_mfma_f32_16x16x32_bf16 v[116:119], v[96:99], v[186:189], 0
	v_mfma_f32_16x16x32_bf16 v[112:115], v[120:123], v[186:189], 0
	v_mfma_f32_16x16x32_bf16 v[92:95], v[96:99], v[194:197], 0
	v_mfma_f32_16x16x32_bf16 v[88:91], v[120:123], v[194:197], 0
	v_mfma_f32_16x16x32_bf16 v[76:79], v[96:99], v[202:205], 0
	v_mfma_f32_16x16x32_bf16 v[72:75], v[120:123], v[202:205], 0
	v_mfma_f32_16x16x32_bf16 v[140:143], v[100:103], v[182:185], v[140:143]
	v_mfma_f32_16x16x32_bf16 v[136:139], v[124:127], v[182:185], v[136:139]
	v_mfma_f32_16x16x32_bf16 v[116:119], v[100:103], v[190:193], v[116:119]
	v_mfma_f32_16x16x32_bf16 v[112:115], v[124:127], v[190:193], v[112:115]
	v_mfma_f32_16x16x32_bf16 v[92:95], v[100:103], v[198:201], v[92:95]
	v_mfma_f32_16x16x32_bf16 v[88:91], v[124:127], v[198:201], v[88:91]
	v_mfma_f32_16x16x32_bf16 v[76:79], v[100:103], v[218:221], v[76:79]
	v_mfma_f32_16x16x32_bf16 v[72:75], v[124:127], v[218:221], v[72:75]
	s_setprio 0
	s_setprio 1
	v_mfma_f32_16x16x32_bf16 v[132:135], v[144:147], v[178:181], 0
	v_mfma_f32_16x16x32_bf16 v[128:131], v[152:155], v[178:181], 0
	v_mfma_f32_16x16x32_bf16 v[108:111], v[144:147], v[186:189], 0
	v_mfma_f32_16x16x32_bf16 v[104:107], v[152:155], v[186:189], 0
	v_mfma_f32_16x16x32_bf16 v[84:87], v[144:147], v[194:197], 0
	v_mfma_f32_16x16x32_bf16 v[80:83], v[152:155], v[194:197], 0
	v_mfma_f32_16x16x32_bf16 v[68:71], v[144:147], v[202:205], 0
	v_mfma_f32_16x16x32_bf16 v[64:67], v[152:155], v[202:205], 0
	v_mfma_f32_16x16x32_bf16 v[132:135], v[148:151], v[182:185], v[132:135]
	v_mfma_f32_16x16x32_bf16 v[128:131], v[156:159], v[182:185], v[128:131]
	v_mfma_f32_16x16x32_bf16 v[108:111], v[148:151], v[190:193], v[108:111]
	v_mfma_f32_16x16x32_bf16 v[104:107], v[156:159], v[190:193], v[104:107]
	s_setprio 2
	s_barrier
	v_mfma_f32_16x16x32_bf16 v[84:87], v[148:151], v[198:201], v[84:87]
	v_mfma_f32_16x16x32_bf16 v[80:83], v[156:159], v[198:201], v[80:83]
	v_mfma_f32_16x16x32_bf16 v[68:71], v[148:151], v[218:221], v[68:71]
	v_mfma_f32_16x16x32_bf16 v[64:67], v[156:159], v[218:221], v[64:67]
	s_setprio 2
	s_add_i32 s79, s73, s61
	v_lshl_add_u64 v[206:207], s[8:9], 0, v[162:163]
	s_mov_b32 m0, s79
	ds_read_b128 v[178:181], v211 offset:16384
	ds_read_b128 v[182:185], v211 offset:17408
	ds_read_b128 v[186:189], v211 offset:18432
	ds_read_b128 v[190:193], v211 offset:19456
	ds_read_b128 v[194:197], v211 offset:20480
	ds_read_b128 v[198:201], v211 offset:21504
	ds_read_b128 v[202:205], v211 offset:22528
	ds_read_b128 v[218:221], v211 offset:23552
	global_load_lds_dwordx4 v[206:207], off
	s_add_i32 m0, s79, 0x2000
	s_add_u32 s80, s8, 0x40000
	v_lshl_add_u64 v[222:223], s[8:9], 0, v[166:167]
	s_addc_u32 s81, s9, 0
	s_add_i32 s79, s74, s61
	global_load_lds_dwordx4 v[222:223], off
	v_lshl_add_u64 v[224:225], s[80:81], 0, v[162:163]
	s_mov_b32 m0, s79
	v_lshl_add_u64 v[226:227], s[50:51], 0, v[164:165]
	global_load_lds_dwordx4 v[224:225], off
	s_add_i32 m0, s79, 0x2000
	v_lshl_add_u64 v[224:225], s[80:81], 0, v[166:167]
	global_load_lds_dwordx4 v[224:225], off
	s_mov_b32 m0, s17
	v_lshl_add_u64 v[224:225], s[50:51], 0, v[160:161]
	global_load_lds_dwordx4 v[224:225], off
	s_mov_b32 m0, s62
	s_nop 0
	global_load_lds_dwordx4 v[226:227], off
	s_waitcnt vmcnt(8)
	s_waitcnt lgkmcnt(0)
	s_barrier
	s_setprio 1
	s_waitcnt lgkmcnt(0)
	v_mfma_f32_16x16x32_bf16 v[60:63], v[96:99], v[178:181], 0
	v_mfma_f32_16x16x32_bf16 v[56:59], v[120:123], v[178:181], 0
	v_mfma_f32_16x16x32_bf16 v[44:47], v[96:99], v[186:189], 0
	v_mfma_f32_16x16x32_bf16 v[40:43], v[120:123], v[186:189], 0
	v_mfma_f32_16x16x32_bf16 v[28:31], v[96:99], v[194:197], 0
	v_mfma_f32_16x16x32_bf16 v[24:27], v[120:123], v[194:197], 0
	v_mfma_f32_16x16x32_bf16 v[12:15], v[96:99], v[202:205], 0
	v_mfma_f32_16x16x32_bf16 v[8:11], v[120:123], v[202:205], 0
	v_mfma_f32_16x16x32_bf16 v[60:63], v[100:103], v[182:185], v[60:63]
	v_mfma_f32_16x16x32_bf16 v[56:59], v[124:127], v[182:185], v[56:59]
	v_mfma_f32_16x16x32_bf16 v[44:47], v[100:103], v[190:193], v[44:47]
	v_mfma_f32_16x16x32_bf16 v[40:43], v[124:127], v[190:193], v[40:43]
	v_mfma_f32_16x16x32_bf16 v[28:31], v[100:103], v[198:201], v[28:31]
	v_mfma_f32_16x16x32_bf16 v[24:27], v[124:127], v[198:201], v[24:27]
	v_mfma_f32_16x16x32_bf16 v[12:15], v[100:103], v[218:221], v[12:15]
	v_mfma_f32_16x16x32_bf16 v[8:11], v[124:127], v[218:221], v[8:11]
	s_setprio 0
	s_setprio 1
	v_mfma_f32_16x16x32_bf16 v[52:55], v[144:147], v[178:181], 0
	v_mfma_f32_16x16x32_bf16 v[48:51], v[152:155], v[178:181], 0
	v_mfma_f32_16x16x32_bf16 v[36:39], v[144:147], v[186:189], 0
	v_mfma_f32_16x16x32_bf16 v[32:35], v[152:155], v[186:189], 0
	v_mfma_f32_16x16x32_bf16 v[20:23], v[144:147], v[194:197], 0
	v_mfma_f32_16x16x32_bf16 v[16:19], v[152:155], v[194:197], 0
	v_mfma_f32_16x16x32_bf16 v[4:7], v[144:147], v[202:205], 0
	v_mfma_f32_16x16x32_bf16 v[0:3], v[152:155], v[202:205], 0
	v_mfma_f32_16x16x32_bf16 v[52:55], v[148:151], v[182:185], v[52:55]
	v_mfma_f32_16x16x32_bf16 v[48:51], v[156:159], v[182:185], v[48:51]
	v_mfma_f32_16x16x32_bf16 v[36:39], v[148:151], v[190:193], v[36:39]
	v_mfma_f32_16x16x32_bf16 v[32:35], v[156:159], v[190:193], v[32:35]
	s_setprio 2
	s_barrier
	v_mfma_f32_16x16x32_bf16 v[20:23], v[148:151], v[198:201], v[20:23]
	v_mfma_f32_16x16x32_bf16 v[16:19], v[156:159], v[198:201], v[16:19]
	v_mfma_f32_16x16x32_bf16 v[4:7], v[148:151], v[218:221], v[4:7]
	v_mfma_f32_16x16x32_bf16 v[0:3], v[156:159], v[218:221], v[0:3]
	s_setprio 0
	s_add_i32 s79, 0, 0x18000
	s_add_i32 s80, 0, 0x1c000
	v_add_u32_e32 v124, s79, v208
	v_add_u32_e32 v156, s80, v208
	ds_read_b128 v[96:99], v124
	ds_read_b128 v[100:103], v124 offset:1024
	ds_read_b128 v[120:123], v124 offset:2048
	ds_read_b128 v[124:127], v124 offset:3072
	ds_read_b128 v[144:147], v156
	ds_read_b128 v[148:151], v156 offset:1024
	ds_read_b128 v[152:155], v156 offset:2048
	ds_read_b128 v[156:159], v156 offset:3072
	s_add_u32 s50, s50, 0x40000
	s_addc_u32 s51, s51, 0
	s_mov_b32 m0, s63
	v_lshl_add_u64 v[228:229], s[50:51], 0, v[160:161]
	ds_read_b128 v[178:181], v211 offset:32768
	ds_read_b128 v[182:185], v211 offset:33792
	ds_read_b128 v[186:189], v211 offset:34816
	ds_read_b128 v[190:193], v211 offset:35840
	ds_read_b128 v[194:197], v211 offset:36864
	ds_read_b128 v[198:201], v211 offset:37888
	ds_read_b128 v[202:205], v211 offset:38912
	ds_read_b128 v[218:221], v211 offset:39936
	global_load_lds_dwordx4 v[228:229], off
	s_mov_b32 m0, s64
	v_lshl_add_u64 v[228:229], s[50:51], 0, v[164:165]
	global_load_lds_dwordx4 v[228:229], off
	s_waitcnt vmcnt(8)
	s_waitcnt lgkmcnt(0)
	s_barrier
	s_setprio 1
	s_waitcnt lgkmcnt(0)
	v_mfma_f32_16x16x32_bf16 v[140:143], v[96:99], v[178:181], v[140:143]
	v_mfma_f32_16x16x32_bf16 v[136:139], v[120:123], v[178:181], v[136:139]
	v_mfma_f32_16x16x32_bf16 v[116:119], v[96:99], v[186:189], v[116:119]
	v_mfma_f32_16x16x32_bf16 v[112:115], v[120:123], v[186:189], v[112:115]
	v_mfma_f32_16x16x32_bf16 v[92:95], v[96:99], v[194:197], v[92:95]
	v_mfma_f32_16x16x32_bf16 v[88:91], v[120:123], v[194:197], v[88:91]
	v_mfma_f32_16x16x32_bf16 v[76:79], v[96:99], v[202:205], v[76:79]
	v_mfma_f32_16x16x32_bf16 v[72:75], v[120:123], v[202:205], v[72:75]
	v_mfma_f32_16x16x32_bf16 v[140:143], v[100:103], v[182:185], v[140:143]
	v_mfma_f32_16x16x32_bf16 v[136:139], v[124:127], v[182:185], v[136:139]
	v_mfma_f32_16x16x32_bf16 v[116:119], v[100:103], v[190:193], v[116:119]
	v_mfma_f32_16x16x32_bf16 v[112:115], v[124:127], v[190:193], v[112:115]
	v_mfma_f32_16x16x32_bf16 v[92:95], v[100:103], v[198:201], v[92:95]
	v_mfma_f32_16x16x32_bf16 v[88:91], v[124:127], v[198:201], v[88:91]
	v_mfma_f32_16x16x32_bf16 v[76:79], v[100:103], v[218:221], v[76:79]
	v_mfma_f32_16x16x32_bf16 v[72:75], v[124:127], v[218:221], v[72:75]
	s_setprio 0
	s_setprio 1
	v_mfma_f32_16x16x32_bf16 v[132:135], v[144:147], v[178:181], v[132:135]
	v_mfma_f32_16x16x32_bf16 v[128:131], v[152:155], v[178:181], v[128:131]
	v_mfma_f32_16x16x32_bf16 v[108:111], v[144:147], v[186:189], v[108:111]
	v_mfma_f32_16x16x32_bf16 v[104:107], v[152:155], v[186:189], v[104:107]
	v_mfma_f32_16x16x32_bf16 v[84:87], v[144:147], v[194:197], v[84:87]
	v_mfma_f32_16x16x32_bf16 v[80:83], v[152:155], v[194:197], v[80:83]
	v_mfma_f32_16x16x32_bf16 v[68:71], v[144:147], v[202:205], v[68:71]
	v_mfma_f32_16x16x32_bf16 v[64:67], v[152:155], v[202:205], v[64:67]
	v_mfma_f32_16x16x32_bf16 v[132:135], v[148:151], v[182:185], v[132:135]
	v_mfma_f32_16x16x32_bf16 v[128:131], v[156:159], v[182:185], v[128:131]
	v_mfma_f32_16x16x32_bf16 v[108:111], v[148:151], v[190:193], v[108:111]
	v_mfma_f32_16x16x32_bf16 v[104:107], v[156:159], v[190:193], v[104:107]
	s_setprio 2
	s_barrier
	v_mfma_f32_16x16x32_bf16 v[84:87], v[148:151], v[198:201], v[84:87]
	v_mfma_f32_16x16x32_bf16 v[80:83], v[156:159], v[198:201], v[80:83]
	v_mfma_f32_16x16x32_bf16 v[68:71], v[148:151], v[218:221], v[68:71]
	v_mfma_f32_16x16x32_bf16 v[64:67], v[156:159], v[218:221], v[64:67]
	s_setprio 2
	s_add_i32 s50, s79, s61
	v_lshl_add_u64 v[206:207], v[206:207], 0, s[36:37]
	s_mov_b32 m0, s50
	ds_read_b128 v[178:181], v211 offset:49152
	ds_read_b128 v[182:185], v211 offset:50176
	ds_read_b128 v[186:189], v211 offset:51200
	ds_read_b128 v[190:193], v211 offset:52224
	ds_read_b128 v[194:197], v211 offset:53248
	ds_read_b128 v[198:201], v211 offset:54272
	ds_read_b128 v[202:205], v211 offset:55296
	ds_read_b128 v[218:221], v211 offset:56320
	global_load_lds_dwordx4 v[206:207], off
	s_add_i32 m0, s50, 0x2000
	s_add_u32 s8, s8, 0x40080
	v_lshl_add_u64 v[206:207], v[222:223], 0, s[36:37]
	s_addc_u32 s9, s9, 0
	s_add_i32 s50, s80, s61
	global_load_lds_dwordx4 v[206:207], off
	s_mov_b32 m0, s50
	v_lshl_add_u64 v[206:207], s[8:9], 0, v[162:163]
	global_load_lds_dwordx4 v[206:207], off
	s_add_i32 m0, s50, 0x2000
	v_lshl_add_u64 v[206:207], s[8:9], 0, v[166:167]
	global_load_lds_dwordx4 v[206:207], off
	s_mov_b32 m0, s68
	v_lshl_add_u64 v[206:207], v[224:225], 0, s[36:37]
	global_load_lds_dwordx4 v[206:207], off
	s_mov_b32 m0, s69
	v_lshl_add_u64 v[206:207], v[226:227], 0, s[36:37]
	global_load_lds_dwordx4 v[206:207], off
	s_waitcnt vmcnt(8)
	s_waitcnt lgkmcnt(0)
	s_barrier
	s_setprio 1
	s_waitcnt lgkmcnt(0)
	v_mfma_f32_16x16x32_bf16 v[60:63], v[96:99], v[178:181], v[60:63]
	v_mfma_f32_16x16x32_bf16 v[56:59], v[120:123], v[178:181], v[56:59]
	v_mfma_f32_16x16x32_bf16 v[44:47], v[96:99], v[186:189], v[44:47]
	v_mfma_f32_16x16x32_bf16 v[40:43], v[120:123], v[186:189], v[40:43]
	v_mfma_f32_16x16x32_bf16 v[28:31], v[96:99], v[194:197], v[28:31]
	v_mfma_f32_16x16x32_bf16 v[24:27], v[120:123], v[194:197], v[24:27]
	v_mfma_f32_16x16x32_bf16 v[12:15], v[96:99], v[202:205], v[12:15]
	v_mfma_f32_16x16x32_bf16 v[8:11], v[120:123], v[202:205], v[8:11]
	v_mfma_f32_16x16x32_bf16 v[60:63], v[100:103], v[182:185], v[60:63]
	v_mfma_f32_16x16x32_bf16 v[56:59], v[124:127], v[182:185], v[56:59]
	v_mfma_f32_16x16x32_bf16 v[44:47], v[100:103], v[190:193], v[44:47]
	v_mfma_f32_16x16x32_bf16 v[40:43], v[124:127], v[190:193], v[40:43]
	v_mfma_f32_16x16x32_bf16 v[28:31], v[100:103], v[198:201], v[28:31]
	v_mfma_f32_16x16x32_bf16 v[24:27], v[124:127], v[198:201], v[24:27]
	v_mfma_f32_16x16x32_bf16 v[12:15], v[100:103], v[218:221], v[12:15]
	v_mfma_f32_16x16x32_bf16 v[8:11], v[124:127], v[218:221], v[8:11]
	s_setprio 0
	s_setprio 1
	v_mfma_f32_16x16x32_bf16 v[52:55], v[144:147], v[178:181], v[52:55]
	v_mfma_f32_16x16x32_bf16 v[48:51], v[152:155], v[178:181], v[48:51]
	v_mfma_f32_16x16x32_bf16 v[36:39], v[144:147], v[186:189], v[36:39]
	v_mfma_f32_16x16x32_bf16 v[32:35], v[152:155], v[186:189], v[32:35]
	v_mfma_f32_16x16x32_bf16 v[20:23], v[144:147], v[194:197], v[20:23]
	v_mfma_f32_16x16x32_bf16 v[16:19], v[152:155], v[194:197], v[16:19]
	v_mfma_f32_16x16x32_bf16 v[4:7], v[144:147], v[202:205], v[4:7]
	v_mfma_f32_16x16x32_bf16 v[0:3], v[152:155], v[202:205], v[0:3]
	v_mfma_f32_16x16x32_bf16 v[52:55], v[148:151], v[182:185], v[52:55]
	v_mfma_f32_16x16x32_bf16 v[48:51], v[156:159], v[182:185], v[48:51]
	v_mfma_f32_16x16x32_bf16 v[36:39], v[148:151], v[190:193], v[36:39]
	v_mfma_f32_16x16x32_bf16 v[32:35], v[156:159], v[190:193], v[32:35]
	s_setprio 2
	s_barrier
	v_mfma_f32_16x16x32_bf16 v[20:23], v[148:151], v[198:201], v[20:23]
	v_mfma_f32_16x16x32_bf16 v[16:19], v[156:159], v[198:201], v[16:19]
	v_mfma_f32_16x16x32_bf16 v[4:7], v[148:151], v[218:221], v[4:7]
	v_mfma_f32_16x16x32_bf16 v[0:3], v[156:159], v[218:221], v[0:3]
	s_setprio 0
	s_add_i32 s78, s78, 2
	s_add_u32 s6, s6, 0x100
	s_addc_u32 s7, s7, 0
	s_add_u32 s56, s56, 0x100
	s_addc_u32 s57, s57, 0
	s_cmp_gt_u32 s78, 13
.LBB0_323:
	ds_read_b128 v[96:99], v209
	ds_read_b128 v[100:103], v209 offset:1024
	ds_read_b128 v[120:123], v209 offset:2048
	ds_read_b128 v[124:127], v209 offset:3072
	ds_read_b128 v[144:147], v210
	ds_read_b128 v[148:151], v210 offset:1024
	ds_read_b128 v[152:155], v210 offset:2048
	ds_read_b128 v[156:159], v210 offset:3072
	s_add_u32 s8, s6, 0xfffc0080
	s_addc_u32 s9, s7, -1
	s_cmp_eq_u32 s78, 12
	s_cselect_b32 s51, s18, s9
	s_cselect_b32 s50, s43, s8
	s_cselect_b32 s9, s45, s57
	s_cselect_b32 s8, s55, s56
	v_lshl_add_u64 v[206:207], s[6:7], 0, v[170:171]
	s_add_i32 m0, s17, 0xc000
	ds_read_b128 v[178:181], v211
	ds_read_b128 v[182:185], v211 offset:1024
	ds_read_b128 v[186:189], v211 offset:2048
	ds_read_b128 v[190:193], v211 offset:3072
	ds_read_b128 v[194:197], v211 offset:4096
	ds_read_b128 v[198:201], v211 offset:5120
	ds_read_b128 v[202:205], v211 offset:6144
	ds_read_b128 v[218:221], v211 offset:7168
	global_load_lds_dwordx4 v[206:207], off
	s_add_i32 m0, s17, 0xe000
	v_lshl_add_u64 v[206:207], s[6:7], 0, v[172:173]
	global_load_lds_dwordx4 v[206:207], off
	s_waitcnt vmcnt(8)
	s_waitcnt lgkmcnt(0)
	s_barrier
	s_setprio 1
	s_waitcnt lgkmcnt(0)
	v_mfma_f32_16x16x32_bf16 v[140:143], v[96:99], v[178:181], v[140:143]
	v_mfma_f32_16x16x32_bf16 v[136:139], v[120:123], v[178:181], v[136:139]
	v_mfma_f32_16x16x32_bf16 v[116:119], v[96:99], v[186:189], v[116:119]
	v_mfma_f32_16x16x32_bf16 v[112:115], v[120:123], v[186:189], v[112:115]
	v_mfma_f32_16x16x32_bf16 v[92:95], v[96:99], v[194:197], v[92:95]
	v_mfma_f32_16x16x32_bf16 v[88:91], v[120:123], v[194:197], v[88:91]
	v_mfma_f32_16x16x32_bf16 v[76:79], v[96:99], v[202:205], v[76:79]
	v_mfma_f32_16x16x32_bf16 v[72:75], v[120:123], v[202:205], v[72:75]
	v_mfma_f32_16x16x32_bf16 v[140:143], v[100:103], v[182:185], v[140:143]
	v_mfma_f32_16x16x32_bf16 v[136:139], v[124:127], v[182:185], v[136:139]
	v_mfma_f32_16x16x32_bf16 v[116:119], v[100:103], v[190:193], v[116:119]
	v_mfma_f32_16x16x32_bf16 v[112:115], v[124:127], v[190:193], v[112:115]
	v_mfma_f32_16x16x32_bf16 v[92:95], v[100:103], v[198:201], v[92:95]
	v_mfma_f32_16x16x32_bf16 v[88:91], v[124:127], v[198:201], v[88:91]
	v_mfma_f32_16x16x32_bf16 v[76:79], v[100:103], v[218:221], v[76:79]
	v_mfma_f32_16x16x32_bf16 v[72:75], v[124:127], v[218:221], v[72:75]
	s_setprio 0
	s_setprio 1
	v_mfma_f32_16x16x32_bf16 v[132:135], v[144:147], v[178:181], v[132:135]
	v_mfma_f32_16x16x32_bf16 v[128:131], v[152:155], v[178:181], v[128:131]
	v_mfma_f32_16x16x32_bf16 v[108:111], v[144:147], v[186:189], v[108:111]
	v_mfma_f32_16x16x32_bf16 v[104:107], v[152:155], v[186:189], v[104:107]
	v_mfma_f32_16x16x32_bf16 v[84:87], v[144:147], v[194:197], v[84:87]
	v_mfma_f32_16x16x32_bf16 v[80:83], v[152:155], v[194:197], v[80:83]
	v_mfma_f32_16x16x32_bf16 v[68:71], v[144:147], v[202:205], v[68:71]
	v_mfma_f32_16x16x32_bf16 v[64:67], v[152:155], v[202:205], v[64:67]
	v_mfma_f32_16x16x32_bf16 v[132:135], v[148:151], v[182:185], v[132:135]
	v_mfma_f32_16x16x32_bf16 v[128:131], v[156:159], v[182:185], v[128:131]
	v_mfma_f32_16x16x32_bf16 v[108:111], v[148:151], v[190:193], v[108:111]
	v_mfma_f32_16x16x32_bf16 v[104:107], v[156:159], v[190:193], v[104:107]
	s_setprio 2
	s_barrier
	v_mfma_f32_16x16x32_bf16 v[84:87], v[148:151], v[198:201], v[84:87]
	v_mfma_f32_16x16x32_bf16 v[80:83], v[156:159], v[198:201], v[80:83]
	v_mfma_f32_16x16x32_bf16 v[68:71], v[148:151], v[218:221], v[68:71]
	v_mfma_f32_16x16x32_bf16 v[64:67], v[156:159], v[218:221], v[64:67]
	s_setprio 2
	s_add_i32 s79, s73, s61
	v_lshl_add_u64 v[206:207], s[8:9], 0, v[162:163]
	s_mov_b32 m0, s79
	ds_read_b128 v[178:181], v211 offset:16384
	ds_read_b128 v[182:185], v211 offset:17408
	ds_read_b128 v[186:189], v211 offset:18432
	ds_read_b128 v[190:193], v211 offset:19456
	ds_read_b128 v[194:197], v211 offset:20480
	ds_read_b128 v[198:201], v211 offset:21504
	ds_read_b128 v[202:205], v211 offset:22528
	ds_read_b128 v[218:221], v211 offset:23552
	global_load_lds_dwordx4 v[206:207], off
	s_add_i32 m0, s79, 0x2000
	s_add_u32 s80, s8, 0x40000
	v_lshl_add_u64 v[222:223], s[8:9], 0, v[166:167]
	s_addc_u32 s81, s9, 0
	s_add_i32 s79, s74, s61
	global_load_lds_dwordx4 v[222:223], off
	v_lshl_add_u64 v[224:225], s[80:81], 0, v[162:163]
	s_mov_b32 m0, s79
	v_lshl_add_u64 v[226:227], s[50:51], 0, v[164:165]
	global_load_lds_dwordx4 v[224:225], off
	s_add_i32 m0, s79, 0x2000
	v_lshl_add_u64 v[224:225], s[80:81], 0, v[166:167]
	global_load_lds_dwordx4 v[224:225], off
	s_mov_b32 m0, s17
	v_lshl_add_u64 v[224:225], s[50:51], 0, v[160:161]
	global_load_lds_dwordx4 v[224:225], off
	s_mov_b32 m0, s62
	s_nop 0
	global_load_lds_dwordx4 v[226:227], off
	s_waitcnt vmcnt(8)
	s_waitcnt lgkmcnt(0)
	s_barrier
	s_setprio 1
	s_waitcnt lgkmcnt(0)
	v_mfma_f32_16x16x32_bf16 v[60:63], v[96:99], v[178:181], v[60:63]
	v_mfma_f32_16x16x32_bf16 v[56:59], v[120:123], v[178:181], v[56:59]
	v_mfma_f32_16x16x32_bf16 v[44:47], v[96:99], v[186:189], v[44:47]
	v_mfma_f32_16x16x32_bf16 v[40:43], v[120:123], v[186:189], v[40:43]
	v_mfma_f32_16x16x32_bf16 v[28:31], v[96:99], v[194:197], v[28:31]
	v_mfma_f32_16x16x32_bf16 v[24:27], v[120:123], v[194:197], v[24:27]
	v_mfma_f32_16x16x32_bf16 v[12:15], v[96:99], v[202:205], v[12:15]
	v_mfma_f32_16x16x32_bf16 v[8:11], v[120:123], v[202:205], v[8:11]
	v_mfma_f32_16x16x32_bf16 v[60:63], v[100:103], v[182:185], v[60:63]
	v_mfma_f32_16x16x32_bf16 v[56:59], v[124:127], v[182:185], v[56:59]
	v_mfma_f32_16x16x32_bf16 v[44:47], v[100:103], v[190:193], v[44:47]
	v_mfma_f32_16x16x32_bf16 v[40:43], v[124:127], v[190:193], v[40:43]
	v_mfma_f32_16x16x32_bf16 v[28:31], v[100:103], v[198:201], v[28:31]
	v_mfma_f32_16x16x32_bf16 v[24:27], v[124:127], v[198:201], v[24:27]
	v_mfma_f32_16x16x32_bf16 v[12:15], v[100:103], v[218:221], v[12:15]
	v_mfma_f32_16x16x32_bf16 v[8:11], v[124:127], v[218:221], v[8:11]
	s_setprio 0
	s_setprio 1
	v_mfma_f32_16x16x32_bf16 v[52:55], v[144:147], v[178:181], v[52:55]
	v_mfma_f32_16x16x32_bf16 v[48:51], v[152:155], v[178:181], v[48:51]
	v_mfma_f32_16x16x32_bf16 v[36:39], v[144:147], v[186:189], v[36:39]
	v_mfma_f32_16x16x32_bf16 v[32:35], v[152:155], v[186:189], v[32:35]
	v_mfma_f32_16x16x32_bf16 v[20:23], v[144:147], v[194:197], v[20:23]
	v_mfma_f32_16x16x32_bf16 v[16:19], v[152:155], v[194:197], v[16:19]
	v_mfma_f32_16x16x32_bf16 v[4:7], v[144:147], v[202:205], v[4:7]
	v_mfma_f32_16x16x32_bf16 v[0:3], v[152:155], v[202:205], v[0:3]
	v_mfma_f32_16x16x32_bf16 v[52:55], v[148:151], v[182:185], v[52:55]
	v_mfma_f32_16x16x32_bf16 v[48:51], v[156:159], v[182:185], v[48:51]
	v_mfma_f32_16x16x32_bf16 v[36:39], v[148:151], v[190:193], v[36:39]
	v_mfma_f32_16x16x32_bf16 v[32:35], v[156:159], v[190:193], v[32:35]
	s_setprio 2
	s_barrier
	v_mfma_f32_16x16x32_bf16 v[20:23], v[148:151], v[198:201], v[20:23]
	v_mfma_f32_16x16x32_bf16 v[16:19], v[156:159], v[198:201], v[16:19]
	v_mfma_f32_16x16x32_bf16 v[4:7], v[148:151], v[218:221], v[4:7]
	v_mfma_f32_16x16x32_bf16 v[0:3], v[156:159], v[218:221], v[0:3]
	s_setprio 0
	s_add_i32 s79, 0, 0x18000
	s_add_i32 s80, 0, 0x1c000
	v_add_u32_e32 v124, s79, v208
	v_add_u32_e32 v156, s80, v208
	ds_read_b128 v[96:99], v124
	ds_read_b128 v[100:103], v124 offset:1024
	ds_read_b128 v[120:123], v124 offset:2048
	ds_read_b128 v[124:127], v124 offset:3072
	ds_read_b128 v[144:147], v156
	ds_read_b128 v[148:151], v156 offset:1024
	ds_read_b128 v[152:155], v156 offset:2048
	ds_read_b128 v[156:159], v156 offset:3072
	s_add_u32 s50, s50, 0x40000
	s_addc_u32 s51, s51, 0
	s_mov_b32 m0, s63
	v_lshl_add_u64 v[228:229], s[50:51], 0, v[160:161]
	ds_read_b128 v[178:181], v211 offset:32768
	ds_read_b128 v[182:185], v211 offset:33792
	ds_read_b128 v[186:189], v211 offset:34816
	ds_read_b128 v[190:193], v211 offset:35840
	ds_read_b128 v[194:197], v211 offset:36864
	ds_read_b128 v[198:201], v211 offset:37888
	ds_read_b128 v[202:205], v211 offset:38912
	ds_read_b128 v[218:221], v211 offset:39936
	global_load_lds_dwordx4 v[228:229], off
	s_mov_b32 m0, s64
	v_lshl_add_u64 v[228:229], s[50:51], 0, v[164:165]
	global_load_lds_dwordx4 v[228:229], off
	s_waitcnt vmcnt(8)
	s_waitcnt lgkmcnt(0)
	s_barrier
	s_setprio 1
	s_waitcnt lgkmcnt(0)
	v_mfma_f32_16x16x32_bf16 v[140:143], v[96:99], v[178:181], v[140:143]
	v_mfma_f32_16x16x32_bf16 v[136:139], v[120:123], v[178:181], v[136:139]
	v_mfma_f32_16x16x32_bf16 v[116:119], v[96:99], v[186:189], v[116:119]
	v_mfma_f32_16x16x32_bf16 v[112:115], v[120:123], v[186:189], v[112:115]
	v_mfma_f32_16x16x32_bf16 v[92:95], v[96:99], v[194:197], v[92:95]
	v_mfma_f32_16x16x32_bf16 v[88:91], v[120:123], v[194:197], v[88:91]
	v_mfma_f32_16x16x32_bf16 v[76:79], v[96:99], v[202:205], v[76:79]
	v_mfma_f32_16x16x32_bf16 v[72:75], v[120:123], v[202:205], v[72:75]
	v_mfma_f32_16x16x32_bf16 v[140:143], v[100:103], v[182:185], v[140:143]
	v_mfma_f32_16x16x32_bf16 v[136:139], v[124:127], v[182:185], v[136:139]
	v_mfma_f32_16x16x32_bf16 v[116:119], v[100:103], v[190:193], v[116:119]
	v_mfma_f32_16x16x32_bf16 v[112:115], v[124:127], v[190:193], v[112:115]
	v_mfma_f32_16x16x32_bf16 v[92:95], v[100:103], v[198:201], v[92:95]
	v_mfma_f32_16x16x32_bf16 v[88:91], v[124:127], v[198:201], v[88:91]
	v_mfma_f32_16x16x32_bf16 v[76:79], v[100:103], v[218:221], v[76:79]
	v_mfma_f32_16x16x32_bf16 v[72:75], v[124:127], v[218:221], v[72:75]
	s_setprio 0
	s_setprio 1
	v_mfma_f32_16x16x32_bf16 v[132:135], v[144:147], v[178:181], v[132:135]
	v_mfma_f32_16x16x32_bf16 v[128:131], v[152:155], v[178:181], v[128:131]
	v_mfma_f32_16x16x32_bf16 v[108:111], v[144:147], v[186:189], v[108:111]
	v_mfma_f32_16x16x32_bf16 v[104:107], v[152:155], v[186:189], v[104:107]
	v_mfma_f32_16x16x32_bf16 v[84:87], v[144:147], v[194:197], v[84:87]
	v_mfma_f32_16x16x32_bf16 v[80:83], v[152:155], v[194:197], v[80:83]
	v_mfma_f32_16x16x32_bf16 v[68:71], v[144:147], v[202:205], v[68:71]
	v_mfma_f32_16x16x32_bf16 v[64:67], v[152:155], v[202:205], v[64:67]
	v_mfma_f32_16x16x32_bf16 v[132:135], v[148:151], v[182:185], v[132:135]
	v_mfma_f32_16x16x32_bf16 v[128:131], v[156:159], v[182:185], v[128:131]
	v_mfma_f32_16x16x32_bf16 v[108:111], v[148:151], v[190:193], v[108:111]
	v_mfma_f32_16x16x32_bf16 v[104:107], v[156:159], v[190:193], v[104:107]
	s_setprio 2
	s_barrier
	v_mfma_f32_16x16x32_bf16 v[84:87], v[148:151], v[198:201], v[84:87]
	v_mfma_f32_16x16x32_bf16 v[80:83], v[156:159], v[198:201], v[80:83]
	v_mfma_f32_16x16x32_bf16 v[68:71], v[148:151], v[218:221], v[68:71]
	v_mfma_f32_16x16x32_bf16 v[64:67], v[156:159], v[218:221], v[64:67]
	s_setprio 2
	s_add_i32 s50, s79, s61
	v_lshl_add_u64 v[206:207], v[206:207], 0, s[36:37]
	s_mov_b32 m0, s50
	ds_read_b128 v[178:181], v211 offset:49152
	ds_read_b128 v[182:185], v211 offset:50176
	ds_read_b128 v[186:189], v211 offset:51200
	ds_read_b128 v[190:193], v211 offset:52224
	ds_read_b128 v[194:197], v211 offset:53248
	ds_read_b128 v[198:201], v211 offset:54272
	ds_read_b128 v[202:205], v211 offset:55296
	ds_read_b128 v[218:221], v211 offset:56320
	global_load_lds_dwordx4 v[206:207], off
	s_add_i32 m0, s50, 0x2000
	s_add_u32 s8, s8, 0x40080
	v_lshl_add_u64 v[206:207], v[222:223], 0, s[36:37]
	s_addc_u32 s9, s9, 0
	s_add_i32 s50, s80, s61
	global_load_lds_dwordx4 v[206:207], off
	s_mov_b32 m0, s50
	v_lshl_add_u64 v[206:207], s[8:9], 0, v[162:163]
	global_load_lds_dwordx4 v[206:207], off
	s_add_i32 m0, s50, 0x2000
	v_lshl_add_u64 v[206:207], s[8:9], 0, v[166:167]
	global_load_lds_dwordx4 v[206:207], off
	s_mov_b32 m0, s68
	v_lshl_add_u64 v[206:207], v[224:225], 0, s[36:37]
	global_load_lds_dwordx4 v[206:207], off
	s_mov_b32 m0, s69
	v_lshl_add_u64 v[206:207], v[226:227], 0, s[36:37]
	global_load_lds_dwordx4 v[206:207], off
	s_waitcnt vmcnt(8)
	s_waitcnt lgkmcnt(0)
	s_barrier
	s_setprio 1
	s_waitcnt lgkmcnt(0)
	v_mfma_f32_16x16x32_bf16 v[60:63], v[96:99], v[178:181], v[60:63]
	v_mfma_f32_16x16x32_bf16 v[56:59], v[120:123], v[178:181], v[56:59]
	v_mfma_f32_16x16x32_bf16 v[44:47], v[96:99], v[186:189], v[44:47]
	v_mfma_f32_16x16x32_bf16 v[40:43], v[120:123], v[186:189], v[40:43]
	v_mfma_f32_16x16x32_bf16 v[28:31], v[96:99], v[194:197], v[28:31]
	v_mfma_f32_16x16x32_bf16 v[24:27], v[120:123], v[194:197], v[24:27]
	v_mfma_f32_16x16x32_bf16 v[12:15], v[96:99], v[202:205], v[12:15]
	v_mfma_f32_16x16x32_bf16 v[8:11], v[120:123], v[202:205], v[8:11]
	v_mfma_f32_16x16x32_bf16 v[60:63], v[100:103], v[182:185], v[60:63]
	v_mfma_f32_16x16x32_bf16 v[56:59], v[124:127], v[182:185], v[56:59]
	v_mfma_f32_16x16x32_bf16 v[44:47], v[100:103], v[190:193], v[44:47]
	v_mfma_f32_16x16x32_bf16 v[40:43], v[124:127], v[190:193], v[40:43]
	v_mfma_f32_16x16x32_bf16 v[28:31], v[100:103], v[198:201], v[28:31]
	v_mfma_f32_16x16x32_bf16 v[24:27], v[124:127], v[198:201], v[24:27]
	v_mfma_f32_16x16x32_bf16 v[12:15], v[100:103], v[218:221], v[12:15]
	v_mfma_f32_16x16x32_bf16 v[8:11], v[124:127], v[218:221], v[8:11]
	s_setprio 0
	s_setprio 1
	v_mfma_f32_16x16x32_bf16 v[52:55], v[144:147], v[178:181], v[52:55]
	v_mfma_f32_16x16x32_bf16 v[48:51], v[152:155], v[178:181], v[48:51]
	v_mfma_f32_16x16x32_bf16 v[36:39], v[144:147], v[186:189], v[36:39]
	v_mfma_f32_16x16x32_bf16 v[32:35], v[152:155], v[186:189], v[32:35]
	v_mfma_f32_16x16x32_bf16 v[20:23], v[144:147], v[194:197], v[20:23]
	v_mfma_f32_16x16x32_bf16 v[16:19], v[152:155], v[194:197], v[16:19]
	v_mfma_f32_16x16x32_bf16 v[4:7], v[144:147], v[202:205], v[4:7]
	v_mfma_f32_16x16x32_bf16 v[0:3], v[152:155], v[202:205], v[0:3]
	v_mfma_f32_16x16x32_bf16 v[52:55], v[148:151], v[182:185], v[52:55]
	v_mfma_f32_16x16x32_bf16 v[48:51], v[156:159], v[182:185], v[48:51]
	v_mfma_f32_16x16x32_bf16 v[36:39], v[148:151], v[190:193], v[36:39]
	v_mfma_f32_16x16x32_bf16 v[32:35], v[156:159], v[190:193], v[32:35]
	s_setprio 2
	s_barrier
	v_mfma_f32_16x16x32_bf16 v[20:23], v[148:151], v[198:201], v[20:23]
	v_mfma_f32_16x16x32_bf16 v[16:19], v[156:159], v[198:201], v[16:19]
	v_mfma_f32_16x16x32_bf16 v[4:7], v[148:151], v[218:221], v[4:7]
	v_mfma_f32_16x16x32_bf16 v[0:3], v[156:159], v[218:221], v[0:3]
	s_setprio 0
	s_add_i32 s78, s78, 2
	s_add_u32 s6, s6, 0x100
	s_addc_u32 s7, s7, 0
	s_add_u32 s56, s56, 0x100
	s_addc_u32 s57, s57, 0
	s_cmp_gt_u32 s78, 13
	s_cbranch_scc0 .LBB0_323

.LBB0_697:
	s_and_b32 s29, s69, 0x1000
	s_add_i32 s70, s66, s29
	s_ashr_i32 s29, s28, 31
	ds_read_b128 v[0:3], v195 offset:3072
	ds_read_b128 v[4:7], v195 offset:2048
	ds_read_b128 v[8:11], v195 offset:1024
	ds_read_b128 v[12:15], v195
	ds_read_b128 v[16:19], v203 offset:3072
	ds_read_b128 v[20:23], v203 offset:2048
	ds_read_b128 v[24:27], v203 offset:1024
	ds_read_b128 v[28:31], v203
	s_lshl_b64 s[36:37], s[28:29], 20
	s_add_u32 s36, s50, s36
	s_addc_u32 s37, s51, s37
	s_and_b64 s[38:39], s[4:5], exec
	s_cselect_b32 s29, s37, s45
	s_cselect_b32 s71, s36, s44
	s_ashr_i32 s31, s30, 31
	s_lshl_b64 s[38:39], s[30:31], 20
	s_add_u32 s38, s54, s38
	s_addc_u32 s39, s55, s39
	s_and_b64 s[48:49], s[4:5], exec
	s_cselect_b32 s31, s39, s47
	s_cselect_b32 s72, s38, s46
	s_add_u32 s48, s44, 0x80080
	s_addc_u32 s49, s45, 0
	s_add_i32 s73, s56, 0xc000
	v_lshl_add_u64 v[64:65], s[48:49], 0, v[176:177]
	s_mov_b32 m0, s73
	s_add_i32 s74, s56, 0xe000
	ds_read_b128 v[32:35], v211
	ds_read_b128 v[36:39], v211 offset:1024
	ds_read_b128 v[40:43], v211 offset:2048
	ds_read_b128 v[44:47], v211 offset:3072
	ds_read_b128 v[48:51], v211 offset:4096
	ds_read_b128 v[52:55], v211 offset:5120
	ds_read_b128 v[56:59], v211 offset:6144
	ds_read_b128 v[60:63], v211 offset:7168
	global_load_lds_dwordx4 v[64:65], off
	s_mov_b32 m0, s74
	v_lshl_add_u64 v[64:65], s[48:49], 0, v[178:179]
	global_load_lds_dwordx4 v[64:65], off
	s_waitcnt vmcnt(8)
	s_waitcnt lgkmcnt(0)
	s_barrier
	s_setprio 1
	s_waitcnt lgkmcnt(0)
	v_mfma_f32_16x16x32_bf16 v[88:91], v[28:31], v[56:59], 0
	v_mfma_f32_16x16x32_bf16 v[64:67], v[28:31], v[32:35], 0
	v_mfma_f32_16x16x32_bf16 v[68:71], v[20:23], v[32:35], 0
	v_mfma_f32_16x16x32_bf16 v[72:75], v[28:31], v[40:43], 0
	v_mfma_f32_16x16x32_bf16 v[76:79], v[20:23], v[40:43], 0
	v_mfma_f32_16x16x32_bf16 v[80:83], v[28:31], v[48:51], 0
	v_mfma_f32_16x16x32_bf16 v[84:87], v[20:23], v[48:51], 0
	v_mfma_f32_16x16x32_bf16 v[96:99], v[24:27], v[60:63], v[88:91]
	v_mfma_f32_16x16x32_bf16 v[88:91], v[20:23], v[56:59], 0
	v_mfma_f32_16x16x32_bf16 v[64:67], v[24:27], v[36:39], v[64:67]
	v_mfma_f32_16x16x32_bf16 v[68:71], v[16:19], v[36:39], v[68:71]
	v_mfma_f32_16x16x32_bf16 v[72:75], v[24:27], v[44:47], v[72:75]
	v_mfma_f32_16x16x32_bf16 v[76:79], v[16:19], v[44:47], v[76:79]
	v_mfma_f32_16x16x32_bf16 v[80:83], v[24:27], v[52:55], v[80:83]
	v_mfma_f32_16x16x32_bf16 v[84:87], v[16:19], v[52:55], v[84:87]
	v_mfma_f32_16x16x32_bf16 v[100:103], v[16:19], v[60:63], v[88:91]
	s_setprio 0
	s_setprio 1
	v_mfma_f32_16x16x32_bf16 v[88:91], v[12:15], v[32:35], 0
	v_mfma_f32_16x16x32_bf16 v[32:35], v[4:7], v[32:35], 0
	v_mfma_f32_16x16x32_bf16 v[112:115], v[8:11], v[36:39], v[88:91]
	v_mfma_f32_16x16x32_bf16 v[32:35], v[0:3], v[36:39], v[32:35]
	v_mfma_f32_16x16x32_bf16 v[36:39], v[12:15], v[40:43], 0
	v_mfma_f32_16x16x32_bf16 v[40:43], v[4:7], v[40:43], 0
	v_mfma_f32_16x16x32_bf16 v[36:39], v[8:11], v[44:47], v[36:39]
	v_mfma_f32_16x16x32_bf16 v[40:43], v[0:3], v[44:47], v[40:43]
	v_mfma_f32_16x16x32_bf16 v[44:47], v[12:15], v[48:51], 0
	v_mfma_f32_16x16x32_bf16 v[48:51], v[4:7], v[48:51], 0
	v_mfma_f32_16x16x32_bf16 v[44:47], v[8:11], v[52:55], v[44:47]
	v_mfma_f32_16x16x32_bf16 v[48:51], v[0:3], v[52:55], v[48:51]
	s_setprio 2
	s_barrier
	v_mfma_f32_16x16x32_bf16 v[52:55], v[12:15], v[56:59], 0
	v_mfma_f32_16x16x32_bf16 v[56:59], v[4:7], v[56:59], 0
	v_mfma_f32_16x16x32_bf16 v[52:55], v[8:11], v[60:63], v[52:55]
	v_mfma_f32_16x16x32_bf16 v[56:59], v[0:3], v[60:63], v[56:59]
	s_setprio 2
	s_add_i32 s75, s68, s43
	v_lshl_add_u64 v[174:175], s[46:47], 0, v[176:177]
	s_add_i32 s76, s75, 0x2000
	v_lshl_add_u64 v[128:129], v[174:175], 0, s[24:25]
	s_mov_b32 m0, s75
	v_lshl_add_u64 v[200:201], s[46:47], 0, v[178:179]
	s_add_u32 s48, s46, 0x80100
	ds_read_b128 v[60:63], v211 offset:16384
	ds_read_b128 v[88:91], v211 offset:17408
	ds_read_b128 v[92:95], v211 offset:18432
	ds_read_b128 v[104:107], v211 offset:19456
	ds_read_b128 v[108:111], v211 offset:20480
	ds_read_b128 v[116:119], v211 offset:21504
	ds_read_b128 v[120:123], v211 offset:22528
	ds_read_b128 v[124:127], v211 offset:23552
	global_load_lds_dwordx4 v[128:129], off
	v_lshl_add_u64 v[128:129], v[200:201], 0, s[24:25]
	s_mov_b32 m0, s76
	s_addc_u32 s49, s47, 0
	s_add_i32 s77, s67, s43
	global_load_lds_dwordx4 v[128:129], off
	v_lshl_add_u64 v[128:129], s[48:49], 0, v[176:177]
	s_mov_b32 m0, s77
	s_add_i32 s78, s77, 0x2000
	global_load_lds_dwordx4 v[128:129], off
	v_lshl_add_u64 v[128:129], s[48:49], 0, v[178:179]
	s_mov_b32 m0, s78
	v_lshl_add_u64 v[208:209], s[44:45], 0, v[176:177]
	global_load_lds_dwordx4 v[128:129], off
	v_lshl_add_u64 v[128:129], v[208:209], 0, s[24:25]
	s_mov_b32 m0, s56
	v_lshl_add_u64 v[252:253], s[44:45], 0, v[178:179]
	global_load_lds_dwordx4 v[128:129], off
	s_mov_b32 m0, s57
	v_lshl_add_u64 v[128:129], v[252:253], 0, s[24:25]
	global_load_lds_dwordx4 v[128:129], off
	s_waitcnt vmcnt(8)
	s_waitcnt lgkmcnt(0)
	s_barrier
	s_setprio 1
	s_waitcnt lgkmcnt(0)
	v_mfma_f32_16x16x32_bf16 v[134:137], v[20:23], v[60:63], 0
	v_mfma_f32_16x16x32_bf16 v[142:145], v[20:23], v[92:95], 0
	v_mfma_f32_16x16x32_bf16 v[150:153], v[20:23], v[108:111], 0
	v_mfma_f32_16x16x32_bf16 v[20:23], v[20:23], v[120:123], 0
	v_mfma_f32_16x16x32_bf16 v[128:131], v[28:31], v[60:63], 0
	v_mfma_f32_16x16x32_bf16 v[134:137], v[16:19], v[88:91], v[134:137]
	v_mfma_f32_16x16x32_bf16 v[138:141], v[28:31], v[92:95], 0
	v_mfma_f32_16x16x32_bf16 v[142:145], v[16:19], v[104:107], v[142:145]
	v_mfma_f32_16x16x32_bf16 v[146:149], v[28:31], v[108:111], 0
	v_mfma_f32_16x16x32_bf16 v[150:153], v[16:19], v[116:119], v[150:153]
	v_mfma_f32_16x16x32_bf16 v[28:31], v[28:31], v[120:123], 0
	v_mfma_f32_16x16x32_bf16 v[16:19], v[16:19], v[124:127], v[20:23]
	v_mfma_f32_16x16x32_bf16 v[130:133], v[24:27], v[88:91], v[128:131]
	v_mfma_f32_16x16x32_bf16 v[138:141], v[24:27], v[104:107], v[138:141]
	v_mfma_f32_16x16x32_bf16 v[146:149], v[24:27], v[116:119], v[146:149]
	v_mfma_f32_16x16x32_bf16 v[154:157], v[24:27], v[124:127], v[28:31]
	s_setprio 0
	s_setprio 1
	v_mfma_f32_16x16x32_bf16 v[24:27], v[4:7], v[60:63], 0
	v_mfma_f32_16x16x32_bf16 v[158:161], v[0:3], v[88:91], v[24:27]
	v_mfma_f32_16x16x32_bf16 v[24:27], v[12:15], v[92:95], 0
	v_mfma_f32_16x16x32_bf16 v[162:165], v[8:11], v[104:107], v[24:27]
	v_mfma_f32_16x16x32_bf16 v[24:27], v[4:7], v[92:95], 0
	v_mfma_f32_16x16x32_bf16 v[166:169], v[0:3], v[104:107], v[24:27]
	v_mfma_f32_16x16x32_bf16 v[24:27], v[12:15], v[108:111], 0
	v_mfma_f32_16x16x32_bf16 v[20:23], v[12:15], v[60:63], 0
	v_mfma_f32_16x16x32_bf16 v[170:173], v[8:11], v[116:119], v[24:27]
	v_mfma_f32_16x16x32_bf16 v[24:27], v[4:7], v[108:111], 0
	v_mfma_f32_16x16x32_bf16 v[4:7], v[4:7], v[120:123], 0
	v_mfma_f32_16x16x32_bf16 v[20:23], v[8:11], v[88:91], v[20:23]
	s_setprio 2
	s_barrier
	v_mfma_f32_16x16x32_bf16 v[190:193], v[0:3], v[116:119], v[24:27]
	v_mfma_f32_16x16x32_bf16 v[12:15], v[12:15], v[120:123], 0
	v_mfma_f32_16x16x32_bf16 v[0:3], v[0:3], v[124:127], v[4:7]
	v_mfma_f32_16x16x32_bf16 v[196:199], v[8:11], v[124:127], v[12:15]
	s_setprio 0
	s_add_i32 s79, 0, 0x18000
	s_add_i32 s81, 0, 0x1c000
	v_add_u32_e32 v128, s79, v189
	v_add_u32_e32 v129, s81, v189
	ds_read_b128 v[4:7], v128
	ds_read_b128 v[8:11], v128 offset:1024
	ds_read_b128 v[204:207], v128 offset:2048
	ds_read_b128 v[212:215], v128 offset:3072
	ds_read_b128 v[216:219], v129
	ds_read_b128 v[220:223], v129 offset:1024
	ds_read_b128 v[224:227], v129 offset:2048
	ds_read_b128 v[228:231], v129 offset:3072
	s_add_u32 s48, s44, 0x80100
	s_addc_u32 s49, s45, 0
	s_mov_b32 m0, s58
	v_lshl_add_u64 v[88:89], s[48:49], 0, v[176:177]
	ds_read_b128 v[12:15], v211 offset:32768
	ds_read_b128 v[24:27], v211 offset:33792
	ds_read_b128 v[28:31], v211 offset:34816
	ds_read_b128 v[60:63], v211 offset:35840
	ds_read_b128 v[232:235], v211 offset:36864
	ds_read_b128 v[236:239], v211 offset:37888
	ds_read_b128 v[240:243], v211 offset:38912
	ds_read_b128 v[244:247], v211 offset:39936
	global_load_lds_dwordx4 v[88:89], off
	s_mov_b32 m0, s59
	v_lshl_add_u64 v[88:89], s[48:49], 0, v[178:179]
	global_load_lds_dwordx4 v[88:89], off
	s_waitcnt vmcnt(8)
	s_waitcnt lgkmcnt(0)
	s_barrier
	s_setprio 1
	s_waitcnt lgkmcnt(0)
	v_mfma_f32_16x16x32_bf16 v[64:67], v[4:7], v[12:15], v[64:67]
	v_mfma_f32_16x16x32_bf16 v[124:127], v[8:11], v[24:27], v[64:67]
	v_mfma_f32_16x16x32_bf16 v[64:67], v[204:207], v[12:15], v[68:71]
	v_mfma_f32_16x16x32_bf16 v[120:123], v[212:215], v[24:27], v[64:67]
	v_mfma_f32_16x16x32_bf16 v[64:67], v[4:7], v[28:31], v[72:75]
	v_mfma_f32_16x16x32_bf16 v[108:111], v[8:11], v[60:63], v[64:67]
	v_mfma_f32_16x16x32_bf16 v[64:67], v[204:207], v[28:31], v[76:79]
	v_mfma_f32_16x16x32_bf16 v[104:107], v[212:215], v[60:63], v[64:67]
	v_mfma_f32_16x16x32_bf16 v[64:67], v[4:7], v[232:235], v[80:83]
	v_mfma_f32_16x16x32_bf16 v[92:95], v[8:11], v[236:239], v[64:67]
	v_mfma_f32_16x16x32_bf16 v[64:67], v[204:207], v[232:235], v[84:87]
	v_mfma_f32_16x16x32_bf16 v[88:91], v[212:215], v[236:239], v[64:67]
	v_mfma_f32_16x16x32_bf16 v[64:67], v[4:7], v[240:243], v[96:99]
	v_mfma_f32_16x16x32_bf16 v[76:79], v[8:11], v[244:247], v[64:67]
	v_mfma_f32_16x16x32_bf16 v[64:67], v[204:207], v[240:243], v[100:103]
	v_mfma_f32_16x16x32_bf16 v[72:75], v[212:215], v[244:247], v[64:67]
	s_setprio 0
	s_setprio 1
	v_mfma_f32_16x16x32_bf16 v[64:67], v[216:219], v[12:15], v[112:115]
	v_mfma_f32_16x16x32_bf16 v[12:15], v[224:227], v[12:15], v[32:35]
	v_mfma_f32_16x16x32_bf16 v[112:115], v[228:231], v[24:27], v[12:15]
	v_mfma_f32_16x16x32_bf16 v[12:15], v[216:219], v[28:31], v[36:39]
	v_mfma_f32_16x16x32_bf16 v[100:103], v[220:223], v[60:63], v[12:15]
	v_mfma_f32_16x16x32_bf16 v[12:15], v[224:227], v[28:31], v[40:43]
	v_mfma_f32_16x16x32_bf16 v[96:99], v[228:231], v[60:63], v[12:15]
	v_mfma_f32_16x16x32_bf16 v[12:15], v[216:219], v[232:235], v[44:47]
	v_mfma_f32_16x16x32_bf16 v[84:87], v[220:223], v[236:239], v[12:15]
	v_mfma_f32_16x16x32_bf16 v[12:15], v[224:227], v[232:235], v[48:51]
	v_mfma_f32_16x16x32_bf16 v[80:83], v[228:231], v[236:239], v[12:15]
	v_mfma_f32_16x16x32_bf16 v[12:15], v[216:219], v[240:243], v[52:55]
	s_setprio 2
	s_barrier
	v_mfma_f32_16x16x32_bf16 v[68:71], v[220:223], v[244:247], v[12:15]
	v_mfma_f32_16x16x32_bf16 v[12:15], v[224:227], v[240:243], v[56:59]
	v_mfma_f32_16x16x32_bf16 v[116:119], v[220:223], v[24:27], v[64:67]
	v_mfma_f32_16x16x32_bf16 v[64:67], v[228:231], v[244:247], v[12:15]
	s_setprio 2
	s_add_i32 s79, s79, s43
	s_add_i32 s80, s79, 0x2000
	s_nop 1
	v_lshl_add_u64 v[12:13], v[174:175], 0, s[26:27]
	s_mov_b32 m0, s79
	s_add_u32 s48, s46, 0x80180
	ds_read_b128 v[32:35], v211 offset:49152
	ds_read_b128 v[36:39], v211 offset:50176
	ds_read_b128 v[232:235], v211 offset:51200
	ds_read_b128 v[236:239], v211 offset:52224
	ds_read_b128 v[240:243], v211 offset:53248
	ds_read_b128 v[244:247], v211 offset:54272
	ds_read_b128 v[248:251], v211 offset:55296
	ds_read_b128 v[184:187], v211 offset:56320
	global_load_lds_dwordx4 v[12:13], off
	v_lshl_add_u64 v[12:13], v[200:201], 0, s[26:27]
	s_mov_b32 m0, s80
	s_addc_u32 s49, s47, 0
	s_add_i32 s81, s81, s43
	global_load_lds_dwordx4 v[12:13], off
	v_lshl_add_u64 v[12:13], s[48:49], 0, v[176:177]
	s_mov_b32 m0, s81
	s_add_i32 s82, s81, 0x2000
	global_load_lds_dwordx4 v[12:13], off
	s_mov_b32 m0, s82
	v_lshl_add_u64 v[12:13], s[48:49], 0, v[178:179]
	global_load_lds_dwordx4 v[12:13], off
	s_mov_b32 m0, s61
	v_lshl_add_u64 v[12:13], v[208:209], 0, s[26:27]
	global_load_lds_dwordx4 v[12:13], off
	s_mov_b32 m0, s62
	v_lshl_add_u64 v[12:13], v[252:253], 0, s[26:27]
	global_load_lds_dwordx4 v[12:13], off
	s_waitcnt vmcnt(8)
	s_waitcnt lgkmcnt(0)
	s_barrier
	s_setprio 1
	s_waitcnt lgkmcnt(0)
	v_mfma_f32_16x16x32_bf16 v[12:15], v[4:7], v[32:35], v[130:133]
	v_mfma_f32_16x16x32_bf16 v[60:63], v[8:11], v[36:39], v[12:15]
	v_mfma_f32_16x16x32_bf16 v[12:15], v[204:207], v[32:35], v[134:137]
	v_mfma_f32_16x16x32_bf16 v[56:59], v[212:215], v[36:39], v[12:15]
	v_mfma_f32_16x16x32_bf16 v[12:15], v[4:7], v[232:235], v[138:141]
	v_mfma_f32_16x16x32_bf16 v[44:47], v[8:11], v[236:239], v[12:15]
	v_mfma_f32_16x16x32_bf16 v[12:15], v[204:207], v[232:235], v[142:145]
	v_mfma_f32_16x16x32_bf16 v[40:43], v[212:215], v[236:239], v[12:15]
	v_mfma_f32_16x16x32_bf16 v[12:15], v[4:7], v[240:243], v[146:149]
	v_mfma_f32_16x16x32_bf16 v[28:31], v[8:11], v[244:247], v[12:15]
	v_mfma_f32_16x16x32_bf16 v[12:15], v[204:207], v[240:243], v[150:153]
	v_mfma_f32_16x16x32_bf16 v[4:7], v[4:7], v[248:251], v[154:157]
	v_mfma_f32_16x16x32_bf16 v[24:27], v[212:215], v[244:247], v[12:15]
	v_mfma_f32_16x16x32_bf16 v[12:15], v[8:11], v[184:187], v[4:7]
	v_mfma_f32_16x16x32_bf16 v[4:7], v[204:207], v[248:251], v[16:19]
	v_mfma_f32_16x16x32_bf16 v[8:11], v[212:215], v[184:187], v[4:7]
	s_setprio 0
	s_setprio 1
	v_mfma_f32_16x16x32_bf16 v[4:7], v[216:219], v[32:35], v[20:23]
	v_mfma_f32_16x16x32_bf16 v[52:55], v[220:223], v[36:39], v[4:7]
	v_mfma_f32_16x16x32_bf16 v[4:7], v[224:227], v[32:35], v[158:161]
	v_mfma_f32_16x16x32_bf16 v[48:51], v[228:231], v[36:39], v[4:7]
	v_mfma_f32_16x16x32_bf16 v[4:7], v[216:219], v[232:235], v[162:165]
	v_mfma_f32_16x16x32_bf16 v[36:39], v[220:223], v[236:239], v[4:7]
	v_mfma_f32_16x16x32_bf16 v[4:7], v[224:227], v[232:235], v[166:169]
	v_mfma_f32_16x16x32_bf16 v[32:35], v[228:231], v[236:239], v[4:7]
	v_mfma_f32_16x16x32_bf16 v[4:7], v[216:219], v[240:243], v[170:173]
	v_mfma_f32_16x16x32_bf16 v[20:23], v[220:223], v[244:247], v[4:7]
	v_mfma_f32_16x16x32_bf16 v[4:7], v[224:227], v[240:243], v[190:193]
	v_mfma_f32_16x16x32_bf16 v[16:19], v[228:231], v[244:247], v[4:7]
	s_setprio 2
	s_barrier
	v_mfma_f32_16x16x32_bf16 v[4:7], v[216:219], v[248:251], v[196:199]
	v_mfma_f32_16x16x32_bf16 v[0:3], v[224:227], v[248:251], v[0:3]
	v_mfma_f32_16x16x32_bf16 v[4:7], v[220:223], v[184:187], v[4:7]
	v_mfma_f32_16x16x32_bf16 v[0:3], v[228:231], v[184:187], v[0:3]
	s_setprio 0
	s_add_u32 s44, s44, 0x80180
	s_addc_u32 s45, s45, 0
	s_add_u32 s83, s46, 0x200
	s_addc_u32 s84, s47, 0
	s_mov_b32 s46, 0
	s_add_i32 s85, s46, 2
	s_and_b32 s47, s85, 6
	s_cmp_lg_u32 s47, 0
	s_cbranch_scc1 .LBB0_700
	s_branch .LBB0_699

.LBB0_700:
	ds_read_b128 v[130:133], v203
	ds_read_b128 v[134:137], v203 offset:1024
	ds_read_b128 v[138:141], v203 offset:2048
	ds_read_b128 v[142:145], v203 offset:3072
	ds_read_b128 v[146:149], v195
	ds_read_b128 v[150:153], v195 offset:1024
	ds_read_b128 v[154:157], v195 offset:2048
	ds_read_b128 v[158:161], v195 offset:3072
	s_add_u32 s47, s44, 0xfff80080
	s_addc_u32 s48, s45, -1
	s_cmp_eq_u32 s46, 28
	s_cselect_b32 s49, s29, s48
	s_cselect_b32 s48, s71, s47
	s_cselect_b32 s47, s31, s84
	s_cselect_b32 s46, s72, s83
	s_mov_b32 m0, s73
	v_lshl_add_u64 v[174:175], s[44:45], 0, v[180:181]
	ds_read_b128 v[162:165], v211
	ds_read_b128 v[166:169], v211 offset:1024
	ds_read_b128 v[170:173], v211 offset:2048
	ds_read_b128 v[184:187], v211 offset:3072
	ds_read_b128 v[190:193], v211 offset:4096
	ds_read_b128 v[196:199], v211 offset:5120
	ds_read_b128 v[204:207], v211 offset:6144
	ds_read_b128 v[212:215], v211 offset:7168
	global_load_lds_dwordx4 v[174:175], off
	s_mov_b32 m0, s74
	v_lshl_add_u64 v[174:175], s[44:45], 0, v[182:183]
	global_load_lds_dwordx4 v[174:175], off
	s_waitcnt vmcnt(8)
	s_waitcnt lgkmcnt(0)
	s_barrier
	s_setprio 1
	s_waitcnt lgkmcnt(0)
	v_mfma_f32_16x16x32_bf16 v[124:127], v[130:133], v[162:165], v[124:127]
	v_mfma_f32_16x16x32_bf16 v[120:123], v[138:141], v[162:165], v[120:123]
	v_mfma_f32_16x16x32_bf16 v[108:111], v[130:133], v[170:173], v[108:111]
	v_mfma_f32_16x16x32_bf16 v[104:107], v[138:141], v[170:173], v[104:107]
	v_mfma_f32_16x16x32_bf16 v[92:95], v[130:133], v[190:193], v[92:95]
	v_mfma_f32_16x16x32_bf16 v[88:91], v[138:141], v[190:193], v[88:91]
	v_mfma_f32_16x16x32_bf16 v[76:79], v[130:133], v[204:207], v[76:79]
	v_mfma_f32_16x16x32_bf16 v[72:75], v[138:141], v[204:207], v[72:75]
	v_mfma_f32_16x16x32_bf16 v[124:127], v[134:137], v[166:169], v[124:127]
	v_mfma_f32_16x16x32_bf16 v[120:123], v[142:145], v[166:169], v[120:123]
	v_mfma_f32_16x16x32_bf16 v[108:111], v[134:137], v[184:187], v[108:111]
	v_mfma_f32_16x16x32_bf16 v[104:107], v[142:145], v[184:187], v[104:107]
	v_mfma_f32_16x16x32_bf16 v[92:95], v[134:137], v[196:199], v[92:95]
	v_mfma_f32_16x16x32_bf16 v[88:91], v[142:145], v[196:199], v[88:91]
	v_mfma_f32_16x16x32_bf16 v[76:79], v[134:137], v[212:215], v[76:79]
	v_mfma_f32_16x16x32_bf16 v[72:75], v[142:145], v[212:215], v[72:75]
	s_setprio 0
	s_setprio 1
	v_mfma_f32_16x16x32_bf16 v[116:119], v[146:149], v[162:165], v[116:119]
	v_mfma_f32_16x16x32_bf16 v[112:115], v[154:157], v[162:165], v[112:115]
	v_mfma_f32_16x16x32_bf16 v[100:103], v[146:149], v[170:173], v[100:103]
	v_mfma_f32_16x16x32_bf16 v[96:99], v[154:157], v[170:173], v[96:99]
	v_mfma_f32_16x16x32_bf16 v[84:87], v[146:149], v[190:193], v[84:87]
	v_mfma_f32_16x16x32_bf16 v[80:83], v[154:157], v[190:193], v[80:83]
	v_mfma_f32_16x16x32_bf16 v[68:71], v[146:149], v[204:207], v[68:71]
	v_mfma_f32_16x16x32_bf16 v[64:67], v[154:157], v[204:207], v[64:67]
	v_mfma_f32_16x16x32_bf16 v[116:119], v[150:153], v[166:169], v[116:119]
	v_mfma_f32_16x16x32_bf16 v[112:115], v[158:161], v[166:169], v[112:115]
	v_mfma_f32_16x16x32_bf16 v[100:103], v[150:153], v[184:187], v[100:103]
	v_mfma_f32_16x16x32_bf16 v[96:99], v[158:161], v[184:187], v[96:99]
	s_setprio 2
	s_barrier
	v_mfma_f32_16x16x32_bf16 v[84:87], v[150:153], v[196:199], v[84:87]
	v_mfma_f32_16x16x32_bf16 v[80:83], v[158:161], v[196:199], v[80:83]
	v_mfma_f32_16x16x32_bf16 v[68:71], v[150:153], v[212:215], v[68:71]
	v_mfma_f32_16x16x32_bf16 v[64:67], v[158:161], v[212:215], v[64:67]
	s_setprio 2
	s_mov_b32 m0, s75
	v_lshl_add_u64 v[174:175], s[46:47], 0, v[176:177]
	s_add_u32 s86, s46, 0x80000
	ds_read_b128 v[162:165], v211 offset:16384
	ds_read_b128 v[166:169], v211 offset:17408
	ds_read_b128 v[170:173], v211 offset:18432
	ds_read_b128 v[184:187], v211 offset:19456
	ds_read_b128 v[190:193], v211 offset:20480
	ds_read_b128 v[196:199], v211 offset:21504
	ds_read_b128 v[204:207], v211 offset:22528
	ds_read_b128 v[212:215], v211 offset:23552
	global_load_lds_dwordx4 v[174:175], off
	v_lshl_add_u64 v[200:201], s[46:47], 0, v[178:179]
	s_mov_b32 m0, s76
	s_addc_u32 s87, s47, 0
	global_load_lds_dwordx4 v[200:201], off
	v_lshl_add_u64 v[208:209], s[86:87], 0, v[176:177]
	s_mov_b32 m0, s77
	v_lshl_add_u64 v[216:217], s[48:49], 0, v[178:179]
	global_load_lds_dwordx4 v[208:209], off
	s_mov_b32 m0, s78
	v_lshl_add_u64 v[208:209], s[86:87], 0, v[178:179]
	global_load_lds_dwordx4 v[208:209], off
	s_mov_b32 m0, s56
	v_lshl_add_u64 v[208:209], s[48:49], 0, v[176:177]
	global_load_lds_dwordx4 v[208:209], off
	s_mov_b32 m0, s57
	s_nop 0
	global_load_lds_dwordx4 v[216:217], off
	s_waitcnt vmcnt(8)
	s_waitcnt lgkmcnt(0)
	s_barrier
	s_setprio 1
	s_waitcnt lgkmcnt(0)
	v_mfma_f32_16x16x32_bf16 v[60:63], v[130:133], v[162:165], v[60:63]
	v_mfma_f32_16x16x32_bf16 v[56:59], v[138:141], v[162:165], v[56:59]
	v_mfma_f32_16x16x32_bf16 v[44:47], v[130:133], v[170:173], v[44:47]
	v_mfma_f32_16x16x32_bf16 v[40:43], v[138:141], v[170:173], v[40:43]
	v_mfma_f32_16x16x32_bf16 v[28:31], v[130:133], v[190:193], v[28:31]
	v_mfma_f32_16x16x32_bf16 v[24:27], v[138:141], v[190:193], v[24:27]
	v_mfma_f32_16x16x32_bf16 v[12:15], v[130:133], v[204:207], v[12:15]
	v_mfma_f32_16x16x32_bf16 v[8:11], v[138:141], v[204:207], v[8:11]
	v_mfma_f32_16x16x32_bf16 v[60:63], v[134:137], v[166:169], v[60:63]
	v_mfma_f32_16x16x32_bf16 v[56:59], v[142:145], v[166:169], v[56:59]
	v_mfma_f32_16x16x32_bf16 v[44:47], v[134:137], v[184:187], v[44:47]
	v_mfma_f32_16x16x32_bf16 v[40:43], v[142:145], v[184:187], v[40:43]
	v_mfma_f32_16x16x32_bf16 v[28:31], v[134:137], v[196:199], v[28:31]
	v_mfma_f32_16x16x32_bf16 v[24:27], v[142:145], v[196:199], v[24:27]
	v_mfma_f32_16x16x32_bf16 v[12:15], v[134:137], v[212:215], v[12:15]
	v_mfma_f32_16x16x32_bf16 v[8:11], v[142:145], v[212:215], v[8:11]
	s_setprio 0
	s_setprio 1
	v_mfma_f32_16x16x32_bf16 v[52:55], v[146:149], v[162:165], v[52:55]
	v_mfma_f32_16x16x32_bf16 v[48:51], v[154:157], v[162:165], v[48:51]
	v_mfma_f32_16x16x32_bf16 v[36:39], v[146:149], v[170:173], v[36:39]
	v_mfma_f32_16x16x32_bf16 v[32:35], v[154:157], v[170:173], v[32:35]
	v_mfma_f32_16x16x32_bf16 v[20:23], v[146:149], v[190:193], v[20:23]
	v_mfma_f32_16x16x32_bf16 v[16:19], v[154:157], v[190:193], v[16:19]
	v_mfma_f32_16x16x32_bf16 v[4:7], v[146:149], v[204:207], v[4:7]
	v_mfma_f32_16x16x32_bf16 v[0:3], v[154:157], v[204:207], v[0:3]
	v_mfma_f32_16x16x32_bf16 v[52:55], v[150:153], v[166:169], v[52:55]
	v_mfma_f32_16x16x32_bf16 v[48:51], v[158:161], v[166:169], v[48:51]
	v_mfma_f32_16x16x32_bf16 v[36:39], v[150:153], v[184:187], v[36:39]
	v_mfma_f32_16x16x32_bf16 v[32:35], v[158:161], v[184:187], v[32:35]
	s_setprio 2
	s_barrier
	v_mfma_f32_16x16x32_bf16 v[20:23], v[150:153], v[196:199], v[20:23]
	v_mfma_f32_16x16x32_bf16 v[16:19], v[158:161], v[196:199], v[16:19]
	v_mfma_f32_16x16x32_bf16 v[4:7], v[150:153], v[212:215], v[4:7]
	v_mfma_f32_16x16x32_bf16 v[0:3], v[158:161], v[212:215], v[0:3]
	s_setprio 0
	ds_read_b128 v[130:133], v128
	ds_read_b128 v[134:137], v128 offset:1024
	ds_read_b128 v[138:141], v128 offset:2048
	ds_read_b128 v[142:145], v128 offset:3072
	ds_read_b128 v[146:149], v129
	ds_read_b128 v[150:153], v129 offset:1024
	ds_read_b128 v[154:157], v129 offset:2048
	ds_read_b128 v[158:161], v129 offset:3072
	s_add_u32 s48, s48, 0x80000
	s_addc_u32 s49, s49, 0
	s_mov_b32 m0, s58
	v_lshl_add_u64 v[218:219], s[48:49], 0, v[176:177]
	ds_read_b128 v[162:165], v211 offset:32768
	ds_read_b128 v[166:169], v211 offset:33792
	ds_read_b128 v[170:173], v211 offset:34816
	ds_read_b128 v[184:187], v211 offset:35840
	ds_read_b128 v[190:193], v211 offset:36864
	ds_read_b128 v[196:199], v211 offset:37888
	ds_read_b128 v[204:207], v211 offset:38912
	ds_read_b128 v[212:215], v211 offset:39936
	global_load_lds_dwordx4 v[218:219], off
	s_mov_b32 m0, s59
	v_lshl_add_u64 v[218:219], s[48:49], 0, v[178:179]
	global_load_lds_dwordx4 v[218:219], off
	s_waitcnt vmcnt(8)
	s_waitcnt lgkmcnt(0)
	s_barrier
	s_setprio 1
	s_waitcnt lgkmcnt(0)
	v_mfma_f32_16x16x32_bf16 v[124:127], v[130:133], v[162:165], v[124:127]
	v_mfma_f32_16x16x32_bf16 v[120:123], v[138:141], v[162:165], v[120:123]
	v_mfma_f32_16x16x32_bf16 v[108:111], v[130:133], v[170:173], v[108:111]
	v_mfma_f32_16x16x32_bf16 v[104:107], v[138:141], v[170:173], v[104:107]
	v_mfma_f32_16x16x32_bf16 v[92:95], v[130:133], v[190:193], v[92:95]
	v_mfma_f32_16x16x32_bf16 v[88:91], v[138:141], v[190:193], v[88:91]
	v_mfma_f32_16x16x32_bf16 v[76:79], v[130:133], v[204:207], v[76:79]
	v_mfma_f32_16x16x32_bf16 v[72:75], v[138:141], v[204:207], v[72:75]
	v_mfma_f32_16x16x32_bf16 v[124:127], v[134:137], v[166:169], v[124:127]
	v_mfma_f32_16x16x32_bf16 v[120:123], v[142:145], v[166:169], v[120:123]
	v_mfma_f32_16x16x32_bf16 v[108:111], v[134:137], v[184:187], v[108:111]
	v_mfma_f32_16x16x32_bf16 v[104:107], v[142:145], v[184:187], v[104:107]
	v_mfma_f32_16x16x32_bf16 v[92:95], v[134:137], v[196:199], v[92:95]
	v_mfma_f32_16x16x32_bf16 v[88:91], v[142:145], v[196:199], v[88:91]
	v_mfma_f32_16x16x32_bf16 v[76:79], v[134:137], v[212:215], v[76:79]
	v_mfma_f32_16x16x32_bf16 v[72:75], v[142:145], v[212:215], v[72:75]
	s_setprio 0
	s_setprio 1
	v_mfma_f32_16x16x32_bf16 v[116:119], v[146:149], v[162:165], v[116:119]
	v_mfma_f32_16x16x32_bf16 v[112:115], v[154:157], v[162:165], v[112:115]
	v_mfma_f32_16x16x32_bf16 v[100:103], v[146:149], v[170:173], v[100:103]
	v_mfma_f32_16x16x32_bf16 v[96:99], v[154:157], v[170:173], v[96:99]
	v_mfma_f32_16x16x32_bf16 v[84:87], v[146:149], v[190:193], v[84:87]
	v_mfma_f32_16x16x32_bf16 v[80:83], v[154:157], v[190:193], v[80:83]
	v_mfma_f32_16x16x32_bf16 v[68:71], v[146:149], v[204:207], v[68:71]
	v_mfma_f32_16x16x32_bf16 v[64:67], v[154:157], v[204:207], v[64:67]
	v_mfma_f32_16x16x32_bf16 v[116:119], v[150:153], v[166:169], v[116:119]
	v_mfma_f32_16x16x32_bf16 v[112:115], v[158:161], v[166:169], v[112:115]
	v_mfma_f32_16x16x32_bf16 v[100:103], v[150:153], v[184:187], v[100:103]
	v_mfma_f32_16x16x32_bf16 v[96:99], v[158:161], v[184:187], v[96:99]
	s_setprio 2
	s_barrier
	v_mfma_f32_16x16x32_bf16 v[84:87], v[150:153], v[196:199], v[84:87]
	v_mfma_f32_16x16x32_bf16 v[80:83], v[158:161], v[196:199], v[80:83]
	v_mfma_f32_16x16x32_bf16 v[68:71], v[150:153], v[212:215], v[68:71]
	v_mfma_f32_16x16x32_bf16 v[64:67], v[158:161], v[212:215], v[64:67]
	s_setprio 2
	s_mov_b32 m0, s79
	v_lshl_add_u64 v[174:175], v[174:175], 0, s[20:21]
	s_add_u32 s46, s46, 0x80080
	ds_read_b128 v[162:165], v211 offset:49152
	ds_read_b128 v[166:169], v211 offset:50176
	ds_read_b128 v[170:173], v211 offset:51200
	ds_read_b128 v[184:187], v211 offset:52224
	ds_read_b128 v[190:193], v211 offset:53248
	ds_read_b128 v[196:199], v211 offset:54272
	ds_read_b128 v[204:207], v211 offset:55296
	ds_read_b128 v[212:215], v211 offset:56320
	global_load_lds_dwordx4 v[174:175], off
	v_lshl_add_u64 v[174:175], v[200:201], 0, s[20:21]
	s_mov_b32 m0, s80
	s_addc_u32 s47, s47, 0
	global_load_lds_dwordx4 v[174:175], off
	s_mov_b32 m0, s81
	v_lshl_add_u64 v[174:175], s[46:47], 0, v[176:177]
	global_load_lds_dwordx4 v[174:175], off
	s_mov_b32 m0, s82
	v_lshl_add_u64 v[174:175], s[46:47], 0, v[178:179]
	global_load_lds_dwordx4 v[174:175], off
	s_mov_b32 m0, s61
	v_lshl_add_u64 v[174:175], v[208:209], 0, s[20:21]
	global_load_lds_dwordx4 v[174:175], off
	s_mov_b32 m0, s62
	v_lshl_add_u64 v[174:175], v[216:217], 0, s[20:21]
	global_load_lds_dwordx4 v[174:175], off
	s_waitcnt vmcnt(8)
	s_waitcnt lgkmcnt(0)
	s_barrier
	s_setprio 1
	s_waitcnt lgkmcnt(0)
	v_mfma_f32_16x16x32_bf16 v[60:63], v[130:133], v[162:165], v[60:63]
	v_mfma_f32_16x16x32_bf16 v[56:59], v[138:141], v[162:165], v[56:59]
	v_mfma_f32_16x16x32_bf16 v[44:47], v[130:133], v[170:173], v[44:47]
	v_mfma_f32_16x16x32_bf16 v[40:43], v[138:141], v[170:173], v[40:43]
	v_mfma_f32_16x16x32_bf16 v[28:31], v[130:133], v[190:193], v[28:31]
	v_mfma_f32_16x16x32_bf16 v[24:27], v[138:141], v[190:193], v[24:27]
	v_mfma_f32_16x16x32_bf16 v[12:15], v[130:133], v[204:207], v[12:15]
	v_mfma_f32_16x16x32_bf16 v[8:11], v[138:141], v[204:207], v[8:11]
	v_mfma_f32_16x16x32_bf16 v[60:63], v[134:137], v[166:169], v[60:63]
	v_mfma_f32_16x16x32_bf16 v[56:59], v[142:145], v[166:169], v[56:59]
	v_mfma_f32_16x16x32_bf16 v[44:47], v[134:137], v[184:187], v[44:47]
	v_mfma_f32_16x16x32_bf16 v[40:43], v[142:145], v[184:187], v[40:43]
	v_mfma_f32_16x16x32_bf16 v[28:31], v[134:137], v[196:199], v[28:31]
	v_mfma_f32_16x16x32_bf16 v[24:27], v[142:145], v[196:199], v[24:27]
	v_mfma_f32_16x16x32_bf16 v[12:15], v[134:137], v[212:215], v[12:15]
	v_mfma_f32_16x16x32_bf16 v[8:11], v[142:145], v[212:215], v[8:11]
	s_setprio 0
	s_setprio 1
	v_mfma_f32_16x16x32_bf16 v[52:55], v[146:149], v[162:165], v[52:55]
	v_mfma_f32_16x16x32_bf16 v[48:51], v[154:157], v[162:165], v[48:51]
	v_mfma_f32_16x16x32_bf16 v[36:39], v[146:149], v[170:173], v[36:39]
	v_mfma_f32_16x16x32_bf16 v[32:35], v[154:157], v[170:173], v[32:35]
	v_mfma_f32_16x16x32_bf16 v[20:23], v[146:149], v[190:193], v[20:23]
	v_mfma_f32_16x16x32_bf16 v[16:19], v[154:157], v[190:193], v[16:19]
	v_mfma_f32_16x16x32_bf16 v[4:7], v[146:149], v[204:207], v[4:7]
	v_mfma_f32_16x16x32_bf16 v[0:3], v[154:157], v[204:207], v[0:3]
	v_mfma_f32_16x16x32_bf16 v[52:55], v[150:153], v[166:169], v[52:55]
	v_mfma_f32_16x16x32_bf16 v[48:51], v[158:161], v[166:169], v[48:51]
	v_mfma_f32_16x16x32_bf16 v[36:39], v[150:153], v[184:187], v[36:39]
	v_mfma_f32_16x16x32_bf16 v[32:35], v[158:161], v[184:187], v[32:35]
	s_setprio 2
	s_barrier
	v_mfma_f32_16x16x32_bf16 v[20:23], v[150:153], v[196:199], v[20:23]
	v_mfma_f32_16x16x32_bf16 v[16:19], v[158:161], v[196:199], v[16:19]
	v_mfma_f32_16x16x32_bf16 v[4:7], v[150:153], v[212:215], v[4:7]
	v_mfma_f32_16x16x32_bf16 v[0:3], v[158:161], v[212:215], v[0:3]
	s_setprio 0
	s_add_i32 s70, s70, 1
	s_add_u32 s44, s44, 0x100
	s_addc_u32 s45, s45, 0
	s_add_u32 s83, s83, 0x100
	s_addc_u32 s84, s84, 0
	s_cmp_gt_u32 s85, 29
	s_cbranch_scc0 .LBB0_698
	s_lshl_b32 s29, s41, 12
	s_and_b32 s29, s29, 0x1000
	s_add_i32 s29, s29, 0
	v_mbcnt_lo_u32_b32 v128, -1, 0
	v_mbcnt_hi_u32_b32 v128, -1, v128
	s_add_i32 s29, s29, s63
	v_lshlrev_b32_e32 v128, 4, v128
	s_add_i32 s29, s29, 0x20400
	v_and_b32_e32 v128, 0xf0, v128
	v_add_u32_e32 v128, s29, v128
	ds_read2_b32 v[214:215], v128 offset0:3 offset1:67
	ds_read2_b32 v[206:207], v128 offset0:131 offset1:195
	v_add_u32_e32 v128, 12, v128
	ds_read2st64_b32 v[196:197], v128 offset0:8 offset1:9
	ds_read2st64_b32 v[190:191], v128 offset0:10 offset1:11
	s_and_b64 vcc, exec, s[22:23]
	s_waitcnt lgkmcnt(0)
	v_mov_b32_e32 v210, v215
	v_mov_b32_e32 v202, v207
	v_mov_b32_e32 v194, v197
	v_mov_b32_e32 v188, v191
	s_cbranch_vccz .LBB0_703
	s_barrier

.LBB0_783:
	s_ashr_i32 s23, s22, 31
	s_lshl_b64 s[26:27], s[22:23], 19
	s_add_u32 s26, s43, s26
	s_addc_u32 s27, s44, s27
	s_and_b64 s[28:29], s[4:5], exec
	s_cselect_b32 s23, s27, s37
	s_cselect_b32 s31, s26, s36
	s_ashr_i32 s25, s24, 31
	s_lshl_b64 s[28:29], s[24:25], 19
	s_add_u32 s28, s45, s28
	s_addc_u32 s29, s46, s29
	s_and_b64 s[40:41], s[4:5], exec
	s_cselect_b32 s25, s29, s39
	s_cselect_b32 s62, s28, s38
	s_add_u32 s36, s36, 0x40080
	s_addc_u32 s37, s37, 0
	s_add_u32 s63, s38, 0x100
	s_addc_u32 s64, s39, 0
	s_mov_b32 s65, -2
	ds_read_b128 v[144:147], v163
	ds_read_b128 v[148:151], v163 offset:1024
	ds_read_b128 v[152:155], v163 offset:2048
	ds_read_b128 v[156:159], v163 offset:3072
	ds_read_b128 v[168:171], v164
	ds_read_b128 v[172:175], v164 offset:1024
	ds_read_b128 v[176:179], v164 offset:2048
	ds_read_b128 v[180:183], v164 offset:3072
	s_add_u32 s38, s36, 0xfffc0080
	s_addc_u32 s39, s37, -1
	s_cmp_eq_u32 s65, 12
	s_cselect_b32 s41, s23, s39
	s_cselect_b32 s40, s31, s38
	s_cselect_b32 s39, s25, s64
	s_cselect_b32 s38, s62, s63
	v_lshl_add_u64 v[160:161], s[36:37], 0, v[136:137]
	s_add_i32 m0, s50, 0xc000
	ds_read_b128 v[184:187], v165
	ds_read_b128 v[188:191], v165 offset:1024
	ds_read_b128 v[192:195], v165 offset:2048
	ds_read_b128 v[196:199], v165 offset:3072
	ds_read_b128 v[200:203], v165 offset:4096
	ds_read_b128 v[204:207], v165 offset:5120
	ds_read_b128 v[208:211], v165 offset:6144
	ds_read_b128 v[212:215], v165 offset:7168
	global_load_lds_dwordx4 v[160:161], off
	s_add_i32 m0, s50, 0xe000
	v_lshl_add_u64 v[160:161], s[36:37], 0, v[138:139]
	global_load_lds_dwordx4 v[160:161], off
	s_waitcnt vmcnt(8)
	s_waitcnt lgkmcnt(0)
	s_barrier
	s_setprio 1
	s_waitcnt lgkmcnt(0)
	v_mfma_f32_16x16x32_bf16 v[124:127], v[144:147], v[184:187], 0
	v_mfma_f32_16x16x32_bf16 v[120:123], v[152:155], v[184:187], 0
	v_mfma_f32_16x16x32_bf16 v[108:111], v[144:147], v[192:195], 0
	v_mfma_f32_16x16x32_bf16 v[104:107], v[152:155], v[192:195], 0
	v_mfma_f32_16x16x32_bf16 v[92:95], v[144:147], v[200:203], 0
	v_mfma_f32_16x16x32_bf16 v[88:91], v[152:155], v[200:203], 0
	v_mfma_f32_16x16x32_bf16 v[76:79], v[144:147], v[208:211], 0
	v_mfma_f32_16x16x32_bf16 v[72:75], v[152:155], v[208:211], 0
	v_mfma_f32_16x16x32_bf16 v[124:127], v[148:151], v[188:191], v[124:127]
	v_mfma_f32_16x16x32_bf16 v[120:123], v[156:159], v[188:191], v[120:123]
	v_mfma_f32_16x16x32_bf16 v[108:111], v[148:151], v[196:199], v[108:111]
	v_mfma_f32_16x16x32_bf16 v[104:107], v[156:159], v[196:199], v[104:107]
	v_mfma_f32_16x16x32_bf16 v[92:95], v[148:151], v[204:207], v[92:95]
	v_mfma_f32_16x16x32_bf16 v[88:91], v[156:159], v[204:207], v[88:91]
	v_mfma_f32_16x16x32_bf16 v[76:79], v[148:151], v[212:215], v[76:79]
	v_mfma_f32_16x16x32_bf16 v[72:75], v[156:159], v[212:215], v[72:75]
	s_setprio 0
	s_setprio 1
	v_mfma_f32_16x16x32_bf16 v[116:119], v[168:171], v[184:187], 0
	v_mfma_f32_16x16x32_bf16 v[112:115], v[176:179], v[184:187], 0
	v_mfma_f32_16x16x32_bf16 v[100:103], v[168:171], v[192:195], 0
	v_mfma_f32_16x16x32_bf16 v[96:99], v[176:179], v[192:195], 0
	v_mfma_f32_16x16x32_bf16 v[84:87], v[168:171], v[200:203], 0
	v_mfma_f32_16x16x32_bf16 v[80:83], v[176:179], v[200:203], 0
	v_mfma_f32_16x16x32_bf16 v[68:71], v[168:171], v[208:211], 0
	v_mfma_f32_16x16x32_bf16 v[64:67], v[176:179], v[208:211], 0
	v_mfma_f32_16x16x32_bf16 v[116:119], v[172:175], v[188:191], v[116:119]
	v_mfma_f32_16x16x32_bf16 v[112:115], v[180:183], v[188:191], v[112:115]
	v_mfma_f32_16x16x32_bf16 v[100:103], v[172:175], v[196:199], v[100:103]
	v_mfma_f32_16x16x32_bf16 v[96:99], v[180:183], v[196:199], v[96:99]
	s_setprio 2
	s_barrier
	v_mfma_f32_16x16x32_bf16 v[84:87], v[172:175], v[204:207], v[84:87]
	v_mfma_f32_16x16x32_bf16 v[80:83], v[180:183], v[204:207], v[80:83]
	v_mfma_f32_16x16x32_bf16 v[68:71], v[172:175], v[212:215], v[68:71]
	v_mfma_f32_16x16x32_bf16 v[64:67], v[180:183], v[212:215], v[64:67]
	s_setprio 2
	s_add_i32 s66, s59, s47
	v_lshl_add_u64 v[160:161], s[38:39], 0, v[132:133]
	s_mov_b32 m0, s66
	ds_read_b128 v[184:187], v165 offset:16384
	ds_read_b128 v[188:191], v165 offset:17408
	ds_read_b128 v[192:195], v165 offset:18432
	ds_read_b128 v[196:199], v165 offset:19456
	ds_read_b128 v[200:203], v165 offset:20480
	ds_read_b128 v[204:207], v165 offset:21504
	ds_read_b128 v[208:211], v165 offset:22528
	ds_read_b128 v[212:215], v165 offset:23552
	global_load_lds_dwordx4 v[160:161], off
	s_add_i32 m0, s66, 0x2000
	s_add_u32 s66, s38, 0x40000
	v_lshl_add_u64 v[216:217], s[38:39], 0, v[128:129]
	s_addc_u32 s67, s39, 0
	s_add_i32 s68, s60, s47
	global_load_lds_dwordx4 v[216:217], off
	v_lshl_add_u64 v[218:219], s[66:67], 0, v[132:133]
	s_mov_b32 m0, s68
	v_lshl_add_u64 v[220:221], s[40:41], 0, v[130:131]
	global_load_lds_dwordx4 v[218:219], off
	s_add_i32 m0, s68, 0x2000
	v_lshl_add_u64 v[218:219], s[66:67], 0, v[128:129]
	global_load_lds_dwordx4 v[218:219], off
	s_mov_b32 m0, s50
	v_lshl_add_u64 v[218:219], s[40:41], 0, v[134:135]
	global_load_lds_dwordx4 v[218:219], off
	s_mov_b32 m0, s51
	s_nop 0
	global_load_lds_dwordx4 v[220:221], off
	s_waitcnt vmcnt(8)
	s_waitcnt lgkmcnt(0)
	s_barrier
	s_setprio 1
	s_waitcnt lgkmcnt(0)
	v_mfma_f32_16x16x32_bf16 v[60:63], v[144:147], v[184:187], 0
	v_mfma_f32_16x16x32_bf16 v[56:59], v[152:155], v[184:187], 0
	v_mfma_f32_16x16x32_bf16 v[44:47], v[144:147], v[192:195], 0
	v_mfma_f32_16x16x32_bf16 v[40:43], v[152:155], v[192:195], 0
	v_mfma_f32_16x16x32_bf16 v[28:31], v[144:147], v[200:203], 0
	v_mfma_f32_16x16x32_bf16 v[24:27], v[152:155], v[200:203], 0
	v_mfma_f32_16x16x32_bf16 v[12:15], v[144:147], v[208:211], 0
	v_mfma_f32_16x16x32_bf16 v[8:11], v[152:155], v[208:211], 0
	v_mfma_f32_16x16x32_bf16 v[60:63], v[148:151], v[188:191], v[60:63]
	v_mfma_f32_16x16x32_bf16 v[56:59], v[156:159], v[188:191], v[56:59]
	v_mfma_f32_16x16x32_bf16 v[44:47], v[148:151], v[196:199], v[44:47]
	v_mfma_f32_16x16x32_bf16 v[40:43], v[156:159], v[196:199], v[40:43]
	v_mfma_f32_16x16x32_bf16 v[28:31], v[148:151], v[204:207], v[28:31]
	v_mfma_f32_16x16x32_bf16 v[24:27], v[156:159], v[204:207], v[24:27]
	v_mfma_f32_16x16x32_bf16 v[12:15], v[148:151], v[212:215], v[12:15]
	v_mfma_f32_16x16x32_bf16 v[8:11], v[156:159], v[212:215], v[8:11]
	s_setprio 0
	s_setprio 1
	v_mfma_f32_16x16x32_bf16 v[52:55], v[168:171], v[184:187], 0
	v_mfma_f32_16x16x32_bf16 v[48:51], v[176:179], v[184:187], 0
	v_mfma_f32_16x16x32_bf16 v[36:39], v[168:171], v[192:195], 0
	v_mfma_f32_16x16x32_bf16 v[32:35], v[176:179], v[192:195], 0
	v_mfma_f32_16x16x32_bf16 v[20:23], v[168:171], v[200:203], 0
	v_mfma_f32_16x16x32_bf16 v[16:19], v[176:179], v[200:203], 0
	v_mfma_f32_16x16x32_bf16 v[4:7], v[168:171], v[208:211], 0
	v_mfma_f32_16x16x32_bf16 v[0:3], v[176:179], v[208:211], 0
	v_mfma_f32_16x16x32_bf16 v[52:55], v[172:175], v[188:191], v[52:55]
	v_mfma_f32_16x16x32_bf16 v[48:51], v[180:183], v[188:191], v[48:51]
	v_mfma_f32_16x16x32_bf16 v[36:39], v[172:175], v[196:199], v[36:39]
	v_mfma_f32_16x16x32_bf16 v[32:35], v[180:183], v[196:199], v[32:35]
	s_setprio 2
	s_barrier
	v_mfma_f32_16x16x32_bf16 v[20:23], v[172:175], v[204:207], v[20:23]
	v_mfma_f32_16x16x32_bf16 v[16:19], v[180:183], v[204:207], v[16:19]
	v_mfma_f32_16x16x32_bf16 v[4:7], v[172:175], v[212:215], v[4:7]
	v_mfma_f32_16x16x32_bf16 v[0:3], v[180:183], v[212:215], v[0:3]
	s_setprio 0
	s_add_i32 s66, 0, 0x18000
	s_add_i32 s67, 0, 0x1c000
	v_add_u32_e32 v156, s66, v162
	v_add_u32_e32 v167, s67, v162
	ds_read_b128 v[144:147], v156
	ds_read_b128 v[148:151], v156 offset:1024
	ds_read_b128 v[152:155], v156 offset:2048
	ds_read_b128 v[156:159], v156 offset:3072
	ds_read_b128 v[168:171], v167
	ds_read_b128 v[172:175], v167 offset:1024
	ds_read_b128 v[176:179], v167 offset:2048
	ds_read_b128 v[180:183], v167 offset:3072
	s_add_u32 s40, s40, 0x40000
	s_addc_u32 s41, s41, 0
	s_mov_b32 m0, s54
	v_lshl_add_u64 v[222:223], s[40:41], 0, v[134:135]
	ds_read_b128 v[184:187], v165 offset:32768
	ds_read_b128 v[188:191], v165 offset:33792
	ds_read_b128 v[192:195], v165 offset:34816
	ds_read_b128 v[196:199], v165 offset:35840
	ds_read_b128 v[200:203], v165 offset:36864
	ds_read_b128 v[204:207], v165 offset:37888
	ds_read_b128 v[208:211], v165 offset:38912
	ds_read_b128 v[212:215], v165 offset:39936
	global_load_lds_dwordx4 v[222:223], off
	s_mov_b32 m0, s55
	v_lshl_add_u64 v[222:223], s[40:41], 0, v[130:131]
	global_load_lds_dwordx4 v[222:223], off
	s_waitcnt vmcnt(8)
	s_waitcnt lgkmcnt(0)
	s_barrier
	s_setprio 1
	s_waitcnt lgkmcnt(0)
	v_mfma_f32_16x16x32_bf16 v[124:127], v[144:147], v[184:187], v[124:127]
	v_mfma_f32_16x16x32_bf16 v[120:123], v[152:155], v[184:187], v[120:123]
	v_mfma_f32_16x16x32_bf16 v[108:111], v[144:147], v[192:195], v[108:111]
	v_mfma_f32_16x16x32_bf16 v[104:107], v[152:155], v[192:195], v[104:107]
	v_mfma_f32_16x16x32_bf16 v[92:95], v[144:147], v[200:203], v[92:95]
	v_mfma_f32_16x16x32_bf16 v[88:91], v[152:155], v[200:203], v[88:91]
	v_mfma_f32_16x16x32_bf16 v[76:79], v[144:147], v[208:211], v[76:79]
	v_mfma_f32_16x16x32_bf16 v[72:75], v[152:155], v[208:211], v[72:75]
	v_mfma_f32_16x16x32_bf16 v[124:127], v[148:151], v[188:191], v[124:127]
	v_mfma_f32_16x16x32_bf16 v[120:123], v[156:159], v[188:191], v[120:123]
	v_mfma_f32_16x16x32_bf16 v[108:111], v[148:151], v[196:199], v[108:111]
	v_mfma_f32_16x16x32_bf16 v[104:107], v[156:159], v[196:199], v[104:107]
	v_mfma_f32_16x16x32_bf16 v[92:95], v[148:151], v[204:207], v[92:95]
	v_mfma_f32_16x16x32_bf16 v[88:91], v[156:159], v[204:207], v[88:91]
	v_mfma_f32_16x16x32_bf16 v[76:79], v[148:151], v[212:215], v[76:79]
	v_mfma_f32_16x16x32_bf16 v[72:75], v[156:159], v[212:215], v[72:75]
	s_setprio 0
	s_setprio 1
	v_mfma_f32_16x16x32_bf16 v[116:119], v[168:171], v[184:187], v[116:119]
	v_mfma_f32_16x16x32_bf16 v[112:115], v[176:179], v[184:187], v[112:115]
	v_mfma_f32_16x16x32_bf16 v[100:103], v[168:171], v[192:195], v[100:103]
	v_mfma_f32_16x16x32_bf16 v[96:99], v[176:179], v[192:195], v[96:99]
	v_mfma_f32_16x16x32_bf16 v[84:87], v[168:171], v[200:203], v[84:87]
	v_mfma_f32_16x16x32_bf16 v[80:83], v[176:179], v[200:203], v[80:83]
	v_mfma_f32_16x16x32_bf16 v[68:71], v[168:171], v[208:211], v[68:71]
	v_mfma_f32_16x16x32_bf16 v[64:67], v[176:179], v[208:211], v[64:67]
	v_mfma_f32_16x16x32_bf16 v[116:119], v[172:175], v[188:191], v[116:119]
	v_mfma_f32_16x16x32_bf16 v[112:115], v[180:183], v[188:191], v[112:115]
	v_mfma_f32_16x16x32_bf16 v[100:103], v[172:175], v[196:199], v[100:103]
	v_mfma_f32_16x16x32_bf16 v[96:99], v[180:183], v[196:199], v[96:99]
	s_setprio 2
	s_barrier
	v_mfma_f32_16x16x32_bf16 v[84:87], v[172:175], v[204:207], v[84:87]
	v_mfma_f32_16x16x32_bf16 v[80:83], v[180:183], v[204:207], v[80:83]
	v_mfma_f32_16x16x32_bf16 v[68:71], v[172:175], v[212:215], v[68:71]
	v_mfma_f32_16x16x32_bf16 v[64:67], v[180:183], v[212:215], v[64:67]
	s_setprio 2
	s_add_i32 s40, s66, s47
	v_lshl_add_u64 v[160:161], v[160:161], 0, s[16:17]
	s_mov_b32 m0, s40
	ds_read_b128 v[184:187], v165 offset:49152
	ds_read_b128 v[188:191], v165 offset:50176
	ds_read_b128 v[192:195], v165 offset:51200
	ds_read_b128 v[196:199], v165 offset:52224
	ds_read_b128 v[200:203], v165 offset:53248
	ds_read_b128 v[204:207], v165 offset:54272
	ds_read_b128 v[208:211], v165 offset:55296
	ds_read_b128 v[212:215], v165 offset:56320
	global_load_lds_dwordx4 v[160:161], off
	s_add_i32 m0, s40, 0x2000
	s_add_u32 s38, s38, 0x40080
	v_lshl_add_u64 v[160:161], v[216:217], 0, s[16:17]
	s_addc_u32 s39, s39, 0
	s_add_i32 s40, s67, s47
	global_load_lds_dwordx4 v[160:161], off
	s_mov_b32 m0, s40
	v_lshl_add_u64 v[160:161], s[38:39], 0, v[132:133]
	global_load_lds_dwordx4 v[160:161], off
	s_add_i32 m0, s40, 0x2000
	v_lshl_add_u64 v[160:161], s[38:39], 0, v[128:129]
	global_load_lds_dwordx4 v[160:161], off
	s_mov_b32 m0, s57
	v_lshl_add_u64 v[160:161], v[218:219], 0, s[16:17]
	global_load_lds_dwordx4 v[160:161], off
	s_mov_b32 m0, s58
	v_lshl_add_u64 v[160:161], v[220:221], 0, s[16:17]
	global_load_lds_dwordx4 v[160:161], off
	s_waitcnt vmcnt(8)
	s_waitcnt lgkmcnt(0)
	s_barrier
	s_setprio 1
	s_waitcnt lgkmcnt(0)
	v_mfma_f32_16x16x32_bf16 v[60:63], v[144:147], v[184:187], v[60:63]
	v_mfma_f32_16x16x32_bf16 v[56:59], v[152:155], v[184:187], v[56:59]
	v_mfma_f32_16x16x32_bf16 v[44:47], v[144:147], v[192:195], v[44:47]
	v_mfma_f32_16x16x32_bf16 v[40:43], v[152:155], v[192:195], v[40:43]
	v_mfma_f32_16x16x32_bf16 v[28:31], v[144:147], v[200:203], v[28:31]
	v_mfma_f32_16x16x32_bf16 v[24:27], v[152:155], v[200:203], v[24:27]
	v_mfma_f32_16x16x32_bf16 v[12:15], v[144:147], v[208:211], v[12:15]
	v_mfma_f32_16x16x32_bf16 v[8:11], v[152:155], v[208:211], v[8:11]
	v_mfma_f32_16x16x32_bf16 v[60:63], v[148:151], v[188:191], v[60:63]
	v_mfma_f32_16x16x32_bf16 v[56:59], v[156:159], v[188:191], v[56:59]
	v_mfma_f32_16x16x32_bf16 v[44:47], v[148:151], v[196:199], v[44:47]
	v_mfma_f32_16x16x32_bf16 v[40:43], v[156:159], v[196:199], v[40:43]
	v_mfma_f32_16x16x32_bf16 v[28:31], v[148:151], v[204:207], v[28:31]
	v_mfma_f32_16x16x32_bf16 v[24:27], v[156:159], v[204:207], v[24:27]
	v_mfma_f32_16x16x32_bf16 v[12:15], v[148:151], v[212:215], v[12:15]
	v_mfma_f32_16x16x32_bf16 v[8:11], v[156:159], v[212:215], v[8:11]
	s_setprio 0
	s_setprio 1
	v_mfma_f32_16x16x32_bf16 v[52:55], v[168:171], v[184:187], v[52:55]
	v_mfma_f32_16x16x32_bf16 v[48:51], v[176:179], v[184:187], v[48:51]
	v_mfma_f32_16x16x32_bf16 v[36:39], v[168:171], v[192:195], v[36:39]
	v_mfma_f32_16x16x32_bf16 v[32:35], v[176:179], v[192:195], v[32:35]
	v_mfma_f32_16x16x32_bf16 v[20:23], v[168:171], v[200:203], v[20:23]
	v_mfma_f32_16x16x32_bf16 v[16:19], v[176:179], v[200:203], v[16:19]
	v_mfma_f32_16x16x32_bf16 v[4:7], v[168:171], v[208:211], v[4:7]
	v_mfma_f32_16x16x32_bf16 v[0:3], v[176:179], v[208:211], v[0:3]
	v_mfma_f32_16x16x32_bf16 v[52:55], v[172:175], v[188:191], v[52:55]
	v_mfma_f32_16x16x32_bf16 v[48:51], v[180:183], v[188:191], v[48:51]
	v_mfma_f32_16x16x32_bf16 v[36:39], v[172:175], v[196:199], v[36:39]
	v_mfma_f32_16x16x32_bf16 v[32:35], v[180:183], v[196:199], v[32:35]
	s_setprio 2
	s_barrier
	v_mfma_f32_16x16x32_bf16 v[20:23], v[172:175], v[204:207], v[20:23]
	v_mfma_f32_16x16x32_bf16 v[16:19], v[180:183], v[204:207], v[16:19]
	v_mfma_f32_16x16x32_bf16 v[4:7], v[172:175], v[212:215], v[4:7]
	v_mfma_f32_16x16x32_bf16 v[0:3], v[180:183], v[212:215], v[0:3]
	s_setprio 0
	s_add_i32 s65, s65, 2
	s_add_u32 s36, s36, 0x100
	s_addc_u32 s37, s37, 0
	s_add_u32 s63, s63, 0x100
	s_addc_u32 s64, s64, 0
	s_cmp_gt_u32 s65, 13
.LBB0_784:
	ds_read_b128 v[144:147], v163
	ds_read_b128 v[148:151], v163 offset:1024
	ds_read_b128 v[152:155], v163 offset:2048
	ds_read_b128 v[156:159], v163 offset:3072
	ds_read_b128 v[168:171], v164
	ds_read_b128 v[172:175], v164 offset:1024
	ds_read_b128 v[176:179], v164 offset:2048
	ds_read_b128 v[180:183], v164 offset:3072
	s_add_u32 s38, s36, 0xfffc0080
	s_addc_u32 s39, s37, -1
	s_cmp_eq_u32 s65, 12
	s_cselect_b32 s41, s23, s39
	s_cselect_b32 s40, s31, s38
	s_cselect_b32 s39, s25, s64
	s_cselect_b32 s38, s62, s63
	v_lshl_add_u64 v[160:161], s[36:37], 0, v[136:137]
	s_add_i32 m0, s50, 0xc000
	ds_read_b128 v[184:187], v165
	ds_read_b128 v[188:191], v165 offset:1024
	ds_read_b128 v[192:195], v165 offset:2048
	ds_read_b128 v[196:199], v165 offset:3072
	ds_read_b128 v[200:203], v165 offset:4096
	ds_read_b128 v[204:207], v165 offset:5120
	ds_read_b128 v[208:211], v165 offset:6144
	ds_read_b128 v[212:215], v165 offset:7168
	global_load_lds_dwordx4 v[160:161], off
	s_add_i32 m0, s50, 0xe000
	v_lshl_add_u64 v[160:161], s[36:37], 0, v[138:139]
	global_load_lds_dwordx4 v[160:161], off
	s_waitcnt vmcnt(8)
	s_waitcnt lgkmcnt(0)
	s_barrier
	s_setprio 1
	s_waitcnt lgkmcnt(0)
	v_mfma_f32_16x16x32_bf16 v[124:127], v[144:147], v[184:187], v[124:127]
	v_mfma_f32_16x16x32_bf16 v[120:123], v[152:155], v[184:187], v[120:123]
	v_mfma_f32_16x16x32_bf16 v[108:111], v[144:147], v[192:195], v[108:111]
	v_mfma_f32_16x16x32_bf16 v[104:107], v[152:155], v[192:195], v[104:107]
	v_mfma_f32_16x16x32_bf16 v[92:95], v[144:147], v[200:203], v[92:95]
	v_mfma_f32_16x16x32_bf16 v[88:91], v[152:155], v[200:203], v[88:91]
	v_mfma_f32_16x16x32_bf16 v[76:79], v[144:147], v[208:211], v[76:79]
	v_mfma_f32_16x16x32_bf16 v[72:75], v[152:155], v[208:211], v[72:75]
	v_mfma_f32_16x16x32_bf16 v[124:127], v[148:151], v[188:191], v[124:127]
	v_mfma_f32_16x16x32_bf16 v[120:123], v[156:159], v[188:191], v[120:123]
	v_mfma_f32_16x16x32_bf16 v[108:111], v[148:151], v[196:199], v[108:111]
	v_mfma_f32_16x16x32_bf16 v[104:107], v[156:159], v[196:199], v[104:107]
	v_mfma_f32_16x16x32_bf16 v[92:95], v[148:151], v[204:207], v[92:95]
	v_mfma_f32_16x16x32_bf16 v[88:91], v[156:159], v[204:207], v[88:91]
	v_mfma_f32_16x16x32_bf16 v[76:79], v[148:151], v[212:215], v[76:79]
	v_mfma_f32_16x16x32_bf16 v[72:75], v[156:159], v[212:215], v[72:75]
	s_setprio 0
	s_setprio 1
	v_mfma_f32_16x16x32_bf16 v[116:119], v[168:171], v[184:187], v[116:119]
	v_mfma_f32_16x16x32_bf16 v[112:115], v[176:179], v[184:187], v[112:115]
	v_mfma_f32_16x16x32_bf16 v[100:103], v[168:171], v[192:195], v[100:103]
	v_mfma_f32_16x16x32_bf16 v[96:99], v[176:179], v[192:195], v[96:99]
	v_mfma_f32_16x16x32_bf16 v[84:87], v[168:171], v[200:203], v[84:87]
	v_mfma_f32_16x16x32_bf16 v[80:83], v[176:179], v[200:203], v[80:83]
	v_mfma_f32_16x16x32_bf16 v[68:71], v[168:171], v[208:211], v[68:71]
	v_mfma_f32_16x16x32_bf16 v[64:67], v[176:179], v[208:211], v[64:67]
	v_mfma_f32_16x16x32_bf16 v[116:119], v[172:175], v[188:191], v[116:119]
	v_mfma_f32_16x16x32_bf16 v[112:115], v[180:183], v[188:191], v[112:115]
	v_mfma_f32_16x16x32_bf16 v[100:103], v[172:175], v[196:199], v[100:103]
	v_mfma_f32_16x16x32_bf16 v[96:99], v[180:183], v[196:199], v[96:99]
	s_setprio 2
	s_barrier
	v_mfma_f32_16x16x32_bf16 v[84:87], v[172:175], v[204:207], v[84:87]
	v_mfma_f32_16x16x32_bf16 v[80:83], v[180:183], v[204:207], v[80:83]
	v_mfma_f32_16x16x32_bf16 v[68:71], v[172:175], v[212:215], v[68:71]
	v_mfma_f32_16x16x32_bf16 v[64:67], v[180:183], v[212:215], v[64:67]
	s_setprio 2
	s_add_i32 s66, s59, s47
	v_lshl_add_u64 v[160:161], s[38:39], 0, v[132:133]
	s_mov_b32 m0, s66
	ds_read_b128 v[184:187], v165 offset:16384
	ds_read_b128 v[188:191], v165 offset:17408
	ds_read_b128 v[192:195], v165 offset:18432
	ds_read_b128 v[196:199], v165 offset:19456
	ds_read_b128 v[200:203], v165 offset:20480
	ds_read_b128 v[204:207], v165 offset:21504
	ds_read_b128 v[208:211], v165 offset:22528
	ds_read_b128 v[212:215], v165 offset:23552
	global_load_lds_dwordx4 v[160:161], off
	s_add_i32 m0, s66, 0x2000
	s_add_u32 s66, s38, 0x40000
	v_lshl_add_u64 v[216:217], s[38:39], 0, v[128:129]
	s_addc_u32 s67, s39, 0
	s_add_i32 s68, s60, s47
	global_load_lds_dwordx4 v[216:217], off
	v_lshl_add_u64 v[218:219], s[66:67], 0, v[132:133]
	s_mov_b32 m0, s68
	v_lshl_add_u64 v[220:221], s[40:41], 0, v[130:131]
	global_load_lds_dwordx4 v[218:219], off
	s_add_i32 m0, s68, 0x2000
	v_lshl_add_u64 v[218:219], s[66:67], 0, v[128:129]
	global_load_lds_dwordx4 v[218:219], off
	s_mov_b32 m0, s50
	v_lshl_add_u64 v[218:219], s[40:41], 0, v[134:135]
	global_load_lds_dwordx4 v[218:219], off
	s_mov_b32 m0, s51
	s_nop 0
	global_load_lds_dwordx4 v[220:221], off
	s_waitcnt vmcnt(8)
	s_waitcnt lgkmcnt(0)
	s_barrier
	s_setprio 1
	s_waitcnt lgkmcnt(0)
	v_mfma_f32_16x16x32_bf16 v[60:63], v[144:147], v[184:187], v[60:63]
	v_mfma_f32_16x16x32_bf16 v[56:59], v[152:155], v[184:187], v[56:59]
	v_mfma_f32_16x16x32_bf16 v[44:47], v[144:147], v[192:195], v[44:47]
	v_mfma_f32_16x16x32_bf16 v[40:43], v[152:155], v[192:195], v[40:43]
	v_mfma_f32_16x16x32_bf16 v[28:31], v[144:147], v[200:203], v[28:31]
	v_mfma_f32_16x16x32_bf16 v[24:27], v[152:155], v[200:203], v[24:27]
	v_mfma_f32_16x16x32_bf16 v[12:15], v[144:147], v[208:211], v[12:15]
	v_mfma_f32_16x16x32_bf16 v[8:11], v[152:155], v[208:211], v[8:11]
	v_mfma_f32_16x16x32_bf16 v[60:63], v[148:151], v[188:191], v[60:63]
	v_mfma_f32_16x16x32_bf16 v[56:59], v[156:159], v[188:191], v[56:59]
	v_mfma_f32_16x16x32_bf16 v[44:47], v[148:151], v[196:199], v[44:47]
	v_mfma_f32_16x16x32_bf16 v[40:43], v[156:159], v[196:199], v[40:43]
	v_mfma_f32_16x16x32_bf16 v[28:31], v[148:151], v[204:207], v[28:31]
	v_mfma_f32_16x16x32_bf16 v[24:27], v[156:159], v[204:207], v[24:27]
	v_mfma_f32_16x16x32_bf16 v[12:15], v[148:151], v[212:215], v[12:15]
	v_mfma_f32_16x16x32_bf16 v[8:11], v[156:159], v[212:215], v[8:11]
	s_setprio 0
	s_setprio 1
	v_mfma_f32_16x16x32_bf16 v[52:55], v[168:171], v[184:187], v[52:55]
	v_mfma_f32_16x16x32_bf16 v[48:51], v[176:179], v[184:187], v[48:51]
	v_mfma_f32_16x16x32_bf16 v[36:39], v[168:171], v[192:195], v[36:39]
	v_mfma_f32_16x16x32_bf16 v[32:35], v[176:179], v[192:195], v[32:35]
	v_mfma_f32_16x16x32_bf16 v[20:23], v[168:171], v[200:203], v[20:23]
	v_mfma_f32_16x16x32_bf16 v[16:19], v[176:179], v[200:203], v[16:19]
	v_mfma_f32_16x16x32_bf16 v[4:7], v[168:171], v[208:211], v[4:7]
	v_mfma_f32_16x16x32_bf16 v[0:3], v[176:179], v[208:211], v[0:3]
	v_mfma_f32_16x16x32_bf16 v[52:55], v[172:175], v[188:191], v[52:55]
	v_mfma_f32_16x16x32_bf16 v[48:51], v[180:183], v[188:191], v[48:51]
	v_mfma_f32_16x16x32_bf16 v[36:39], v[172:175], v[196:199], v[36:39]
	v_mfma_f32_16x16x32_bf16 v[32:35], v[180:183], v[196:199], v[32:35]
	s_setprio 2
	s_barrier
	v_mfma_f32_16x16x32_bf16 v[20:23], v[172:175], v[204:207], v[20:23]
	v_mfma_f32_16x16x32_bf16 v[16:19], v[180:183], v[204:207], v[16:19]
	v_mfma_f32_16x16x32_bf16 v[4:7], v[172:175], v[212:215], v[4:7]
	v_mfma_f32_16x16x32_bf16 v[0:3], v[180:183], v[212:215], v[0:3]
	s_setprio 0
	s_add_i32 s66, 0, 0x18000
	s_add_i32 s67, 0, 0x1c000
	v_add_u32_e32 v156, s66, v162
	v_add_u32_e32 v167, s67, v162
	ds_read_b128 v[144:147], v156
	ds_read_b128 v[148:151], v156 offset:1024
	ds_read_b128 v[152:155], v156 offset:2048
	ds_read_b128 v[156:159], v156 offset:3072
	ds_read_b128 v[168:171], v167
	ds_read_b128 v[172:175], v167 offset:1024
	ds_read_b128 v[176:179], v167 offset:2048
	ds_read_b128 v[180:183], v167 offset:3072
	s_add_u32 s40, s40, 0x40000
	s_addc_u32 s41, s41, 0
	s_mov_b32 m0, s54
	v_lshl_add_u64 v[222:223], s[40:41], 0, v[134:135]
	ds_read_b128 v[184:187], v165 offset:32768
	ds_read_b128 v[188:191], v165 offset:33792
	ds_read_b128 v[192:195], v165 offset:34816
	ds_read_b128 v[196:199], v165 offset:35840
	ds_read_b128 v[200:203], v165 offset:36864
	ds_read_b128 v[204:207], v165 offset:37888
	ds_read_b128 v[208:211], v165 offset:38912
	ds_read_b128 v[212:215], v165 offset:39936
	global_load_lds_dwordx4 v[222:223], off
	s_mov_b32 m0, s55
	v_lshl_add_u64 v[222:223], s[40:41], 0, v[130:131]
	global_load_lds_dwordx4 v[222:223], off
	s_waitcnt vmcnt(8)
	s_waitcnt lgkmcnt(0)
	s_barrier
	s_setprio 1
	s_waitcnt lgkmcnt(0)
	v_mfma_f32_16x16x32_bf16 v[124:127], v[144:147], v[184:187], v[124:127]
	v_mfma_f32_16x16x32_bf16 v[120:123], v[152:155], v[184:187], v[120:123]
	v_mfma_f32_16x16x32_bf16 v[108:111], v[144:147], v[192:195], v[108:111]
	v_mfma_f32_16x16x32_bf16 v[104:107], v[152:155], v[192:195], v[104:107]
	v_mfma_f32_16x16x32_bf16 v[92:95], v[144:147], v[200:203], v[92:95]
	v_mfma_f32_16x16x32_bf16 v[88:91], v[152:155], v[200:203], v[88:91]
	v_mfma_f32_16x16x32_bf16 v[76:79], v[144:147], v[208:211], v[76:79]
	v_mfma_f32_16x16x32_bf16 v[72:75], v[152:155], v[208:211], v[72:75]
	v_mfma_f32_16x16x32_bf16 v[124:127], v[148:151], v[188:191], v[124:127]
	v_mfma_f32_16x16x32_bf16 v[120:123], v[156:159], v[188:191], v[120:123]
	v_mfma_f32_16x16x32_bf16 v[108:111], v[148:151], v[196:199], v[108:111]
	v_mfma_f32_16x16x32_bf16 v[104:107], v[156:159], v[196:199], v[104:107]
	v_mfma_f32_16x16x32_bf16 v[92:95], v[148:151], v[204:207], v[92:95]
	v_mfma_f32_16x16x32_bf16 v[88:91], v[156:159], v[204:207], v[88:91]
	v_mfma_f32_16x16x32_bf16 v[76:79], v[148:151], v[212:215], v[76:79]
	v_mfma_f32_16x16x32_bf16 v[72:75], v[156:159], v[212:215], v[72:75]
	s_setprio 0
	s_setprio 1
	v_mfma_f32_16x16x32_bf16 v[116:119], v[168:171], v[184:187], v[116:119]
	v_mfma_f32_16x16x32_bf16 v[112:115], v[176:179], v[184:187], v[112:115]
	v_mfma_f32_16x16x32_bf16 v[100:103], v[168:171], v[192:195], v[100:103]
	v_mfma_f32_16x16x32_bf16 v[96:99], v[176:179], v[192:195], v[96:99]
	v_mfma_f32_16x16x32_bf16 v[84:87], v[168:171], v[200:203], v[84:87]
	v_mfma_f32_16x16x32_bf16 v[80:83], v[176:179], v[200:203], v[80:83]
	v_mfma_f32_16x16x32_bf16 v[68:71], v[168:171], v[208:211], v[68:71]
	v_mfma_f32_16x16x32_bf16 v[64:67], v[176:179], v[208:211], v[64:67]
	v_mfma_f32_16x16x32_bf16 v[116:119], v[172:175], v[188:191], v[116:119]
	v_mfma_f32_16x16x32_bf16 v[112:115], v[180:183], v[188:191], v[112:115]
	v_mfma_f32_16x16x32_bf16 v[100:103], v[172:175], v[196:199], v[100:103]
	v_mfma_f32_16x16x32_bf16 v[96:99], v[180:183], v[196:199], v[96:99]
	s_setprio 2
	s_barrier
	v_mfma_f32_16x16x32_bf16 v[84:87], v[172:175], v[204:207], v[84:87]
	v_mfma_f32_16x16x32_bf16 v[80:83], v[180:183], v[204:207], v[80:83]
	v_mfma_f32_16x16x32_bf16 v[68:71], v[172:175], v[212:215], v[68:71]
	v_mfma_f32_16x16x32_bf16 v[64:67], v[180:183], v[212:215], v[64:67]
	s_setprio 2
	s_add_i32 s40, s66, s47
	v_lshl_add_u64 v[160:161], v[160:161], 0, s[16:17]
	s_mov_b32 m0, s40
	ds_read_b128 v[184:187], v165 offset:49152
	ds_read_b128 v[188:191], v165 offset:50176
	ds_read_b128 v[192:195], v165 offset:51200
	ds_read_b128 v[196:199], v165 offset:52224
	ds_read_b128 v[200:203], v165 offset:53248
	ds_read_b128 v[204:207], v165 offset:54272
	ds_read_b128 v[208:211], v165 offset:55296
	ds_read_b128 v[212:215], v165 offset:56320
	global_load_lds_dwordx4 v[160:161], off
	s_add_i32 m0, s40, 0x2000
	s_add_u32 s38, s38, 0x40080
	v_lshl_add_u64 v[160:161], v[216:217], 0, s[16:17]
	s_addc_u32 s39, s39, 0
	s_add_i32 s40, s67, s47
	global_load_lds_dwordx4 v[160:161], off
	s_mov_b32 m0, s40
	v_lshl_add_u64 v[160:161], s[38:39], 0, v[132:133]
	global_load_lds_dwordx4 v[160:161], off
	s_add_i32 m0, s40, 0x2000
	v_lshl_add_u64 v[160:161], s[38:39], 0, v[128:129]
	global_load_lds_dwordx4 v[160:161], off
	s_mov_b32 m0, s57
	v_lshl_add_u64 v[160:161], v[218:219], 0, s[16:17]
	global_load_lds_dwordx4 v[160:161], off
	s_mov_b32 m0, s58
	v_lshl_add_u64 v[160:161], v[220:221], 0, s[16:17]
	global_load_lds_dwordx4 v[160:161], off
	s_waitcnt vmcnt(8)
	s_waitcnt lgkmcnt(0)
	s_barrier
	s_setprio 1
	s_waitcnt lgkmcnt(0)
	v_mfma_f32_16x16x32_bf16 v[60:63], v[144:147], v[184:187], v[60:63]
	v_mfma_f32_16x16x32_bf16 v[56:59], v[152:155], v[184:187], v[56:59]
	v_mfma_f32_16x16x32_bf16 v[44:47], v[144:147], v[192:195], v[44:47]
	v_mfma_f32_16x16x32_bf16 v[40:43], v[152:155], v[192:195], v[40:43]
	v_mfma_f32_16x16x32_bf16 v[28:31], v[144:147], v[200:203], v[28:31]
	v_mfma_f32_16x16x32_bf16 v[24:27], v[152:155], v[200:203], v[24:27]
	v_mfma_f32_16x16x32_bf16 v[12:15], v[144:147], v[208:211], v[12:15]
	v_mfma_f32_16x16x32_bf16 v[8:11], v[152:155], v[208:211], v[8:11]
	v_mfma_f32_16x16x32_bf16 v[60:63], v[148:151], v[188:191], v[60:63]
	v_mfma_f32_16x16x32_bf16 v[56:59], v[156:159], v[188:191], v[56:59]
	v_mfma_f32_16x16x32_bf16 v[44:47], v[148:151], v[196:199], v[44:47]
	v_mfma_f32_16x16x32_bf16 v[40:43], v[156:159], v[196:199], v[40:43]
	v_mfma_f32_16x16x32_bf16 v[28:31], v[148:151], v[204:207], v[28:31]
	v_mfma_f32_16x16x32_bf16 v[24:27], v[156:159], v[204:207], v[24:27]
	v_mfma_f32_16x16x32_bf16 v[12:15], v[148:151], v[212:215], v[12:15]
	v_mfma_f32_16x16x32_bf16 v[8:11], v[156:159], v[212:215], v[8:11]
	s_setprio 0
	s_setprio 1
	v_mfma_f32_16x16x32_bf16 v[52:55], v[168:171], v[184:187], v[52:55]
	v_mfma_f32_16x16x32_bf16 v[48:51], v[176:179], v[184:187], v[48:51]
	v_mfma_f32_16x16x32_bf16 v[36:39], v[168:171], v[192:195], v[36:39]
	v_mfma_f32_16x16x32_bf16 v[32:35], v[176:179], v[192:195], v[32:35]
	v_mfma_f32_16x16x32_bf16 v[20:23], v[168:171], v[200:203], v[20:23]
	v_mfma_f32_16x16x32_bf16 v[16:19], v[176:179], v[200:203], v[16:19]
	v_mfma_f32_16x16x32_bf16 v[4:7], v[168:171], v[208:211], v[4:7]
	v_mfma_f32_16x16x32_bf16 v[0:3], v[176:179], v[208:211], v[0:3]
	v_mfma_f32_16x16x32_bf16 v[52:55], v[172:175], v[188:191], v[52:55]
	v_mfma_f32_16x16x32_bf16 v[48:51], v[180:183], v[188:191], v[48:51]
	v_mfma_f32_16x16x32_bf16 v[36:39], v[172:175], v[196:199], v[36:39]
	v_mfma_f32_16x16x32_bf16 v[32:35], v[180:183], v[196:199], v[32:35]
	s_setprio 2
	s_barrier
	v_mfma_f32_16x16x32_bf16 v[20:23], v[172:175], v[204:207], v[20:23]
	v_mfma_f32_16x16x32_bf16 v[16:19], v[180:183], v[204:207], v[16:19]
	v_mfma_f32_16x16x32_bf16 v[4:7], v[172:175], v[212:215], v[4:7]
	v_mfma_f32_16x16x32_bf16 v[0:3], v[180:183], v[212:215], v[0:3]
	s_setprio 0
	s_add_i32 s65, s65, 2
	s_add_u32 s36, s36, 0x100
	s_addc_u32 s37, s37, 0
	s_add_u32 s63, s63, 0x100
	s_addc_u32 s64, s64, 0
	s_cmp_gt_u32 s65, 13
	s_cbranch_scc0 .LBB0_784

.LBB0_865:
	s_add_u32 s62, s28, 0x100
	s_addc_u32 s63, s29, 0
	s_mov_b32 s64, -2
	ds_read_b128 v[120:123], v233
	ds_read_b128 v[124:127], v233 offset:1024
	ds_read_b128 v[136:139], v233 offset:2048
	ds_read_b128 v[140:143], v233 offset:3072
	ds_read_b128 v[144:147], v234
	ds_read_b128 v[148:151], v234 offset:1024
	ds_read_b128 v[152:155], v234 offset:2048
	ds_read_b128 v[156:159], v234 offset:3072
	s_add_u32 s28, s26, 0x100
	s_addc_u32 s29, s27, 0
	s_cmp_eq_u32 s64, 40
	s_cselect_b32 s37, s7, s29
	s_cselect_b32 s36, s6, s28
	s_cselect_b32 s31, s25, s63
	s_cselect_b32 s30, s24, s62
	v_lshl_add_u64 v[208:209], s[26:27], 0, v[192:193]
	s_add_i32 m0, s44, 0xc000
	ds_read_b128 v[160:163], v235
	ds_read_b128 v[164:167], v235 offset:1024
	ds_read_b128 v[168:171], v235 offset:2048
	ds_read_b128 v[172:175], v235 offset:3072
	ds_read_b128 v[176:179], v235 offset:4096
	ds_read_b128 v[180:183], v235 offset:5120
	ds_read_b128 v[200:203], v235 offset:6144
	ds_read_b128 v[204:207], v235 offset:7168
	global_load_lds_dwordx4 v[208:209], off
	s_add_i32 m0, s44, 0xe000
	v_lshl_add_u64 v[208:209], s[26:27], 0, v[194:195]
	global_load_lds_dwordx4 v[208:209], off
	s_waitcnt vmcnt(8)
	s_waitcnt lgkmcnt(0)
	s_barrier
	s_setprio 1
	s_waitcnt lgkmcnt(0)
	v_mfma_f32_16x16x32_bf16 v[132:135], v[120:123], v[160:163], 0
	v_mfma_f32_16x16x32_bf16 v[128:131], v[136:139], v[160:163], 0
	v_mfma_f32_16x16x32_bf16 v[108:111], v[120:123], v[168:171], 0
	v_mfma_f32_16x16x32_bf16 v[104:107], v[136:139], v[168:171], 0
	v_mfma_f32_16x16x32_bf16 v[92:95], v[120:123], v[176:179], 0
	v_mfma_f32_16x16x32_bf16 v[88:91], v[136:139], v[176:179], 0
	v_mfma_f32_16x16x32_bf16 v[76:79], v[120:123], v[200:203], 0
	v_mfma_f32_16x16x32_bf16 v[72:75], v[136:139], v[200:203], 0
	v_mfma_f32_16x16x32_bf16 v[132:135], v[124:127], v[164:167], v[132:135]
	v_mfma_f32_16x16x32_bf16 v[128:131], v[140:143], v[164:167], v[128:131]
	v_mfma_f32_16x16x32_bf16 v[108:111], v[124:127], v[172:175], v[108:111]
	v_mfma_f32_16x16x32_bf16 v[104:107], v[140:143], v[172:175], v[104:107]
	v_mfma_f32_16x16x32_bf16 v[92:95], v[124:127], v[180:183], v[92:95]
	v_mfma_f32_16x16x32_bf16 v[88:91], v[140:143], v[180:183], v[88:91]
	v_mfma_f32_16x16x32_bf16 v[76:79], v[124:127], v[204:207], v[76:79]
	v_mfma_f32_16x16x32_bf16 v[72:75], v[140:143], v[204:207], v[72:75]
	s_setprio 0
	s_setprio 1
	v_mfma_f32_16x16x32_bf16 v[116:119], v[144:147], v[160:163], 0
	v_mfma_f32_16x16x32_bf16 v[112:115], v[152:155], v[160:163], 0
	v_mfma_f32_16x16x32_bf16 v[100:103], v[144:147], v[168:171], 0
	v_mfma_f32_16x16x32_bf16 v[96:99], v[152:155], v[168:171], 0
	v_mfma_f32_16x16x32_bf16 v[84:87], v[144:147], v[176:179], 0
	v_mfma_f32_16x16x32_bf16 v[80:83], v[152:155], v[176:179], 0
	v_mfma_f32_16x16x32_bf16 v[68:71], v[144:147], v[200:203], 0
	v_mfma_f32_16x16x32_bf16 v[64:67], v[152:155], v[200:203], 0
	v_mfma_f32_16x16x32_bf16 v[116:119], v[148:151], v[164:167], v[116:119]
	v_mfma_f32_16x16x32_bf16 v[112:115], v[156:159], v[164:167], v[112:115]
	v_mfma_f32_16x16x32_bf16 v[100:103], v[148:151], v[172:175], v[100:103]
	v_mfma_f32_16x16x32_bf16 v[96:99], v[156:159], v[172:175], v[96:99]
	s_setprio 2
	s_barrier
	v_mfma_f32_16x16x32_bf16 v[84:87], v[148:151], v[180:183], v[84:87]
	v_mfma_f32_16x16x32_bf16 v[80:83], v[156:159], v[180:183], v[80:83]
	v_mfma_f32_16x16x32_bf16 v[68:71], v[148:151], v[204:207], v[68:71]
	v_mfma_f32_16x16x32_bf16 v[64:67], v[156:159], v[204:207], v[64:67]
	s_setprio 2
	s_add_i32 s26, s56, s43
	v_lshl_add_u64 v[208:209], s[30:31], 0, v[186:187]
	s_mov_b32 m0, s26
	ds_read_b128 v[160:163], v235 offset:16384
	ds_read_b128 v[164:167], v235 offset:17408
	ds_read_b128 v[168:171], v235 offset:18432
	ds_read_b128 v[172:175], v235 offset:19456
	ds_read_b128 v[176:179], v235 offset:20480
	ds_read_b128 v[180:183], v235 offset:21504
	ds_read_b128 v[200:203], v235 offset:22528
	ds_read_b128 v[204:207], v235 offset:23552
	global_load_lds_dwordx4 v[208:209], off
	s_add_i32 m0, s26, 0x2000
	s_add_u32 s26, s30, 0xb0000
	v_lshl_add_u64 v[210:211], s[30:31], 0, v[190:191]
	s_addc_u32 s27, s31, 0
	s_add_i32 s65, s57, s43
	global_load_lds_dwordx4 v[210:211], off
	v_lshl_add_u64 v[212:213], s[26:27], 0, v[186:187]
	s_mov_b32 m0, s65
	v_lshl_add_u64 v[214:215], s[36:37], 0, v[188:189]
	global_load_lds_dwordx4 v[212:213], off
	s_add_i32 m0, s65, 0x2000
	v_lshl_add_u64 v[212:213], s[26:27], 0, v[190:191]
	global_load_lds_dwordx4 v[212:213], off
	s_mov_b32 m0, s44
	v_lshl_add_u64 v[212:213], s[36:37], 0, v[184:185]
	global_load_lds_dwordx4 v[212:213], off
	s_mov_b32 m0, s45
	s_nop 0
	global_load_lds_dwordx4 v[214:215], off
	s_waitcnt vmcnt(8)
	s_waitcnt lgkmcnt(0)
	s_barrier
	s_setprio 1
	s_waitcnt lgkmcnt(0)
	v_mfma_f32_16x16x32_bf16 v[60:63], v[120:123], v[160:163], 0
	v_mfma_f32_16x16x32_bf16 v[56:59], v[136:139], v[160:163], 0
	v_mfma_f32_16x16x32_bf16 v[44:47], v[120:123], v[168:171], 0
	v_mfma_f32_16x16x32_bf16 v[40:43], v[136:139], v[168:171], 0
	v_mfma_f32_16x16x32_bf16 v[28:31], v[120:123], v[176:179], 0
	v_mfma_f32_16x16x32_bf16 v[24:27], v[136:139], v[176:179], 0
	v_mfma_f32_16x16x32_bf16 v[12:15], v[120:123], v[200:203], 0
	v_mfma_f32_16x16x32_bf16 v[8:11], v[136:139], v[200:203], 0
	v_mfma_f32_16x16x32_bf16 v[60:63], v[124:127], v[164:167], v[60:63]
	v_mfma_f32_16x16x32_bf16 v[56:59], v[140:143], v[164:167], v[56:59]
	v_mfma_f32_16x16x32_bf16 v[44:47], v[124:127], v[172:175], v[44:47]
	v_mfma_f32_16x16x32_bf16 v[40:43], v[140:143], v[172:175], v[40:43]
	v_mfma_f32_16x16x32_bf16 v[28:31], v[124:127], v[180:183], v[28:31]
	v_mfma_f32_16x16x32_bf16 v[24:27], v[140:143], v[180:183], v[24:27]
	v_mfma_f32_16x16x32_bf16 v[12:15], v[124:127], v[204:207], v[12:15]
	v_mfma_f32_16x16x32_bf16 v[8:11], v[140:143], v[204:207], v[8:11]
	s_setprio 0
	s_setprio 1
	v_mfma_f32_16x16x32_bf16 v[52:55], v[144:147], v[160:163], 0
	v_mfma_f32_16x16x32_bf16 v[48:51], v[152:155], v[160:163], 0
	v_mfma_f32_16x16x32_bf16 v[36:39], v[144:147], v[168:171], 0
	v_mfma_f32_16x16x32_bf16 v[32:35], v[152:155], v[168:171], 0
	v_mfma_f32_16x16x32_bf16 v[20:23], v[144:147], v[176:179], 0
	v_mfma_f32_16x16x32_bf16 v[16:19], v[152:155], v[176:179], 0
	v_mfma_f32_16x16x32_bf16 v[4:7], v[144:147], v[200:203], 0
	v_mfma_f32_16x16x32_bf16 v[0:3], v[152:155], v[200:203], 0
	v_mfma_f32_16x16x32_bf16 v[52:55], v[148:151], v[164:167], v[52:55]
	v_mfma_f32_16x16x32_bf16 v[48:51], v[156:159], v[164:167], v[48:51]
	v_mfma_f32_16x16x32_bf16 v[36:39], v[148:151], v[172:175], v[36:39]
	v_mfma_f32_16x16x32_bf16 v[32:35], v[156:159], v[172:175], v[32:35]
	s_setprio 2
	s_barrier
	v_mfma_f32_16x16x32_bf16 v[20:23], v[148:151], v[180:183], v[20:23]
	v_mfma_f32_16x16x32_bf16 v[16:19], v[156:159], v[180:183], v[16:19]
	v_mfma_f32_16x16x32_bf16 v[4:7], v[148:151], v[204:207], v[4:7]
	v_mfma_f32_16x16x32_bf16 v[0:3], v[156:159], v[204:207], v[0:3]
	s_setprio 0
	s_add_i32 s65, 0, 0x18000
	s_add_i32 s66, 0, 0x1c000
	v_add_u32_e32 v140, s65, v232
	v_add_u32_e32 v156, s66, v232
	ds_read_b128 v[120:123], v140
	ds_read_b128 v[124:127], v140 offset:1024
	ds_read_b128 v[136:139], v140 offset:2048
	ds_read_b128 v[140:143], v140 offset:3072
	ds_read_b128 v[144:147], v156
	ds_read_b128 v[148:151], v156 offset:1024
	ds_read_b128 v[152:155], v156 offset:2048
	ds_read_b128 v[156:159], v156 offset:3072
	s_add_u32 s26, s36, 0xb0000
	s_addc_u32 s27, s37, 0
	s_mov_b32 m0, s46
	v_lshl_add_u64 v[216:217], s[26:27], 0, v[184:185]
	ds_read_b128 v[160:163], v235 offset:32768
	ds_read_b128 v[164:167], v235 offset:33792
	ds_read_b128 v[168:171], v235 offset:34816
	ds_read_b128 v[172:175], v235 offset:35840
	ds_read_b128 v[176:179], v235 offset:36864
	ds_read_b128 v[180:183], v235 offset:37888
	ds_read_b128 v[200:203], v235 offset:38912
	ds_read_b128 v[204:207], v235 offset:39936
	global_load_lds_dwordx4 v[216:217], off
	s_mov_b32 m0, s47
	v_lshl_add_u64 v[216:217], s[26:27], 0, v[188:189]
	global_load_lds_dwordx4 v[216:217], off
	s_waitcnt vmcnt(8)
	s_waitcnt lgkmcnt(0)
	s_barrier
	s_setprio 1
	s_waitcnt lgkmcnt(0)
	v_mfma_f32_16x16x32_bf16 v[132:135], v[120:123], v[160:163], v[132:135]
	v_mfma_f32_16x16x32_bf16 v[128:131], v[136:139], v[160:163], v[128:131]
	v_mfma_f32_16x16x32_bf16 v[108:111], v[120:123], v[168:171], v[108:111]
	v_mfma_f32_16x16x32_bf16 v[104:107], v[136:139], v[168:171], v[104:107]
	v_mfma_f32_16x16x32_bf16 v[92:95], v[120:123], v[176:179], v[92:95]
	v_mfma_f32_16x16x32_bf16 v[88:91], v[136:139], v[176:179], v[88:91]
	v_mfma_f32_16x16x32_bf16 v[76:79], v[120:123], v[200:203], v[76:79]
	v_mfma_f32_16x16x32_bf16 v[72:75], v[136:139], v[200:203], v[72:75]
	v_mfma_f32_16x16x32_bf16 v[132:135], v[124:127], v[164:167], v[132:135]
	v_mfma_f32_16x16x32_bf16 v[128:131], v[140:143], v[164:167], v[128:131]
	v_mfma_f32_16x16x32_bf16 v[108:111], v[124:127], v[172:175], v[108:111]
	v_mfma_f32_16x16x32_bf16 v[104:107], v[140:143], v[172:175], v[104:107]
	v_mfma_f32_16x16x32_bf16 v[92:95], v[124:127], v[180:183], v[92:95]
	v_mfma_f32_16x16x32_bf16 v[88:91], v[140:143], v[180:183], v[88:91]
	v_mfma_f32_16x16x32_bf16 v[76:79], v[124:127], v[204:207], v[76:79]
	v_mfma_f32_16x16x32_bf16 v[72:75], v[140:143], v[204:207], v[72:75]
	s_setprio 0
	s_setprio 1
	v_mfma_f32_16x16x32_bf16 v[116:119], v[144:147], v[160:163], v[116:119]
	v_mfma_f32_16x16x32_bf16 v[112:115], v[152:155], v[160:163], v[112:115]
	v_mfma_f32_16x16x32_bf16 v[100:103], v[144:147], v[168:171], v[100:103]
	v_mfma_f32_16x16x32_bf16 v[96:99], v[152:155], v[168:171], v[96:99]
	v_mfma_f32_16x16x32_bf16 v[84:87], v[144:147], v[176:179], v[84:87]
	v_mfma_f32_16x16x32_bf16 v[80:83], v[152:155], v[176:179], v[80:83]
	v_mfma_f32_16x16x32_bf16 v[68:71], v[144:147], v[200:203], v[68:71]
	v_mfma_f32_16x16x32_bf16 v[64:67], v[152:155], v[200:203], v[64:67]
	v_mfma_f32_16x16x32_bf16 v[116:119], v[148:151], v[164:167], v[116:119]
	v_mfma_f32_16x16x32_bf16 v[112:115], v[156:159], v[164:167], v[112:115]
	v_mfma_f32_16x16x32_bf16 v[100:103], v[148:151], v[172:175], v[100:103]
	v_mfma_f32_16x16x32_bf16 v[96:99], v[156:159], v[172:175], v[96:99]
	s_setprio 2
	s_barrier
	v_mfma_f32_16x16x32_bf16 v[84:87], v[148:151], v[180:183], v[84:87]
	v_mfma_f32_16x16x32_bf16 v[80:83], v[156:159], v[180:183], v[80:83]
	v_mfma_f32_16x16x32_bf16 v[68:71], v[148:151], v[204:207], v[68:71]
	v_mfma_f32_16x16x32_bf16 v[64:67], v[156:159], v[204:207], v[64:67]
	s_setprio 2
	s_add_i32 s26, s65, s43
	v_lshl_add_u64 v[208:209], v[208:209], 0, s[20:21]
	s_mov_b32 m0, s26
	ds_read_b128 v[160:163], v235 offset:49152
	ds_read_b128 v[164:167], v235 offset:50176
	ds_read_b128 v[168:171], v235 offset:51200
	ds_read_b128 v[172:175], v235 offset:52224
	ds_read_b128 v[176:179], v235 offset:53248
	ds_read_b128 v[180:183], v235 offset:54272
	ds_read_b128 v[200:203], v235 offset:55296
	ds_read_b128 v[204:207], v235 offset:56320
	global_load_lds_dwordx4 v[208:209], off
	s_add_i32 m0, s26, 0x2000
	s_add_u32 s26, s30, 0xb0080
	v_lshl_add_u64 v[208:209], v[210:211], 0, s[20:21]
	s_addc_u32 s27, s31, 0
	s_add_i32 s30, s66, s43
	global_load_lds_dwordx4 v[208:209], off
	s_mov_b32 m0, s30
	v_lshl_add_u64 v[208:209], s[26:27], 0, v[186:187]
	global_load_lds_dwordx4 v[208:209], off
	s_add_i32 m0, s30, 0x2000
	v_lshl_add_u64 v[208:209], s[26:27], 0, v[190:191]
	global_load_lds_dwordx4 v[208:209], off
	s_mov_b32 m0, s49
	v_lshl_add_u64 v[208:209], v[212:213], 0, s[20:21]
	global_load_lds_dwordx4 v[208:209], off
	s_mov_b32 m0, s50
	v_lshl_add_u64 v[208:209], v[214:215], 0, s[20:21]
	global_load_lds_dwordx4 v[208:209], off
	s_waitcnt vmcnt(8)
	s_waitcnt lgkmcnt(0)
	s_barrier
	s_setprio 1
	s_waitcnt lgkmcnt(0)
	v_mfma_f32_16x16x32_bf16 v[60:63], v[120:123], v[160:163], v[60:63]
	v_mfma_f32_16x16x32_bf16 v[56:59], v[136:139], v[160:163], v[56:59]
	v_mfma_f32_16x16x32_bf16 v[44:47], v[120:123], v[168:171], v[44:47]
	v_mfma_f32_16x16x32_bf16 v[40:43], v[136:139], v[168:171], v[40:43]
	v_mfma_f32_16x16x32_bf16 v[28:31], v[120:123], v[176:179], v[28:31]
	v_mfma_f32_16x16x32_bf16 v[24:27], v[136:139], v[176:179], v[24:27]
	v_mfma_f32_16x16x32_bf16 v[12:15], v[120:123], v[200:203], v[12:15]
	v_mfma_f32_16x16x32_bf16 v[8:11], v[136:139], v[200:203], v[8:11]
	v_mfma_f32_16x16x32_bf16 v[60:63], v[124:127], v[164:167], v[60:63]
	v_mfma_f32_16x16x32_bf16 v[56:59], v[140:143], v[164:167], v[56:59]
	v_mfma_f32_16x16x32_bf16 v[44:47], v[124:127], v[172:175], v[44:47]
	v_mfma_f32_16x16x32_bf16 v[40:43], v[140:143], v[172:175], v[40:43]
	v_mfma_f32_16x16x32_bf16 v[28:31], v[124:127], v[180:183], v[28:31]
	v_mfma_f32_16x16x32_bf16 v[24:27], v[140:143], v[180:183], v[24:27]
	v_mfma_f32_16x16x32_bf16 v[12:15], v[124:127], v[204:207], v[12:15]
	v_mfma_f32_16x16x32_bf16 v[8:11], v[140:143], v[204:207], v[8:11]
	s_setprio 0
	s_setprio 1
	v_mfma_f32_16x16x32_bf16 v[52:55], v[144:147], v[160:163], v[52:55]
	v_mfma_f32_16x16x32_bf16 v[48:51], v[152:155], v[160:163], v[48:51]
	v_mfma_f32_16x16x32_bf16 v[36:39], v[144:147], v[168:171], v[36:39]
	v_mfma_f32_16x16x32_bf16 v[32:35], v[152:155], v[168:171], v[32:35]
	v_mfma_f32_16x16x32_bf16 v[20:23], v[144:147], v[176:179], v[20:23]
	v_mfma_f32_16x16x32_bf16 v[16:19], v[152:155], v[176:179], v[16:19]
	v_mfma_f32_16x16x32_bf16 v[4:7], v[144:147], v[200:203], v[4:7]
	v_mfma_f32_16x16x32_bf16 v[0:3], v[152:155], v[200:203], v[0:3]
	v_mfma_f32_16x16x32_bf16 v[52:55], v[148:151], v[164:167], v[52:55]
	v_mfma_f32_16x16x32_bf16 v[48:51], v[156:159], v[164:167], v[48:51]
	v_mfma_f32_16x16x32_bf16 v[36:39], v[148:151], v[172:175], v[36:39]
	v_mfma_f32_16x16x32_bf16 v[32:35], v[156:159], v[172:175], v[32:35]
	s_setprio 2
	s_barrier
	v_mfma_f32_16x16x32_bf16 v[20:23], v[148:151], v[180:183], v[20:23]
	v_mfma_f32_16x16x32_bf16 v[16:19], v[156:159], v[180:183], v[16:19]
	v_mfma_f32_16x16x32_bf16 v[4:7], v[148:151], v[204:207], v[4:7]
	v_mfma_f32_16x16x32_bf16 v[0:3], v[156:159], v[204:207], v[0:3]
	s_setprio 0
	s_add_i32 s64, s64, 2
	s_add_u32 s62, s62, 0x100
	s_addc_u32 s63, s63, 0
	s_cmp_gt_u32 s64, 41
	s_mov_b64 s[26:27], s[28:29]
.LBB0_866:
	ds_read_b128 v[120:123], v233
	ds_read_b128 v[124:127], v233 offset:1024
	ds_read_b128 v[136:139], v233 offset:2048
	ds_read_b128 v[140:143], v233 offset:3072
	ds_read_b128 v[144:147], v234
	ds_read_b128 v[148:151], v234 offset:1024
	ds_read_b128 v[152:155], v234 offset:2048
	ds_read_b128 v[156:159], v234 offset:3072
	s_add_u32 s28, s26, 0x100
	s_addc_u32 s29, s27, 0
	s_cmp_eq_u32 s64, 40
	s_cselect_b32 s37, s7, s29
	s_cselect_b32 s36, s6, s28
	s_cselect_b32 s31, s25, s63
	s_cselect_b32 s30, s24, s62
	v_lshl_add_u64 v[208:209], s[26:27], 0, v[192:193]
	s_add_i32 m0, s44, 0xc000
	ds_read_b128 v[160:163], v235
	ds_read_b128 v[164:167], v235 offset:1024
	ds_read_b128 v[168:171], v235 offset:2048
	ds_read_b128 v[172:175], v235 offset:3072
	ds_read_b128 v[176:179], v235 offset:4096
	ds_read_b128 v[180:183], v235 offset:5120
	ds_read_b128 v[200:203], v235 offset:6144
	ds_read_b128 v[204:207], v235 offset:7168
	global_load_lds_dwordx4 v[208:209], off
	s_add_i32 m0, s44, 0xe000
	v_lshl_add_u64 v[208:209], s[26:27], 0, v[194:195]
	global_load_lds_dwordx4 v[208:209], off
	s_waitcnt vmcnt(8)
	s_waitcnt lgkmcnt(0)
	s_barrier
	s_setprio 1
	s_waitcnt lgkmcnt(0)
	v_mfma_f32_16x16x32_bf16 v[132:135], v[120:123], v[160:163], v[132:135]
	v_mfma_f32_16x16x32_bf16 v[128:131], v[136:139], v[160:163], v[128:131]
	v_mfma_f32_16x16x32_bf16 v[108:111], v[120:123], v[168:171], v[108:111]
	v_mfma_f32_16x16x32_bf16 v[104:107], v[136:139], v[168:171], v[104:107]
	v_mfma_f32_16x16x32_bf16 v[92:95], v[120:123], v[176:179], v[92:95]
	v_mfma_f32_16x16x32_bf16 v[88:91], v[136:139], v[176:179], v[88:91]
	v_mfma_f32_16x16x32_bf16 v[76:79], v[120:123], v[200:203], v[76:79]
	v_mfma_f32_16x16x32_bf16 v[72:75], v[136:139], v[200:203], v[72:75]
	v_mfma_f32_16x16x32_bf16 v[132:135], v[124:127], v[164:167], v[132:135]
	v_mfma_f32_16x16x32_bf16 v[128:131], v[140:143], v[164:167], v[128:131]
	v_mfma_f32_16x16x32_bf16 v[108:111], v[124:127], v[172:175], v[108:111]
	v_mfma_f32_16x16x32_bf16 v[104:107], v[140:143], v[172:175], v[104:107]
	v_mfma_f32_16x16x32_bf16 v[92:95], v[124:127], v[180:183], v[92:95]
	v_mfma_f32_16x16x32_bf16 v[88:91], v[140:143], v[180:183], v[88:91]
	v_mfma_f32_16x16x32_bf16 v[76:79], v[124:127], v[204:207], v[76:79]
	v_mfma_f32_16x16x32_bf16 v[72:75], v[140:143], v[204:207], v[72:75]
	s_setprio 0
	s_setprio 1
	v_mfma_f32_16x16x32_bf16 v[116:119], v[144:147], v[160:163], v[116:119]
	v_mfma_f32_16x16x32_bf16 v[112:115], v[152:155], v[160:163], v[112:115]
	v_mfma_f32_16x16x32_bf16 v[100:103], v[144:147], v[168:171], v[100:103]
	v_mfma_f32_16x16x32_bf16 v[96:99], v[152:155], v[168:171], v[96:99]
	v_mfma_f32_16x16x32_bf16 v[84:87], v[144:147], v[176:179], v[84:87]
	v_mfma_f32_16x16x32_bf16 v[80:83], v[152:155], v[176:179], v[80:83]
	v_mfma_f32_16x16x32_bf16 v[68:71], v[144:147], v[200:203], v[68:71]
	v_mfma_f32_16x16x32_bf16 v[64:67], v[152:155], v[200:203], v[64:67]
	v_mfma_f32_16x16x32_bf16 v[116:119], v[148:151], v[164:167], v[116:119]
	v_mfma_f32_16x16x32_bf16 v[112:115], v[156:159], v[164:167], v[112:115]
	v_mfma_f32_16x16x32_bf16 v[100:103], v[148:151], v[172:175], v[100:103]
	v_mfma_f32_16x16x32_bf16 v[96:99], v[156:159], v[172:175], v[96:99]
	s_setprio 2
	s_barrier
	v_mfma_f32_16x16x32_bf16 v[84:87], v[148:151], v[180:183], v[84:87]
	v_mfma_f32_16x16x32_bf16 v[80:83], v[156:159], v[180:183], v[80:83]
	v_mfma_f32_16x16x32_bf16 v[68:71], v[148:151], v[204:207], v[68:71]
	v_mfma_f32_16x16x32_bf16 v[64:67], v[156:159], v[204:207], v[64:67]
	s_setprio 2
	s_add_i32 s26, s56, s43
	v_lshl_add_u64 v[208:209], s[30:31], 0, v[186:187]
	s_mov_b32 m0, s26
	ds_read_b128 v[160:163], v235 offset:16384
	ds_read_b128 v[164:167], v235 offset:17408
	ds_read_b128 v[168:171], v235 offset:18432
	ds_read_b128 v[172:175], v235 offset:19456
	ds_read_b128 v[176:179], v235 offset:20480
	ds_read_b128 v[180:183], v235 offset:21504
	ds_read_b128 v[200:203], v235 offset:22528
	ds_read_b128 v[204:207], v235 offset:23552
	global_load_lds_dwordx4 v[208:209], off
	s_add_i32 m0, s26, 0x2000
	s_add_u32 s26, s30, 0xb0000
	v_lshl_add_u64 v[210:211], s[30:31], 0, v[190:191]
	s_addc_u32 s27, s31, 0
	s_add_i32 s65, s57, s43
	global_load_lds_dwordx4 v[210:211], off
	v_lshl_add_u64 v[212:213], s[26:27], 0, v[186:187]
	s_mov_b32 m0, s65
	v_lshl_add_u64 v[214:215], s[36:37], 0, v[188:189]
	global_load_lds_dwordx4 v[212:213], off
	s_add_i32 m0, s65, 0x2000
	v_lshl_add_u64 v[212:213], s[26:27], 0, v[190:191]
	global_load_lds_dwordx4 v[212:213], off
	s_mov_b32 m0, s44
	v_lshl_add_u64 v[212:213], s[36:37], 0, v[184:185]
	global_load_lds_dwordx4 v[212:213], off
	s_mov_b32 m0, s45
	s_nop 0
	global_load_lds_dwordx4 v[214:215], off
	s_waitcnt vmcnt(8)
	s_waitcnt lgkmcnt(0)
	s_barrier
	s_setprio 1
	s_waitcnt lgkmcnt(0)
	v_mfma_f32_16x16x32_bf16 v[60:63], v[120:123], v[160:163], v[60:63]
	v_mfma_f32_16x16x32_bf16 v[56:59], v[136:139], v[160:163], v[56:59]
	v_mfma_f32_16x16x32_bf16 v[44:47], v[120:123], v[168:171], v[44:47]
	v_mfma_f32_16x16x32_bf16 v[40:43], v[136:139], v[168:171], v[40:43]
	v_mfma_f32_16x16x32_bf16 v[28:31], v[120:123], v[176:179], v[28:31]
	v_mfma_f32_16x16x32_bf16 v[24:27], v[136:139], v[176:179], v[24:27]
	v_mfma_f32_16x16x32_bf16 v[12:15], v[120:123], v[200:203], v[12:15]
	v_mfma_f32_16x16x32_bf16 v[8:11], v[136:139], v[200:203], v[8:11]
	v_mfma_f32_16x16x32_bf16 v[60:63], v[124:127], v[164:167], v[60:63]
	v_mfma_f32_16x16x32_bf16 v[56:59], v[140:143], v[164:167], v[56:59]
	v_mfma_f32_16x16x32_bf16 v[44:47], v[124:127], v[172:175], v[44:47]
	v_mfma_f32_16x16x32_bf16 v[40:43], v[140:143], v[172:175], v[40:43]
	v_mfma_f32_16x16x32_bf16 v[28:31], v[124:127], v[180:183], v[28:31]
	v_mfma_f32_16x16x32_bf16 v[24:27], v[140:143], v[180:183], v[24:27]
	v_mfma_f32_16x16x32_bf16 v[12:15], v[124:127], v[204:207], v[12:15]
	v_mfma_f32_16x16x32_bf16 v[8:11], v[140:143], v[204:207], v[8:11]
	s_setprio 0
	s_setprio 1
	v_mfma_f32_16x16x32_bf16 v[52:55], v[144:147], v[160:163], v[52:55]
	v_mfma_f32_16x16x32_bf16 v[48:51], v[152:155], v[160:163], v[48:51]
	v_mfma_f32_16x16x32_bf16 v[36:39], v[144:147], v[168:171], v[36:39]
	v_mfma_f32_16x16x32_bf16 v[32:35], v[152:155], v[168:171], v[32:35]
	v_mfma_f32_16x16x32_bf16 v[20:23], v[144:147], v[176:179], v[20:23]
	v_mfma_f32_16x16x32_bf16 v[16:19], v[152:155], v[176:179], v[16:19]
	v_mfma_f32_16x16x32_bf16 v[4:7], v[144:147], v[200:203], v[4:7]
	v_mfma_f32_16x16x32_bf16 v[0:3], v[152:155], v[200:203], v[0:3]
	v_mfma_f32_16x16x32_bf16 v[52:55], v[148:151], v[164:167], v[52:55]
	v_mfma_f32_16x16x32_bf16 v[48:51], v[156:159], v[164:167], v[48:51]
	v_mfma_f32_16x16x32_bf16 v[36:39], v[148:151], v[172:175], v[36:39]
	v_mfma_f32_16x16x32_bf16 v[32:35], v[156:159], v[172:175], v[32:35]
	s_setprio 2
	s_barrier
	v_mfma_f32_16x16x32_bf16 v[20:23], v[148:151], v[180:183], v[20:23]
	v_mfma_f32_16x16x32_bf16 v[16:19], v[156:159], v[180:183], v[16:19]
	v_mfma_f32_16x16x32_bf16 v[4:7], v[148:151], v[204:207], v[4:7]
	v_mfma_f32_16x16x32_bf16 v[0:3], v[156:159], v[204:207], v[0:3]
	s_setprio 0
	s_add_i32 s65, 0, 0x18000
	s_add_i32 s66, 0, 0x1c000
	v_add_u32_e32 v140, s65, v232
	v_add_u32_e32 v156, s66, v232
	ds_read_b128 v[120:123], v140
	ds_read_b128 v[124:127], v140 offset:1024
	ds_read_b128 v[136:139], v140 offset:2048
	ds_read_b128 v[140:143], v140 offset:3072
	ds_read_b128 v[144:147], v156
	ds_read_b128 v[148:151], v156 offset:1024
	ds_read_b128 v[152:155], v156 offset:2048
	ds_read_b128 v[156:159], v156 offset:3072
	s_add_u32 s26, s36, 0xb0000
	s_addc_u32 s27, s37, 0
	s_mov_b32 m0, s46
	v_lshl_add_u64 v[216:217], s[26:27], 0, v[184:185]
	ds_read_b128 v[160:163], v235 offset:32768
	ds_read_b128 v[164:167], v235 offset:33792
	ds_read_b128 v[168:171], v235 offset:34816
	ds_read_b128 v[172:175], v235 offset:35840
	ds_read_b128 v[176:179], v235 offset:36864
	ds_read_b128 v[180:183], v235 offset:37888
	ds_read_b128 v[200:203], v235 offset:38912
	ds_read_b128 v[204:207], v235 offset:39936
	global_load_lds_dwordx4 v[216:217], off
	s_mov_b32 m0, s47
	v_lshl_add_u64 v[216:217], s[26:27], 0, v[188:189]
	global_load_lds_dwordx4 v[216:217], off
	s_waitcnt vmcnt(8)
	s_waitcnt lgkmcnt(0)
	s_barrier
	s_setprio 1
	s_waitcnt lgkmcnt(0)
	v_mfma_f32_16x16x32_bf16 v[132:135], v[120:123], v[160:163], v[132:135]
	v_mfma_f32_16x16x32_bf16 v[128:131], v[136:139], v[160:163], v[128:131]
	v_mfma_f32_16x16x32_bf16 v[108:111], v[120:123], v[168:171], v[108:111]
	v_mfma_f32_16x16x32_bf16 v[104:107], v[136:139], v[168:171], v[104:107]
	v_mfma_f32_16x16x32_bf16 v[92:95], v[120:123], v[176:179], v[92:95]
	v_mfma_f32_16x16x32_bf16 v[88:91], v[136:139], v[176:179], v[88:91]
	v_mfma_f32_16x16x32_bf16 v[76:79], v[120:123], v[200:203], v[76:79]
	v_mfma_f32_16x16x32_bf16 v[72:75], v[136:139], v[200:203], v[72:75]
	v_mfma_f32_16x16x32_bf16 v[132:135], v[124:127], v[164:167], v[132:135]
	v_mfma_f32_16x16x32_bf16 v[128:131], v[140:143], v[164:167], v[128:131]
	v_mfma_f32_16x16x32_bf16 v[108:111], v[124:127], v[172:175], v[108:111]
	v_mfma_f32_16x16x32_bf16 v[104:107], v[140:143], v[172:175], v[104:107]
	v_mfma_f32_16x16x32_bf16 v[92:95], v[124:127], v[180:183], v[92:95]
	v_mfma_f32_16x16x32_bf16 v[88:91], v[140:143], v[180:183], v[88:91]
	v_mfma_f32_16x16x32_bf16 v[76:79], v[124:127], v[204:207], v[76:79]
	v_mfma_f32_16x16x32_bf16 v[72:75], v[140:143], v[204:207], v[72:75]
	s_setprio 0
	s_setprio 1
	v_mfma_f32_16x16x32_bf16 v[116:119], v[144:147], v[160:163], v[116:119]
	v_mfma_f32_16x16x32_bf16 v[112:115], v[152:155], v[160:163], v[112:115]
	v_mfma_f32_16x16x32_bf16 v[100:103], v[144:147], v[168:171], v[100:103]
	v_mfma_f32_16x16x32_bf16 v[96:99], v[152:155], v[168:171], v[96:99]
	v_mfma_f32_16x16x32_bf16 v[84:87], v[144:147], v[176:179], v[84:87]
	v_mfma_f32_16x16x32_bf16 v[80:83], v[152:155], v[176:179], v[80:83]
	v_mfma_f32_16x16x32_bf16 v[68:71], v[144:147], v[200:203], v[68:71]
	v_mfma_f32_16x16x32_bf16 v[64:67], v[152:155], v[200:203], v[64:67]
	v_mfma_f32_16x16x32_bf16 v[116:119], v[148:151], v[164:167], v[116:119]
	v_mfma_f32_16x16x32_bf16 v[112:115], v[156:159], v[164:167], v[112:115]
	v_mfma_f32_16x16x32_bf16 v[100:103], v[148:151], v[172:175], v[100:103]
	v_mfma_f32_16x16x32_bf16 v[96:99], v[156:159], v[172:175], v[96:99]
	s_setprio 2
	s_barrier
	v_mfma_f32_16x16x32_bf16 v[84:87], v[148:151], v[180:183], v[84:87]
	v_mfma_f32_16x16x32_bf16 v[80:83], v[156:159], v[180:183], v[80:83]
	v_mfma_f32_16x16x32_bf16 v[68:71], v[148:151], v[204:207], v[68:71]
	v_mfma_f32_16x16x32_bf16 v[64:67], v[156:159], v[204:207], v[64:67]
	s_setprio 2
	s_add_i32 s26, s65, s43
	v_lshl_add_u64 v[208:209], v[208:209], 0, s[20:21]
	s_mov_b32 m0, s26
	ds_read_b128 v[160:163], v235 offset:49152
	ds_read_b128 v[164:167], v235 offset:50176
	ds_read_b128 v[168:171], v235 offset:51200
	ds_read_b128 v[172:175], v235 offset:52224
	ds_read_b128 v[176:179], v235 offset:53248
	ds_read_b128 v[180:183], v235 offset:54272
	ds_read_b128 v[200:203], v235 offset:55296
	ds_read_b128 v[204:207], v235 offset:56320
	global_load_lds_dwordx4 v[208:209], off
	s_add_i32 m0, s26, 0x2000
	s_add_u32 s26, s30, 0xb0080
	v_lshl_add_u64 v[208:209], v[210:211], 0, s[20:21]
	s_addc_u32 s27, s31, 0
	s_add_i32 s30, s66, s43
	global_load_lds_dwordx4 v[208:209], off
	s_mov_b32 m0, s30
	v_lshl_add_u64 v[208:209], s[26:27], 0, v[186:187]
	global_load_lds_dwordx4 v[208:209], off
	s_add_i32 m0, s30, 0x2000
	v_lshl_add_u64 v[208:209], s[26:27], 0, v[190:191]
	global_load_lds_dwordx4 v[208:209], off
	s_mov_b32 m0, s49
	v_lshl_add_u64 v[208:209], v[212:213], 0, s[20:21]
	global_load_lds_dwordx4 v[208:209], off
	s_mov_b32 m0, s50
	v_lshl_add_u64 v[208:209], v[214:215], 0, s[20:21]
	global_load_lds_dwordx4 v[208:209], off
	s_waitcnt vmcnt(8)
	s_waitcnt lgkmcnt(0)
	s_barrier
	s_setprio 1
	s_waitcnt lgkmcnt(0)
	v_mfma_f32_16x16x32_bf16 v[60:63], v[120:123], v[160:163], v[60:63]
	v_mfma_f32_16x16x32_bf16 v[56:59], v[136:139], v[160:163], v[56:59]
	v_mfma_f32_16x16x32_bf16 v[44:47], v[120:123], v[168:171], v[44:47]
	v_mfma_f32_16x16x32_bf16 v[40:43], v[136:139], v[168:171], v[40:43]
	v_mfma_f32_16x16x32_bf16 v[28:31], v[120:123], v[176:179], v[28:31]
	v_mfma_f32_16x16x32_bf16 v[24:27], v[136:139], v[176:179], v[24:27]
	v_mfma_f32_16x16x32_bf16 v[12:15], v[120:123], v[200:203], v[12:15]
	v_mfma_f32_16x16x32_bf16 v[8:11], v[136:139], v[200:203], v[8:11]
	v_mfma_f32_16x16x32_bf16 v[60:63], v[124:127], v[164:167], v[60:63]
	v_mfma_f32_16x16x32_bf16 v[56:59], v[140:143], v[164:167], v[56:59]
	v_mfma_f32_16x16x32_bf16 v[44:47], v[124:127], v[172:175], v[44:47]
	v_mfma_f32_16x16x32_bf16 v[40:43], v[140:143], v[172:175], v[40:43]
	v_mfma_f32_16x16x32_bf16 v[28:31], v[124:127], v[180:183], v[28:31]
	v_mfma_f32_16x16x32_bf16 v[24:27], v[140:143], v[180:183], v[24:27]
	v_mfma_f32_16x16x32_bf16 v[12:15], v[124:127], v[204:207], v[12:15]
	v_mfma_f32_16x16x32_bf16 v[8:11], v[140:143], v[204:207], v[8:11]
	s_setprio 0
	s_setprio 1
	v_mfma_f32_16x16x32_bf16 v[52:55], v[144:147], v[160:163], v[52:55]
	v_mfma_f32_16x16x32_bf16 v[48:51], v[152:155], v[160:163], v[48:51]
	v_mfma_f32_16x16x32_bf16 v[36:39], v[144:147], v[168:171], v[36:39]
	v_mfma_f32_16x16x32_bf16 v[32:35], v[152:155], v[168:171], v[32:35]
	v_mfma_f32_16x16x32_bf16 v[20:23], v[144:147], v[176:179], v[20:23]
	v_mfma_f32_16x16x32_bf16 v[16:19], v[152:155], v[176:179], v[16:19]
	v_mfma_f32_16x16x32_bf16 v[4:7], v[144:147], v[200:203], v[4:7]
	v_mfma_f32_16x16x32_bf16 v[0:3], v[152:155], v[200:203], v[0:3]
	v_mfma_f32_16x16x32_bf16 v[52:55], v[148:151], v[164:167], v[52:55]
	v_mfma_f32_16x16x32_bf16 v[48:51], v[156:159], v[164:167], v[48:51]
	v_mfma_f32_16x16x32_bf16 v[36:39], v[148:151], v[172:175], v[36:39]
	v_mfma_f32_16x16x32_bf16 v[32:35], v[156:159], v[172:175], v[32:35]
	s_setprio 2
	s_barrier
	v_mfma_f32_16x16x32_bf16 v[20:23], v[148:151], v[180:183], v[20:23]
	v_mfma_f32_16x16x32_bf16 v[16:19], v[156:159], v[180:183], v[16:19]
	v_mfma_f32_16x16x32_bf16 v[4:7], v[148:151], v[204:207], v[4:7]
	v_mfma_f32_16x16x32_bf16 v[0:3], v[156:159], v[204:207], v[0:3]
	s_setprio 0
	s_add_i32 s64, s64, 2
	s_add_u32 s62, s62, 0x100
	s_addc_u32 s63, s63, 0
	s_cmp_gt_u32 s64, 41
	s_mov_b64 s[26:27], s[28:29]
	s_cbranch_scc0 .LBB0_866

.LBB0_951:
	s_ashr_i32 s27, s26, 31
	s_lshl_b64 s[30:31], s[26:27], 19
	s_add_u32 s30, s47, s30
	s_addc_u32 s31, s48, s31
	s_and_b64 s[36:37], s[4:5], exec
	s_cselect_b32 s27, s31, s7
	s_cselect_b32 s39, s30, s6
	s_ashr_i32 s29, s28, 31
	s_lshl_b64 s[36:37], s[28:29], 19
	s_add_u32 s36, s49, s36
	s_addc_u32 s37, s50, s37
	s_and_b64 s[44:45], s[4:5], exec
	s_cselect_b32 s29, s37, s41
	s_cselect_b32 s43, s36, s40
	s_add_u32 s6, s6, 0x40080
	s_addc_u32 s7, s7, 0
	s_add_u32 s71, s40, 0x100
	s_addc_u32 s72, s41, 0
	s_mov_b32 s73, -2
	ds_read_b128 v[144:147], v179
	ds_read_b128 v[148:151], v179 offset:1024
	ds_read_b128 v[152:155], v179 offset:2048
	ds_read_b128 v[156:159], v179 offset:3072
	ds_read_b128 v[160:163], v180
	ds_read_b128 v[164:167], v180 offset:1024
	ds_read_b128 v[168:171], v180 offset:2048
	ds_read_b128 v[172:175], v180 offset:3072
	s_add_u32 s40, s6, 0xfffc0080
	s_addc_u32 s41, s7, -1
	s_cmp_eq_u32 s73, 12
	s_cselect_b32 s45, s27, s41
	s_cselect_b32 s44, s39, s40
	s_cselect_b32 s41, s29, s72
	s_cselect_b32 s40, s43, s71
	v_lshl_add_u64 v[176:177], s[6:7], 0, v[136:137]
	s_add_i32 m0, s54, 0xc000
	ds_read_b128 v[184:187], v181
	ds_read_b128 v[188:191], v181 offset:1024
	ds_read_b128 v[192:195], v181 offset:2048
	ds_read_b128 v[196:199], v181 offset:3072
	ds_read_b128 v[200:203], v181 offset:4096
	ds_read_b128 v[204:207], v181 offset:5120
	ds_read_b128 v[208:211], v181 offset:6144
	ds_read_b128 v[212:215], v181 offset:7168
	global_load_lds_dwordx4 v[176:177], off
	s_add_i32 m0, s54, 0xe000
	v_lshl_add_u64 v[176:177], s[6:7], 0, v[138:139]
	global_load_lds_dwordx4 v[176:177], off
	s_waitcnt vmcnt(8)
	s_waitcnt lgkmcnt(0)
	s_barrier
	s_setprio 1
	s_waitcnt lgkmcnt(0)
	v_mfma_f32_16x16x32_bf16 v[124:127], v[144:147], v[184:187], 0
	v_mfma_f32_16x16x32_bf16 v[120:123], v[152:155], v[184:187], 0
	v_mfma_f32_16x16x32_bf16 v[108:111], v[144:147], v[192:195], 0
	v_mfma_f32_16x16x32_bf16 v[104:107], v[152:155], v[192:195], 0
	v_mfma_f32_16x16x32_bf16 v[92:95], v[144:147], v[200:203], 0
	v_mfma_f32_16x16x32_bf16 v[88:91], v[152:155], v[200:203], 0
	v_mfma_f32_16x16x32_bf16 v[76:79], v[144:147], v[208:211], 0
	v_mfma_f32_16x16x32_bf16 v[72:75], v[152:155], v[208:211], 0
	v_mfma_f32_16x16x32_bf16 v[124:127], v[148:151], v[188:191], v[124:127]
	v_mfma_f32_16x16x32_bf16 v[120:123], v[156:159], v[188:191], v[120:123]
	v_mfma_f32_16x16x32_bf16 v[108:111], v[148:151], v[196:199], v[108:111]
	v_mfma_f32_16x16x32_bf16 v[104:107], v[156:159], v[196:199], v[104:107]
	v_mfma_f32_16x16x32_bf16 v[92:95], v[148:151], v[204:207], v[92:95]
	v_mfma_f32_16x16x32_bf16 v[88:91], v[156:159], v[204:207], v[88:91]
	v_mfma_f32_16x16x32_bf16 v[76:79], v[148:151], v[212:215], v[76:79]
	v_mfma_f32_16x16x32_bf16 v[72:75], v[156:159], v[212:215], v[72:75]
	s_setprio 0
	s_setprio 1
	v_mfma_f32_16x16x32_bf16 v[116:119], v[160:163], v[184:187], 0
	v_mfma_f32_16x16x32_bf16 v[112:115], v[168:171], v[184:187], 0
	v_mfma_f32_16x16x32_bf16 v[100:103], v[160:163], v[192:195], 0
	v_mfma_f32_16x16x32_bf16 v[96:99], v[168:171], v[192:195], 0
	v_mfma_f32_16x16x32_bf16 v[84:87], v[160:163], v[200:203], 0
	v_mfma_f32_16x16x32_bf16 v[80:83], v[168:171], v[200:203], 0
	v_mfma_f32_16x16x32_bf16 v[68:71], v[160:163], v[208:211], 0
	v_mfma_f32_16x16x32_bf16 v[64:67], v[168:171], v[208:211], 0
	v_mfma_f32_16x16x32_bf16 v[116:119], v[164:167], v[188:191], v[116:119]
	v_mfma_f32_16x16x32_bf16 v[112:115], v[172:175], v[188:191], v[112:115]
	v_mfma_f32_16x16x32_bf16 v[100:103], v[164:167], v[196:199], v[100:103]
	v_mfma_f32_16x16x32_bf16 v[96:99], v[172:175], v[196:199], v[96:99]
	s_setprio 2
	s_barrier
	v_mfma_f32_16x16x32_bf16 v[84:87], v[164:167], v[204:207], v[84:87]
	v_mfma_f32_16x16x32_bf16 v[80:83], v[172:175], v[204:207], v[80:83]
	v_mfma_f32_16x16x32_bf16 v[68:71], v[164:167], v[212:215], v[68:71]
	v_mfma_f32_16x16x32_bf16 v[64:67], v[172:175], v[212:215], v[64:67]
	s_setprio 2
	s_add_i32 s74, s69, s51
	v_lshl_add_u64 v[176:177], s[40:41], 0, v[130:131]
	s_mov_b32 m0, s74
	ds_read_b128 v[184:187], v181 offset:16384
	ds_read_b128 v[188:191], v181 offset:17408
	ds_read_b128 v[192:195], v181 offset:18432
	ds_read_b128 v[196:199], v181 offset:19456
	ds_read_b128 v[200:203], v181 offset:20480
	ds_read_b128 v[204:207], v181 offset:21504
	ds_read_b128 v[208:211], v181 offset:22528
	ds_read_b128 v[212:215], v181 offset:23552
	global_load_lds_dwordx4 v[176:177], off
	s_add_i32 m0, s74, 0x2000
	s_add_u32 s74, s40, 0x40000
	v_lshl_add_u64 v[216:217], s[40:41], 0, v[134:135]
	s_addc_u32 s75, s41, 0
	s_add_i32 s76, s70, s51
	global_load_lds_dwordx4 v[216:217], off
	v_lshl_add_u64 v[218:219], s[74:75], 0, v[130:131]
	s_mov_b32 m0, s76
	v_lshl_add_u64 v[220:221], s[44:45], 0, v[132:133]
	global_load_lds_dwordx4 v[218:219], off
	s_add_i32 m0, s76, 0x2000
	v_lshl_add_u64 v[218:219], s[74:75], 0, v[134:135]
	global_load_lds_dwordx4 v[218:219], off
	s_mov_b32 m0, s54
	v_lshl_add_u64 v[218:219], s[44:45], 0, v[128:129]
	global_load_lds_dwordx4 v[218:219], off
	s_mov_b32 m0, s55
	s_nop 0
	global_load_lds_dwordx4 v[220:221], off
	s_waitcnt vmcnt(8)
	s_waitcnt lgkmcnt(0)
	s_barrier
	s_setprio 1
	s_waitcnt lgkmcnt(0)
	v_mfma_f32_16x16x32_bf16 v[60:63], v[144:147], v[184:187], 0
	v_mfma_f32_16x16x32_bf16 v[56:59], v[152:155], v[184:187], 0
	v_mfma_f32_16x16x32_bf16 v[44:47], v[144:147], v[192:195], 0
	v_mfma_f32_16x16x32_bf16 v[40:43], v[152:155], v[192:195], 0
	v_mfma_f32_16x16x32_bf16 v[28:31], v[144:147], v[200:203], 0
	v_mfma_f32_16x16x32_bf16 v[24:27], v[152:155], v[200:203], 0
	v_mfma_f32_16x16x32_bf16 v[12:15], v[144:147], v[208:211], 0
	v_mfma_f32_16x16x32_bf16 v[8:11], v[152:155], v[208:211], 0
	v_mfma_f32_16x16x32_bf16 v[60:63], v[148:151], v[188:191], v[60:63]
	v_mfma_f32_16x16x32_bf16 v[56:59], v[156:159], v[188:191], v[56:59]
	v_mfma_f32_16x16x32_bf16 v[44:47], v[148:151], v[196:199], v[44:47]
	v_mfma_f32_16x16x32_bf16 v[40:43], v[156:159], v[196:199], v[40:43]
	v_mfma_f32_16x16x32_bf16 v[28:31], v[148:151], v[204:207], v[28:31]
	v_mfma_f32_16x16x32_bf16 v[24:27], v[156:159], v[204:207], v[24:27]
	v_mfma_f32_16x16x32_bf16 v[12:15], v[148:151], v[212:215], v[12:15]
	v_mfma_f32_16x16x32_bf16 v[8:11], v[156:159], v[212:215], v[8:11]
	s_setprio 0
	s_setprio 1
	v_mfma_f32_16x16x32_bf16 v[52:55], v[160:163], v[184:187], 0
	v_mfma_f32_16x16x32_bf16 v[48:51], v[168:171], v[184:187], 0
	v_mfma_f32_16x16x32_bf16 v[36:39], v[160:163], v[192:195], 0
	v_mfma_f32_16x16x32_bf16 v[32:35], v[168:171], v[192:195], 0
	v_mfma_f32_16x16x32_bf16 v[20:23], v[160:163], v[200:203], 0
	v_mfma_f32_16x16x32_bf16 v[16:19], v[168:171], v[200:203], 0
	v_mfma_f32_16x16x32_bf16 v[4:7], v[160:163], v[208:211], 0
	v_mfma_f32_16x16x32_bf16 v[0:3], v[168:171], v[208:211], 0
	v_mfma_f32_16x16x32_bf16 v[52:55], v[164:167], v[188:191], v[52:55]
	v_mfma_f32_16x16x32_bf16 v[48:51], v[172:175], v[188:191], v[48:51]
	v_mfma_f32_16x16x32_bf16 v[36:39], v[164:167], v[196:199], v[36:39]
	v_mfma_f32_16x16x32_bf16 v[32:35], v[172:175], v[196:199], v[32:35]
	s_setprio 2
	s_barrier
	v_mfma_f32_16x16x32_bf16 v[20:23], v[164:167], v[204:207], v[20:23]
	v_mfma_f32_16x16x32_bf16 v[16:19], v[172:175], v[204:207], v[16:19]
	v_mfma_f32_16x16x32_bf16 v[4:7], v[164:167], v[212:215], v[4:7]
	v_mfma_f32_16x16x32_bf16 v[0:3], v[172:175], v[212:215], v[0:3]
	s_setprio 0
	s_add_i32 s74, 0, 0x18000
	s_add_i32 s75, 0, 0x1c000
	v_add_u32_e32 v156, s74, v178
	v_add_u32_e32 v172, s75, v178
	ds_read_b128 v[144:147], v156
	ds_read_b128 v[148:151], v156 offset:1024
	ds_read_b128 v[152:155], v156 offset:2048
	ds_read_b128 v[156:159], v156 offset:3072
	ds_read_b128 v[160:163], v172
	ds_read_b128 v[164:167], v172 offset:1024
	ds_read_b128 v[168:171], v172 offset:2048
	ds_read_b128 v[172:175], v172 offset:3072
	s_add_u32 s44, s44, 0x40000
	s_addc_u32 s45, s45, 0
	s_mov_b32 m0, s56
	v_lshl_add_u64 v[222:223], s[44:45], 0, v[128:129]
	ds_read_b128 v[184:187], v181 offset:32768
	ds_read_b128 v[188:191], v181 offset:33792
	ds_read_b128 v[192:195], v181 offset:34816
	ds_read_b128 v[196:199], v181 offset:35840
	ds_read_b128 v[200:203], v181 offset:36864
	ds_read_b128 v[204:207], v181 offset:37888
	ds_read_b128 v[208:211], v181 offset:38912
	ds_read_b128 v[212:215], v181 offset:39936
	global_load_lds_dwordx4 v[222:223], off
	s_mov_b32 m0, s57
	v_lshl_add_u64 v[222:223], s[44:45], 0, v[132:133]
	global_load_lds_dwordx4 v[222:223], off
	s_waitcnt vmcnt(8)
	s_waitcnt lgkmcnt(0)
	s_barrier
	s_setprio 1
	s_waitcnt lgkmcnt(0)
	v_mfma_f32_16x16x32_bf16 v[124:127], v[144:147], v[184:187], v[124:127]
	v_mfma_f32_16x16x32_bf16 v[120:123], v[152:155], v[184:187], v[120:123]
	v_mfma_f32_16x16x32_bf16 v[108:111], v[144:147], v[192:195], v[108:111]
	v_mfma_f32_16x16x32_bf16 v[104:107], v[152:155], v[192:195], v[104:107]
	v_mfma_f32_16x16x32_bf16 v[92:95], v[144:147], v[200:203], v[92:95]
	v_mfma_f32_16x16x32_bf16 v[88:91], v[152:155], v[200:203], v[88:91]
	v_mfma_f32_16x16x32_bf16 v[76:79], v[144:147], v[208:211], v[76:79]
	v_mfma_f32_16x16x32_bf16 v[72:75], v[152:155], v[208:211], v[72:75]
	v_mfma_f32_16x16x32_bf16 v[124:127], v[148:151], v[188:191], v[124:127]
	v_mfma_f32_16x16x32_bf16 v[120:123], v[156:159], v[188:191], v[120:123]
	v_mfma_f32_16x16x32_bf16 v[108:111], v[148:151], v[196:199], v[108:111]
	v_mfma_f32_16x16x32_bf16 v[104:107], v[156:159], v[196:199], v[104:107]
	v_mfma_f32_16x16x32_bf16 v[92:95], v[148:151], v[204:207], v[92:95]
	v_mfma_f32_16x16x32_bf16 v[88:91], v[156:159], v[204:207], v[88:91]
	v_mfma_f32_16x16x32_bf16 v[76:79], v[148:151], v[212:215], v[76:79]
	v_mfma_f32_16x16x32_bf16 v[72:75], v[156:159], v[212:215], v[72:75]
	s_setprio 0
	s_setprio 1
	v_mfma_f32_16x16x32_bf16 v[116:119], v[160:163], v[184:187], v[116:119]
	v_mfma_f32_16x16x32_bf16 v[112:115], v[168:171], v[184:187], v[112:115]
	v_mfma_f32_16x16x32_bf16 v[100:103], v[160:163], v[192:195], v[100:103]
	v_mfma_f32_16x16x32_bf16 v[96:99], v[168:171], v[192:195], v[96:99]
	v_mfma_f32_16x16x32_bf16 v[84:87], v[160:163], v[200:203], v[84:87]
	v_mfma_f32_16x16x32_bf16 v[80:83], v[168:171], v[200:203], v[80:83]
	v_mfma_f32_16x16x32_bf16 v[68:71], v[160:163], v[208:211], v[68:71]
	v_mfma_f32_16x16x32_bf16 v[64:67], v[168:171], v[208:211], v[64:67]
	v_mfma_f32_16x16x32_bf16 v[116:119], v[164:167], v[188:191], v[116:119]
	v_mfma_f32_16x16x32_bf16 v[112:115], v[172:175], v[188:191], v[112:115]
	v_mfma_f32_16x16x32_bf16 v[100:103], v[164:167], v[196:199], v[100:103]
	v_mfma_f32_16x16x32_bf16 v[96:99], v[172:175], v[196:199], v[96:99]
	s_setprio 2
	s_barrier
	v_mfma_f32_16x16x32_bf16 v[84:87], v[164:167], v[204:207], v[84:87]
	v_mfma_f32_16x16x32_bf16 v[80:83], v[172:175], v[204:207], v[80:83]
	v_mfma_f32_16x16x32_bf16 v[68:71], v[164:167], v[212:215], v[68:71]
	v_mfma_f32_16x16x32_bf16 v[64:67], v[172:175], v[212:215], v[64:67]
	s_setprio 2
	s_add_i32 s44, s74, s51
	v_lshl_add_u64 v[176:177], v[176:177], 0, s[22:23]
	s_mov_b32 m0, s44
	ds_read_b128 v[184:187], v181 offset:49152
	ds_read_b128 v[188:191], v181 offset:50176
	ds_read_b128 v[192:195], v181 offset:51200
	ds_read_b128 v[196:199], v181 offset:52224
	ds_read_b128 v[200:203], v181 offset:53248
	ds_read_b128 v[204:207], v181 offset:54272
	ds_read_b128 v[208:211], v181 offset:55296
	ds_read_b128 v[212:215], v181 offset:56320
	global_load_lds_dwordx4 v[176:177], off
	s_add_i32 m0, s44, 0x2000
	s_add_u32 s40, s40, 0x40080
	v_lshl_add_u64 v[176:177], v[216:217], 0, s[22:23]
	s_addc_u32 s41, s41, 0
	s_add_i32 s44, s75, s51
	global_load_lds_dwordx4 v[176:177], off
	s_mov_b32 m0, s44
	v_lshl_add_u64 v[176:177], s[40:41], 0, v[130:131]
	global_load_lds_dwordx4 v[176:177], off
	s_add_i32 m0, s44, 0x2000
	v_lshl_add_u64 v[176:177], s[40:41], 0, v[134:135]
	global_load_lds_dwordx4 v[176:177], off
	s_mov_b32 m0, s64
	v_lshl_add_u64 v[176:177], v[218:219], 0, s[22:23]
	global_load_lds_dwordx4 v[176:177], off
	s_mov_b32 m0, s65
	v_lshl_add_u64 v[176:177], v[220:221], 0, s[22:23]
	global_load_lds_dwordx4 v[176:177], off
	s_waitcnt vmcnt(8)
	s_waitcnt lgkmcnt(0)
	s_barrier
	s_setprio 1
	s_waitcnt lgkmcnt(0)
	v_mfma_f32_16x16x32_bf16 v[60:63], v[144:147], v[184:187], v[60:63]
	v_mfma_f32_16x16x32_bf16 v[56:59], v[152:155], v[184:187], v[56:59]
	v_mfma_f32_16x16x32_bf16 v[44:47], v[144:147], v[192:195], v[44:47]
	v_mfma_f32_16x16x32_bf16 v[40:43], v[152:155], v[192:195], v[40:43]
	v_mfma_f32_16x16x32_bf16 v[28:31], v[144:147], v[200:203], v[28:31]
	v_mfma_f32_16x16x32_bf16 v[24:27], v[152:155], v[200:203], v[24:27]
	v_mfma_f32_16x16x32_bf16 v[12:15], v[144:147], v[208:211], v[12:15]
	v_mfma_f32_16x16x32_bf16 v[8:11], v[152:155], v[208:211], v[8:11]
	v_mfma_f32_16x16x32_bf16 v[60:63], v[148:151], v[188:191], v[60:63]
	v_mfma_f32_16x16x32_bf16 v[56:59], v[156:159], v[188:191], v[56:59]
	v_mfma_f32_16x16x32_bf16 v[44:47], v[148:151], v[196:199], v[44:47]
	v_mfma_f32_16x16x32_bf16 v[40:43], v[156:159], v[196:199], v[40:43]
	v_mfma_f32_16x16x32_bf16 v[28:31], v[148:151], v[204:207], v[28:31]
	v_mfma_f32_16x16x32_bf16 v[24:27], v[156:159], v[204:207], v[24:27]
	v_mfma_f32_16x16x32_bf16 v[12:15], v[148:151], v[212:215], v[12:15]
	v_mfma_f32_16x16x32_bf16 v[8:11], v[156:159], v[212:215], v[8:11]
	s_setprio 0
	s_setprio 1
	v_mfma_f32_16x16x32_bf16 v[52:55], v[160:163], v[184:187], v[52:55]
	v_mfma_f32_16x16x32_bf16 v[48:51], v[168:171], v[184:187], v[48:51]
	v_mfma_f32_16x16x32_bf16 v[36:39], v[160:163], v[192:195], v[36:39]
	v_mfma_f32_16x16x32_bf16 v[32:35], v[168:171], v[192:195], v[32:35]
	v_mfma_f32_16x16x32_bf16 v[20:23], v[160:163], v[200:203], v[20:23]
	v_mfma_f32_16x16x32_bf16 v[16:19], v[168:171], v[200:203], v[16:19]
	v_mfma_f32_16x16x32_bf16 v[4:7], v[160:163], v[208:211], v[4:7]
	v_mfma_f32_16x16x32_bf16 v[0:3], v[168:171], v[208:211], v[0:3]
	v_mfma_f32_16x16x32_bf16 v[52:55], v[164:167], v[188:191], v[52:55]
	v_mfma_f32_16x16x32_bf16 v[48:51], v[172:175], v[188:191], v[48:51]
	v_mfma_f32_16x16x32_bf16 v[36:39], v[164:167], v[196:199], v[36:39]
	v_mfma_f32_16x16x32_bf16 v[32:35], v[172:175], v[196:199], v[32:35]
	s_setprio 2
	s_barrier
	v_mfma_f32_16x16x32_bf16 v[20:23], v[164:167], v[204:207], v[20:23]
	v_mfma_f32_16x16x32_bf16 v[16:19], v[172:175], v[204:207], v[16:19]
	v_mfma_f32_16x16x32_bf16 v[4:7], v[164:167], v[212:215], v[4:7]
	v_mfma_f32_16x16x32_bf16 v[0:3], v[172:175], v[212:215], v[0:3]
	s_setprio 0
	s_add_i32 s73, s73, 2
	s_add_u32 s6, s6, 0x100
	s_addc_u32 s7, s7, 0
	s_add_u32 s71, s71, 0x100
	s_addc_u32 s72, s72, 0
	s_cmp_gt_u32 s73, 13
.LBB0_952:
	ds_read_b128 v[144:147], v179
	ds_read_b128 v[148:151], v179 offset:1024
	ds_read_b128 v[152:155], v179 offset:2048
	ds_read_b128 v[156:159], v179 offset:3072
	ds_read_b128 v[160:163], v180
	ds_read_b128 v[164:167], v180 offset:1024
	ds_read_b128 v[168:171], v180 offset:2048
	ds_read_b128 v[172:175], v180 offset:3072
	s_add_u32 s40, s6, 0xfffc0080
	s_addc_u32 s41, s7, -1
	s_cmp_eq_u32 s73, 12
	s_cselect_b32 s45, s27, s41
	s_cselect_b32 s44, s39, s40
	s_cselect_b32 s41, s29, s72
	s_cselect_b32 s40, s43, s71
	v_lshl_add_u64 v[176:177], s[6:7], 0, v[136:137]
	s_add_i32 m0, s54, 0xc000
	ds_read_b128 v[184:187], v181
	ds_read_b128 v[188:191], v181 offset:1024
	ds_read_b128 v[192:195], v181 offset:2048
	ds_read_b128 v[196:199], v181 offset:3072
	ds_read_b128 v[200:203], v181 offset:4096
	ds_read_b128 v[204:207], v181 offset:5120
	ds_read_b128 v[208:211], v181 offset:6144
	ds_read_b128 v[212:215], v181 offset:7168
	global_load_lds_dwordx4 v[176:177], off
	s_add_i32 m0, s54, 0xe000
	v_lshl_add_u64 v[176:177], s[6:7], 0, v[138:139]
	global_load_lds_dwordx4 v[176:177], off
	s_waitcnt vmcnt(8)
	s_waitcnt lgkmcnt(0)
	s_barrier
	s_setprio 1
	s_waitcnt lgkmcnt(0)
	v_mfma_f32_16x16x32_bf16 v[124:127], v[144:147], v[184:187], v[124:127]
	v_mfma_f32_16x16x32_bf16 v[120:123], v[152:155], v[184:187], v[120:123]
	v_mfma_f32_16x16x32_bf16 v[108:111], v[144:147], v[192:195], v[108:111]
	v_mfma_f32_16x16x32_bf16 v[104:107], v[152:155], v[192:195], v[104:107]
	v_mfma_f32_16x16x32_bf16 v[92:95], v[144:147], v[200:203], v[92:95]
	v_mfma_f32_16x16x32_bf16 v[88:91], v[152:155], v[200:203], v[88:91]
	v_mfma_f32_16x16x32_bf16 v[76:79], v[144:147], v[208:211], v[76:79]
	v_mfma_f32_16x16x32_bf16 v[72:75], v[152:155], v[208:211], v[72:75]
	v_mfma_f32_16x16x32_bf16 v[124:127], v[148:151], v[188:191], v[124:127]
	v_mfma_f32_16x16x32_bf16 v[120:123], v[156:159], v[188:191], v[120:123]
	v_mfma_f32_16x16x32_bf16 v[108:111], v[148:151], v[196:199], v[108:111]
	v_mfma_f32_16x16x32_bf16 v[104:107], v[156:159], v[196:199], v[104:107]
	v_mfma_f32_16x16x32_bf16 v[92:95], v[148:151], v[204:207], v[92:95]
	v_mfma_f32_16x16x32_bf16 v[88:91], v[156:159], v[204:207], v[88:91]
	v_mfma_f32_16x16x32_bf16 v[76:79], v[148:151], v[212:215], v[76:79]
	v_mfma_f32_16x16x32_bf16 v[72:75], v[156:159], v[212:215], v[72:75]
	s_setprio 0
	s_setprio 1
	v_mfma_f32_16x16x32_bf16 v[116:119], v[160:163], v[184:187], v[116:119]
	v_mfma_f32_16x16x32_bf16 v[112:115], v[168:171], v[184:187], v[112:115]
	v_mfma_f32_16x16x32_bf16 v[100:103], v[160:163], v[192:195], v[100:103]
	v_mfma_f32_16x16x32_bf16 v[96:99], v[168:171], v[192:195], v[96:99]
	v_mfma_f32_16x16x32_bf16 v[84:87], v[160:163], v[200:203], v[84:87]
	v_mfma_f32_16x16x32_bf16 v[80:83], v[168:171], v[200:203], v[80:83]
	v_mfma_f32_16x16x32_bf16 v[68:71], v[160:163], v[208:211], v[68:71]
	v_mfma_f32_16x16x32_bf16 v[64:67], v[168:171], v[208:211], v[64:67]
	v_mfma_f32_16x16x32_bf16 v[116:119], v[164:167], v[188:191], v[116:119]
	v_mfma_f32_16x16x32_bf16 v[112:115], v[172:175], v[188:191], v[112:115]
	v_mfma_f32_16x16x32_bf16 v[100:103], v[164:167], v[196:199], v[100:103]
	v_mfma_f32_16x16x32_bf16 v[96:99], v[172:175], v[196:199], v[96:99]
	s_setprio 2
	s_barrier
	v_mfma_f32_16x16x32_bf16 v[84:87], v[164:167], v[204:207], v[84:87]
	v_mfma_f32_16x16x32_bf16 v[80:83], v[172:175], v[204:207], v[80:83]
	v_mfma_f32_16x16x32_bf16 v[68:71], v[164:167], v[212:215], v[68:71]
	v_mfma_f32_16x16x32_bf16 v[64:67], v[172:175], v[212:215], v[64:67]
	s_setprio 2
	s_add_i32 s74, s69, s51
	v_lshl_add_u64 v[176:177], s[40:41], 0, v[130:131]
	s_mov_b32 m0, s74
	ds_read_b128 v[184:187], v181 offset:16384
	ds_read_b128 v[188:191], v181 offset:17408
	ds_read_b128 v[192:195], v181 offset:18432
	ds_read_b128 v[196:199], v181 offset:19456
	ds_read_b128 v[200:203], v181 offset:20480
	ds_read_b128 v[204:207], v181 offset:21504
	ds_read_b128 v[208:211], v181 offset:22528
	ds_read_b128 v[212:215], v181 offset:23552
	global_load_lds_dwordx4 v[176:177], off
	s_add_i32 m0, s74, 0x2000
	s_add_u32 s74, s40, 0x40000
	v_lshl_add_u64 v[216:217], s[40:41], 0, v[134:135]
	s_addc_u32 s75, s41, 0
	s_add_i32 s76, s70, s51
	global_load_lds_dwordx4 v[216:217], off
	v_lshl_add_u64 v[218:219], s[74:75], 0, v[130:131]
	s_mov_b32 m0, s76
	v_lshl_add_u64 v[220:221], s[44:45], 0, v[132:133]
	global_load_lds_dwordx4 v[218:219], off
	s_add_i32 m0, s76, 0x2000
	v_lshl_add_u64 v[218:219], s[74:75], 0, v[134:135]
	global_load_lds_dwordx4 v[218:219], off
	s_mov_b32 m0, s54
	v_lshl_add_u64 v[218:219], s[44:45], 0, v[128:129]
	global_load_lds_dwordx4 v[218:219], off
	s_mov_b32 m0, s55
	s_nop 0
	global_load_lds_dwordx4 v[220:221], off
	s_waitcnt vmcnt(8)
	s_waitcnt lgkmcnt(0)
	s_barrier
	s_setprio 1
	s_waitcnt lgkmcnt(0)
	v_mfma_f32_16x16x32_bf16 v[60:63], v[144:147], v[184:187], v[60:63]
	v_mfma_f32_16x16x32_bf16 v[56:59], v[152:155], v[184:187], v[56:59]
	v_mfma_f32_16x16x32_bf16 v[44:47], v[144:147], v[192:195], v[44:47]
	v_mfma_f32_16x16x32_bf16 v[40:43], v[152:155], v[192:195], v[40:43]
	v_mfma_f32_16x16x32_bf16 v[28:31], v[144:147], v[200:203], v[28:31]
	v_mfma_f32_16x16x32_bf16 v[24:27], v[152:155], v[200:203], v[24:27]
	v_mfma_f32_16x16x32_bf16 v[12:15], v[144:147], v[208:211], v[12:15]
	v_mfma_f32_16x16x32_bf16 v[8:11], v[152:155], v[208:211], v[8:11]
	v_mfma_f32_16x16x32_bf16 v[60:63], v[148:151], v[188:191], v[60:63]
	v_mfma_f32_16x16x32_bf16 v[56:59], v[156:159], v[188:191], v[56:59]
	v_mfma_f32_16x16x32_bf16 v[44:47], v[148:151], v[196:199], v[44:47]
	v_mfma_f32_16x16x32_bf16 v[40:43], v[156:159], v[196:199], v[40:43]
	v_mfma_f32_16x16x32_bf16 v[28:31], v[148:151], v[204:207], v[28:31]
	v_mfma_f32_16x16x32_bf16 v[24:27], v[156:159], v[204:207], v[24:27]
	v_mfma_f32_16x16x32_bf16 v[12:15], v[148:151], v[212:215], v[12:15]
	v_mfma_f32_16x16x32_bf16 v[8:11], v[156:159], v[212:215], v[8:11]
	s_setprio 0
	s_setprio 1
	v_mfma_f32_16x16x32_bf16 v[52:55], v[160:163], v[184:187], v[52:55]
	v_mfma_f32_16x16x32_bf16 v[48:51], v[168:171], v[184:187], v[48:51]
	v_mfma_f32_16x16x32_bf16 v[36:39], v[160:163], v[192:195], v[36:39]
	v_mfma_f32_16x16x32_bf16 v[32:35], v[168:171], v[192:195], v[32:35]
	v_mfma_f32_16x16x32_bf16 v[20:23], v[160:163], v[200:203], v[20:23]
	v_mfma_f32_16x16x32_bf16 v[16:19], v[168:171], v[200:203], v[16:19]
	v_mfma_f32_16x16x32_bf16 v[4:7], v[160:163], v[208:211], v[4:7]
	v_mfma_f32_16x16x32_bf16 v[0:3], v[168:171], v[208:211], v[0:3]
	v_mfma_f32_16x16x32_bf16 v[52:55], v[164:167], v[188:191], v[52:55]
	v_mfma_f32_16x16x32_bf16 v[48:51], v[172:175], v[188:191], v[48:51]
	v_mfma_f32_16x16x32_bf16 v[36:39], v[164:167], v[196:199], v[36:39]
	v_mfma_f32_16x16x32_bf16 v[32:35], v[172:175], v[196:199], v[32:35]
	s_setprio 2
	s_barrier
	v_mfma_f32_16x16x32_bf16 v[20:23], v[164:167], v[204:207], v[20:23]
	v_mfma_f32_16x16x32_bf16 v[16:19], v[172:175], v[204:207], v[16:19]
	v_mfma_f32_16x16x32_bf16 v[4:7], v[164:167], v[212:215], v[4:7]
	v_mfma_f32_16x16x32_bf16 v[0:3], v[172:175], v[212:215], v[0:3]
	s_setprio 0
	s_add_i32 s74, 0, 0x18000
	s_add_i32 s75, 0, 0x1c000
	v_add_u32_e32 v156, s74, v178
	v_add_u32_e32 v172, s75, v178
	ds_read_b128 v[144:147], v156
	ds_read_b128 v[148:151], v156 offset:1024
	ds_read_b128 v[152:155], v156 offset:2048
	ds_read_b128 v[156:159], v156 offset:3072
	ds_read_b128 v[160:163], v172
	ds_read_b128 v[164:167], v172 offset:1024
	ds_read_b128 v[168:171], v172 offset:2048
	ds_read_b128 v[172:175], v172 offset:3072
	s_add_u32 s44, s44, 0x40000
	s_addc_u32 s45, s45, 0
	s_mov_b32 m0, s56
	v_lshl_add_u64 v[222:223], s[44:45], 0, v[128:129]
	ds_read_b128 v[184:187], v181 offset:32768
	ds_read_b128 v[188:191], v181 offset:33792
	ds_read_b128 v[192:195], v181 offset:34816
	ds_read_b128 v[196:199], v181 offset:35840
	ds_read_b128 v[200:203], v181 offset:36864
	ds_read_b128 v[204:207], v181 offset:37888
	ds_read_b128 v[208:211], v181 offset:38912
	ds_read_b128 v[212:215], v181 offset:39936
	global_load_lds_dwordx4 v[222:223], off
	s_mov_b32 m0, s57
	v_lshl_add_u64 v[222:223], s[44:45], 0, v[132:133]
	global_load_lds_dwordx4 v[222:223], off
	s_waitcnt vmcnt(8)
	s_waitcnt lgkmcnt(0)
	s_barrier
	s_setprio 1
	s_waitcnt lgkmcnt(0)
	v_mfma_f32_16x16x32_bf16 v[124:127], v[144:147], v[184:187], v[124:127]
	v_mfma_f32_16x16x32_bf16 v[120:123], v[152:155], v[184:187], v[120:123]
	v_mfma_f32_16x16x32_bf16 v[108:111], v[144:147], v[192:195], v[108:111]
	v_mfma_f32_16x16x32_bf16 v[104:107], v[152:155], v[192:195], v[104:107]
	v_mfma_f32_16x16x32_bf16 v[92:95], v[144:147], v[200:203], v[92:95]
	v_mfma_f32_16x16x32_bf16 v[88:91], v[152:155], v[200:203], v[88:91]
	v_mfma_f32_16x16x32_bf16 v[76:79], v[144:147], v[208:211], v[76:79]
	v_mfma_f32_16x16x32_bf16 v[72:75], v[152:155], v[208:211], v[72:75]
	v_mfma_f32_16x16x32_bf16 v[124:127], v[148:151], v[188:191], v[124:127]
	v_mfma_f32_16x16x32_bf16 v[120:123], v[156:159], v[188:191], v[120:123]
	v_mfma_f32_16x16x32_bf16 v[108:111], v[148:151], v[196:199], v[108:111]
	v_mfma_f32_16x16x32_bf16 v[104:107], v[156:159], v[196:199], v[104:107]
	v_mfma_f32_16x16x32_bf16 v[92:95], v[148:151], v[204:207], v[92:95]
	v_mfma_f32_16x16x32_bf16 v[88:91], v[156:159], v[204:207], v[88:91]
	v_mfma_f32_16x16x32_bf16 v[76:79], v[148:151], v[212:215], v[76:79]
	v_mfma_f32_16x16x32_bf16 v[72:75], v[156:159], v[212:215], v[72:75]
	s_setprio 0
	s_setprio 1
	v_mfma_f32_16x16x32_bf16 v[116:119], v[160:163], v[184:187], v[116:119]
	v_mfma_f32_16x16x32_bf16 v[112:115], v[168:171], v[184:187], v[112:115]
	v_mfma_f32_16x16x32_bf16 v[100:103], v[160:163], v[192:195], v[100:103]
	v_mfma_f32_16x16x32_bf16 v[96:99], v[168:171], v[192:195], v[96:99]
	v_mfma_f32_16x16x32_bf16 v[84:87], v[160:163], v[200:203], v[84:87]
	v_mfma_f32_16x16x32_bf16 v[80:83], v[168:171], v[200:203], v[80:83]
	v_mfma_f32_16x16x32_bf16 v[68:71], v[160:163], v[208:211], v[68:71]
	v_mfma_f32_16x16x32_bf16 v[64:67], v[168:171], v[208:211], v[64:67]
	v_mfma_f32_16x16x32_bf16 v[116:119], v[164:167], v[188:191], v[116:119]
	v_mfma_f32_16x16x32_bf16 v[112:115], v[172:175], v[188:191], v[112:115]
	v_mfma_f32_16x16x32_bf16 v[100:103], v[164:167], v[196:199], v[100:103]
	v_mfma_f32_16x16x32_bf16 v[96:99], v[172:175], v[196:199], v[96:99]
	s_setprio 2
	s_barrier
	v_mfma_f32_16x16x32_bf16 v[84:87], v[164:167], v[204:207], v[84:87]
	v_mfma_f32_16x16x32_bf16 v[80:83], v[172:175], v[204:207], v[80:83]
	v_mfma_f32_16x16x32_bf16 v[68:71], v[164:167], v[212:215], v[68:71]
	v_mfma_f32_16x16x32_bf16 v[64:67], v[172:175], v[212:215], v[64:67]
	s_setprio 2
	s_add_i32 s44, s74, s51
	v_lshl_add_u64 v[176:177], v[176:177], 0, s[22:23]
	s_mov_b32 m0, s44
	ds_read_b128 v[184:187], v181 offset:49152
	ds_read_b128 v[188:191], v181 offset:50176
	ds_read_b128 v[192:195], v181 offset:51200
	ds_read_b128 v[196:199], v181 offset:52224
	ds_read_b128 v[200:203], v181 offset:53248
	ds_read_b128 v[204:207], v181 offset:54272
	ds_read_b128 v[208:211], v181 offset:55296
	ds_read_b128 v[212:215], v181 offset:56320
	global_load_lds_dwordx4 v[176:177], off
	s_add_i32 m0, s44, 0x2000
	s_add_u32 s40, s40, 0x40080
	v_lshl_add_u64 v[176:177], v[216:217], 0, s[22:23]
	s_addc_u32 s41, s41, 0
	s_add_i32 s44, s75, s51
	global_load_lds_dwordx4 v[176:177], off
	s_mov_b32 m0, s44
	v_lshl_add_u64 v[176:177], s[40:41], 0, v[130:131]
	global_load_lds_dwordx4 v[176:177], off
	s_add_i32 m0, s44, 0x2000
	v_lshl_add_u64 v[176:177], s[40:41], 0, v[134:135]
	global_load_lds_dwordx4 v[176:177], off
	s_mov_b32 m0, s64
	v_lshl_add_u64 v[176:177], v[218:219], 0, s[22:23]
	global_load_lds_dwordx4 v[176:177], off
	s_mov_b32 m0, s65
	v_lshl_add_u64 v[176:177], v[220:221], 0, s[22:23]
	global_load_lds_dwordx4 v[176:177], off
	s_waitcnt vmcnt(8)
	s_waitcnt lgkmcnt(0)
	s_barrier
	s_setprio 1
	s_waitcnt lgkmcnt(0)
	v_mfma_f32_16x16x32_bf16 v[60:63], v[144:147], v[184:187], v[60:63]
	v_mfma_f32_16x16x32_bf16 v[56:59], v[152:155], v[184:187], v[56:59]
	v_mfma_f32_16x16x32_bf16 v[44:47], v[144:147], v[192:195], v[44:47]
	v_mfma_f32_16x16x32_bf16 v[40:43], v[152:155], v[192:195], v[40:43]
	v_mfma_f32_16x16x32_bf16 v[28:31], v[144:147], v[200:203], v[28:31]
	v_mfma_f32_16x16x32_bf16 v[24:27], v[152:155], v[200:203], v[24:27]
	v_mfma_f32_16x16x32_bf16 v[12:15], v[144:147], v[208:211], v[12:15]
	v_mfma_f32_16x16x32_bf16 v[8:11], v[152:155], v[208:211], v[8:11]
	v_mfma_f32_16x16x32_bf16 v[60:63], v[148:151], v[188:191], v[60:63]
	v_mfma_f32_16x16x32_bf16 v[56:59], v[156:159], v[188:191], v[56:59]
	v_mfma_f32_16x16x32_bf16 v[44:47], v[148:151], v[196:199], v[44:47]
	v_mfma_f32_16x16x32_bf16 v[40:43], v[156:159], v[196:199], v[40:43]
	v_mfma_f32_16x16x32_bf16 v[28:31], v[148:151], v[204:207], v[28:31]
	v_mfma_f32_16x16x32_bf16 v[24:27], v[156:159], v[204:207], v[24:27]
	v_mfma_f32_16x16x32_bf16 v[12:15], v[148:151], v[212:215], v[12:15]
	v_mfma_f32_16x16x32_bf16 v[8:11], v[156:159], v[212:215], v[8:11]
	s_setprio 0
	s_setprio 1
	v_mfma_f32_16x16x32_bf16 v[52:55], v[160:163], v[184:187], v[52:55]
	v_mfma_f32_16x16x32_bf16 v[48:51], v[168:171], v[184:187], v[48:51]
	v_mfma_f32_16x16x32_bf16 v[36:39], v[160:163], v[192:195], v[36:39]
	v_mfma_f32_16x16x32_bf16 v[32:35], v[168:171], v[192:195], v[32:35]
	v_mfma_f32_16x16x32_bf16 v[20:23], v[160:163], v[200:203], v[20:23]
	v_mfma_f32_16x16x32_bf16 v[16:19], v[168:171], v[200:203], v[16:19]
	v_mfma_f32_16x16x32_bf16 v[4:7], v[160:163], v[208:211], v[4:7]
	v_mfma_f32_16x16x32_bf16 v[0:3], v[168:171], v[208:211], v[0:3]
	v_mfma_f32_16x16x32_bf16 v[52:55], v[164:167], v[188:191], v[52:55]
	v_mfma_f32_16x16x32_bf16 v[48:51], v[172:175], v[188:191], v[48:51]
	v_mfma_f32_16x16x32_bf16 v[36:39], v[164:167], v[196:199], v[36:39]
	v_mfma_f32_16x16x32_bf16 v[32:35], v[172:175], v[196:199], v[32:35]
	s_setprio 2
	s_barrier
	v_mfma_f32_16x16x32_bf16 v[20:23], v[164:167], v[204:207], v[20:23]
	v_mfma_f32_16x16x32_bf16 v[16:19], v[172:175], v[204:207], v[16:19]
	v_mfma_f32_16x16x32_bf16 v[4:7], v[164:167], v[212:215], v[4:7]
	v_mfma_f32_16x16x32_bf16 v[0:3], v[172:175], v[212:215], v[0:3]
	s_setprio 0
	s_add_i32 s73, s73, 2
	s_add_u32 s6, s6, 0x100
	s_addc_u32 s7, s7, 0
	s_add_u32 s71, s71, 0x100
	s_addc_u32 s72, s72, 0
	s_cmp_gt_u32 s73, 13
	s_cbranch_scc0 .LBB0_952

.LBB0_1145:
	s_ashr_i32 s23, s22, 31
	s_lshl_b64 s[26:27], s[22:23], 19
	s_add_u32 s26, s45, s26
	s_addc_u32 s27, s46, s27
	s_and_b64 s[28:29], s[4:5], exec
	s_cselect_b32 s23, s27, s39
	s_cselect_b32 s31, s26, s38
	s_ashr_i32 s25, s24, 31
	s_lshl_b64 s[28:29], s[24:25], 19
	s_add_u32 s28, s47, s28
	s_addc_u32 s29, s48, s29
	s_and_b64 s[42:43], s[4:5], exec
	s_cselect_b32 s25, s29, s41
	s_cselect_b32 s37, s28, s40
	s_add_u32 s38, s38, 0x40080
	s_addc_u32 s39, s39, 0
	s_add_u32 s64, s40, 0x100
	s_addc_u32 s65, s41, 0
	s_mov_b32 s66, -2
	ds_read_b128 v[120:123], v233
	ds_read_b128 v[132:135], v233 offset:1024
	ds_read_b128 v[136:139], v233 offset:2048
	ds_read_b128 v[140:143], v233 offset:3072
	ds_read_b128 v[144:147], v234
	ds_read_b128 v[148:151], v234 offset:1024
	ds_read_b128 v[152:155], v234 offset:2048
	ds_read_b128 v[156:159], v234 offset:3072
	s_add_u32 s40, s38, 0xfffc0080
	s_addc_u32 s41, s39, -1
	s_cmp_eq_u32 s66, 12
	s_cselect_b32 s43, s23, s41
	s_cselect_b32 s42, s31, s40
	s_cselect_b32 s41, s25, s65
	s_cselect_b32 s40, s37, s64
	v_lshl_add_u64 v[208:209], s[38:39], 0, v[192:193]
	s_add_i32 m0, s50, 0xc000
	ds_read_b128 v[160:163], v235
	ds_read_b128 v[164:167], v235 offset:1024
	ds_read_b128 v[168:171], v235 offset:2048
	ds_read_b128 v[172:175], v235 offset:3072
	ds_read_b128 v[176:179], v235 offset:4096
	ds_read_b128 v[180:183], v235 offset:5120
	ds_read_b128 v[200:203], v235 offset:6144
	ds_read_b128 v[204:207], v235 offset:7168
	global_load_lds_dwordx4 v[208:209], off
	s_add_i32 m0, s50, 0xe000
	v_lshl_add_u64 v[208:209], s[38:39], 0, v[194:195]
	global_load_lds_dwordx4 v[208:209], off
	s_waitcnt vmcnt(8)
	s_waitcnt lgkmcnt(0)
	s_barrier
	s_setprio 1
	s_waitcnt lgkmcnt(0)
	v_mfma_f32_16x16x32_bf16 v[128:131], v[120:123], v[160:163], 0
	v_mfma_f32_16x16x32_bf16 v[124:127], v[136:139], v[160:163], 0
	v_mfma_f32_16x16x32_bf16 v[108:111], v[120:123], v[168:171], 0
	v_mfma_f32_16x16x32_bf16 v[104:107], v[136:139], v[168:171], 0
	v_mfma_f32_16x16x32_bf16 v[92:95], v[120:123], v[176:179], 0
	v_mfma_f32_16x16x32_bf16 v[88:91], v[136:139], v[176:179], 0
	v_mfma_f32_16x16x32_bf16 v[76:79], v[120:123], v[200:203], 0
	v_mfma_f32_16x16x32_bf16 v[72:75], v[136:139], v[200:203], 0
	v_mfma_f32_16x16x32_bf16 v[128:131], v[132:135], v[164:167], v[128:131]
	v_mfma_f32_16x16x32_bf16 v[124:127], v[140:143], v[164:167], v[124:127]
	v_mfma_f32_16x16x32_bf16 v[108:111], v[132:135], v[172:175], v[108:111]
	v_mfma_f32_16x16x32_bf16 v[104:107], v[140:143], v[172:175], v[104:107]
	v_mfma_f32_16x16x32_bf16 v[92:95], v[132:135], v[180:183], v[92:95]
	v_mfma_f32_16x16x32_bf16 v[88:91], v[140:143], v[180:183], v[88:91]
	v_mfma_f32_16x16x32_bf16 v[76:79], v[132:135], v[204:207], v[76:79]
	v_mfma_f32_16x16x32_bf16 v[72:75], v[140:143], v[204:207], v[72:75]
	s_setprio 0
	s_setprio 1
	v_mfma_f32_16x16x32_bf16 v[116:119], v[144:147], v[160:163], 0
	v_mfma_f32_16x16x32_bf16 v[112:115], v[152:155], v[160:163], 0
	v_mfma_f32_16x16x32_bf16 v[100:103], v[144:147], v[168:171], 0
	v_mfma_f32_16x16x32_bf16 v[96:99], v[152:155], v[168:171], 0
	v_mfma_f32_16x16x32_bf16 v[84:87], v[144:147], v[176:179], 0
	v_mfma_f32_16x16x32_bf16 v[80:83], v[152:155], v[176:179], 0
	v_mfma_f32_16x16x32_bf16 v[68:71], v[144:147], v[200:203], 0
	v_mfma_f32_16x16x32_bf16 v[64:67], v[152:155], v[200:203], 0
	v_mfma_f32_16x16x32_bf16 v[116:119], v[148:151], v[164:167], v[116:119]
	v_mfma_f32_16x16x32_bf16 v[112:115], v[156:159], v[164:167], v[112:115]
	v_mfma_f32_16x16x32_bf16 v[100:103], v[148:151], v[172:175], v[100:103]
	v_mfma_f32_16x16x32_bf16 v[96:99], v[156:159], v[172:175], v[96:99]
	s_setprio 2
	s_barrier
	v_mfma_f32_16x16x32_bf16 v[84:87], v[148:151], v[180:183], v[84:87]
	v_mfma_f32_16x16x32_bf16 v[80:83], v[156:159], v[180:183], v[80:83]
	v_mfma_f32_16x16x32_bf16 v[68:71], v[148:151], v[204:207], v[68:71]
	v_mfma_f32_16x16x32_bf16 v[64:67], v[156:159], v[204:207], v[64:67]
	s_setprio 2
	s_add_i32 s67, s62, s49
	v_lshl_add_u64 v[208:209], s[40:41], 0, v[186:187]
	s_mov_b32 m0, s67
	ds_read_b128 v[160:163], v235 offset:16384
	ds_read_b128 v[164:167], v235 offset:17408
	ds_read_b128 v[168:171], v235 offset:18432
	ds_read_b128 v[172:175], v235 offset:19456
	ds_read_b128 v[176:179], v235 offset:20480
	ds_read_b128 v[180:183], v235 offset:21504
	ds_read_b128 v[200:203], v235 offset:22528
	ds_read_b128 v[204:207], v235 offset:23552
	global_load_lds_dwordx4 v[208:209], off
	s_add_i32 m0, s67, 0x2000
	s_add_u32 s68, s40, 0x40000
	v_lshl_add_u64 v[210:211], s[40:41], 0, v[190:191]
	s_addc_u32 s69, s41, 0
	s_add_i32 s67, s63, s49
	global_load_lds_dwordx4 v[210:211], off
	v_lshl_add_u64 v[212:213], s[68:69], 0, v[186:187]
	s_mov_b32 m0, s67
	v_lshl_add_u64 v[214:215], s[42:43], 0, v[188:189]
	global_load_lds_dwordx4 v[212:213], off
	s_add_i32 m0, s67, 0x2000
	v_lshl_add_u64 v[212:213], s[68:69], 0, v[190:191]
	global_load_lds_dwordx4 v[212:213], off
	s_mov_b32 m0, s50
	v_lshl_add_u64 v[212:213], s[42:43], 0, v[184:185]
	global_load_lds_dwordx4 v[212:213], off
	s_mov_b32 m0, s51
	s_nop 0
	global_load_lds_dwordx4 v[214:215], off
	s_waitcnt vmcnt(8)
	s_waitcnt lgkmcnt(0)
	s_barrier
	s_setprio 1
	s_waitcnt lgkmcnt(0)
	v_mfma_f32_16x16x32_bf16 v[60:63], v[120:123], v[160:163], 0
	v_mfma_f32_16x16x32_bf16 v[56:59], v[136:139], v[160:163], 0
	v_mfma_f32_16x16x32_bf16 v[44:47], v[120:123], v[168:171], 0
	v_mfma_f32_16x16x32_bf16 v[40:43], v[136:139], v[168:171], 0
	v_mfma_f32_16x16x32_bf16 v[28:31], v[120:123], v[176:179], 0
	v_mfma_f32_16x16x32_bf16 v[24:27], v[136:139], v[176:179], 0
	v_mfma_f32_16x16x32_bf16 v[12:15], v[120:123], v[200:203], 0
	v_mfma_f32_16x16x32_bf16 v[8:11], v[136:139], v[200:203], 0
	v_mfma_f32_16x16x32_bf16 v[60:63], v[132:135], v[164:167], v[60:63]
	v_mfma_f32_16x16x32_bf16 v[56:59], v[140:143], v[164:167], v[56:59]
	v_mfma_f32_16x16x32_bf16 v[44:47], v[132:135], v[172:175], v[44:47]
	v_mfma_f32_16x16x32_bf16 v[40:43], v[140:143], v[172:175], v[40:43]
	v_mfma_f32_16x16x32_bf16 v[28:31], v[132:135], v[180:183], v[28:31]
	v_mfma_f32_16x16x32_bf16 v[24:27], v[140:143], v[180:183], v[24:27]
	v_mfma_f32_16x16x32_bf16 v[12:15], v[132:135], v[204:207], v[12:15]
	v_mfma_f32_16x16x32_bf16 v[8:11], v[140:143], v[204:207], v[8:11]
	s_setprio 0
	s_setprio 1
	v_mfma_f32_16x16x32_bf16 v[52:55], v[144:147], v[160:163], 0
	v_mfma_f32_16x16x32_bf16 v[48:51], v[152:155], v[160:163], 0
	v_mfma_f32_16x16x32_bf16 v[36:39], v[144:147], v[168:171], 0
	v_mfma_f32_16x16x32_bf16 v[32:35], v[152:155], v[168:171], 0
	v_mfma_f32_16x16x32_bf16 v[20:23], v[144:147], v[176:179], 0
	v_mfma_f32_16x16x32_bf16 v[16:19], v[152:155], v[176:179], 0
	v_mfma_f32_16x16x32_bf16 v[4:7], v[144:147], v[200:203], 0
	v_mfma_f32_16x16x32_bf16 v[0:3], v[152:155], v[200:203], 0
	v_mfma_f32_16x16x32_bf16 v[52:55], v[148:151], v[164:167], v[52:55]
	v_mfma_f32_16x16x32_bf16 v[48:51], v[156:159], v[164:167], v[48:51]
	v_mfma_f32_16x16x32_bf16 v[36:39], v[148:151], v[172:175], v[36:39]
	v_mfma_f32_16x16x32_bf16 v[32:35], v[156:159], v[172:175], v[32:35]
	s_setprio 2
	s_barrier
	v_mfma_f32_16x16x32_bf16 v[20:23], v[148:151], v[180:183], v[20:23]
	v_mfma_f32_16x16x32_bf16 v[16:19], v[156:159], v[180:183], v[16:19]
	v_mfma_f32_16x16x32_bf16 v[4:7], v[148:151], v[204:207], v[4:7]
	v_mfma_f32_16x16x32_bf16 v[0:3], v[156:159], v[204:207], v[0:3]
	s_setprio 0
	s_add_i32 s67, 0, 0x18000
	s_add_i32 s68, 0, 0x1c000
	v_add_u32_e32 v140, s67, v232
	v_add_u32_e32 v156, s68, v232
	ds_read_b128 v[120:123], v140
	ds_read_b128 v[132:135], v140 offset:1024
	ds_read_b128 v[136:139], v140 offset:2048
	ds_read_b128 v[140:143], v140 offset:3072
	ds_read_b128 v[144:147], v156
	ds_read_b128 v[148:151], v156 offset:1024
	ds_read_b128 v[152:155], v156 offset:2048
	ds_read_b128 v[156:159], v156 offset:3072
	s_add_u32 s42, s42, 0x40000
	s_addc_u32 s43, s43, 0
	s_mov_b32 m0, s54
	v_lshl_add_u64 v[216:217], s[42:43], 0, v[184:185]
	ds_read_b128 v[160:163], v235 offset:32768
	ds_read_b128 v[164:167], v235 offset:33792
	ds_read_b128 v[168:171], v235 offset:34816
	ds_read_b128 v[172:175], v235 offset:35840
	ds_read_b128 v[176:179], v235 offset:36864
	ds_read_b128 v[180:183], v235 offset:37888
	ds_read_b128 v[200:203], v235 offset:38912
	ds_read_b128 v[204:207], v235 offset:39936
	global_load_lds_dwordx4 v[216:217], off
	s_mov_b32 m0, s55
	v_lshl_add_u64 v[216:217], s[42:43], 0, v[188:189]
	global_load_lds_dwordx4 v[216:217], off
	s_waitcnt vmcnt(8)
	s_waitcnt lgkmcnt(0)
	s_barrier
	s_setprio 1
	s_waitcnt lgkmcnt(0)
	v_mfma_f32_16x16x32_bf16 v[128:131], v[120:123], v[160:163], v[128:131]
	v_mfma_f32_16x16x32_bf16 v[124:127], v[136:139], v[160:163], v[124:127]
	v_mfma_f32_16x16x32_bf16 v[108:111], v[120:123], v[168:171], v[108:111]
	v_mfma_f32_16x16x32_bf16 v[104:107], v[136:139], v[168:171], v[104:107]
	v_mfma_f32_16x16x32_bf16 v[92:95], v[120:123], v[176:179], v[92:95]
	v_mfma_f32_16x16x32_bf16 v[88:91], v[136:139], v[176:179], v[88:91]
	v_mfma_f32_16x16x32_bf16 v[76:79], v[120:123], v[200:203], v[76:79]
	v_mfma_f32_16x16x32_bf16 v[72:75], v[136:139], v[200:203], v[72:75]
	v_mfma_f32_16x16x32_bf16 v[128:131], v[132:135], v[164:167], v[128:131]
	v_mfma_f32_16x16x32_bf16 v[124:127], v[140:143], v[164:167], v[124:127]
	v_mfma_f32_16x16x32_bf16 v[108:111], v[132:135], v[172:175], v[108:111]
	v_mfma_f32_16x16x32_bf16 v[104:107], v[140:143], v[172:175], v[104:107]
	v_mfma_f32_16x16x32_bf16 v[92:95], v[132:135], v[180:183], v[92:95]
	v_mfma_f32_16x16x32_bf16 v[88:91], v[140:143], v[180:183], v[88:91]
	v_mfma_f32_16x16x32_bf16 v[76:79], v[132:135], v[204:207], v[76:79]
	v_mfma_f32_16x16x32_bf16 v[72:75], v[140:143], v[204:207], v[72:75]
	s_setprio 0
	s_setprio 1
	v_mfma_f32_16x16x32_bf16 v[116:119], v[144:147], v[160:163], v[116:119]
	v_mfma_f32_16x16x32_bf16 v[112:115], v[152:155], v[160:163], v[112:115]
	v_mfma_f32_16x16x32_bf16 v[100:103], v[144:147], v[168:171], v[100:103]
	v_mfma_f32_16x16x32_bf16 v[96:99], v[152:155], v[168:171], v[96:99]
	v_mfma_f32_16x16x32_bf16 v[84:87], v[144:147], v[176:179], v[84:87]
	v_mfma_f32_16x16x32_bf16 v[80:83], v[152:155], v[176:179], v[80:83]
	v_mfma_f32_16x16x32_bf16 v[68:71], v[144:147], v[200:203], v[68:71]
	v_mfma_f32_16x16x32_bf16 v[64:67], v[152:155], v[200:203], v[64:67]
	v_mfma_f32_16x16x32_bf16 v[116:119], v[148:151], v[164:167], v[116:119]
	v_mfma_f32_16x16x32_bf16 v[112:115], v[156:159], v[164:167], v[112:115]
	v_mfma_f32_16x16x32_bf16 v[100:103], v[148:151], v[172:175], v[100:103]
	v_mfma_f32_16x16x32_bf16 v[96:99], v[156:159], v[172:175], v[96:99]
	s_setprio 2
	s_barrier
	v_mfma_f32_16x16x32_bf16 v[84:87], v[148:151], v[180:183], v[84:87]
	v_mfma_f32_16x16x32_bf16 v[80:83], v[156:159], v[180:183], v[80:83]
	v_mfma_f32_16x16x32_bf16 v[68:71], v[148:151], v[204:207], v[68:71]
	v_mfma_f32_16x16x32_bf16 v[64:67], v[156:159], v[204:207], v[64:67]
	s_setprio 2
	s_add_i32 s42, s67, s49
	v_lshl_add_u64 v[208:209], v[208:209], 0, s[18:19]
	s_mov_b32 m0, s42
	ds_read_b128 v[160:163], v235 offset:49152
	ds_read_b128 v[164:167], v235 offset:50176
	ds_read_b128 v[168:171], v235 offset:51200
	ds_read_b128 v[172:175], v235 offset:52224
	ds_read_b128 v[176:179], v235 offset:53248
	ds_read_b128 v[180:183], v235 offset:54272
	ds_read_b128 v[200:203], v235 offset:55296
	ds_read_b128 v[204:207], v235 offset:56320
	global_load_lds_dwordx4 v[208:209], off
	s_add_i32 m0, s42, 0x2000
	s_add_u32 s40, s40, 0x40080
	v_lshl_add_u64 v[208:209], v[210:211], 0, s[18:19]
	s_addc_u32 s41, s41, 0
	s_add_i32 s42, s68, s49
	global_load_lds_dwordx4 v[208:209], off
	s_mov_b32 m0, s42
	v_lshl_add_u64 v[208:209], s[40:41], 0, v[186:187]
	global_load_lds_dwordx4 v[208:209], off
	s_add_i32 m0, s42, 0x2000
	v_lshl_add_u64 v[208:209], s[40:41], 0, v[190:191]
	global_load_lds_dwordx4 v[208:209], off
	s_mov_b32 m0, s57
	v_lshl_add_u64 v[208:209], v[212:213], 0, s[18:19]
	global_load_lds_dwordx4 v[208:209], off
	s_mov_b32 m0, s58
	v_lshl_add_u64 v[208:209], v[214:215], 0, s[18:19]
	global_load_lds_dwordx4 v[208:209], off
	s_waitcnt vmcnt(8)
	s_waitcnt lgkmcnt(0)
	s_barrier
	s_setprio 1
	s_waitcnt lgkmcnt(0)
	v_mfma_f32_16x16x32_bf16 v[60:63], v[120:123], v[160:163], v[60:63]
	v_mfma_f32_16x16x32_bf16 v[56:59], v[136:139], v[160:163], v[56:59]
	v_mfma_f32_16x16x32_bf16 v[44:47], v[120:123], v[168:171], v[44:47]
	v_mfma_f32_16x16x32_bf16 v[40:43], v[136:139], v[168:171], v[40:43]
	v_mfma_f32_16x16x32_bf16 v[28:31], v[120:123], v[176:179], v[28:31]
	v_mfma_f32_16x16x32_bf16 v[24:27], v[136:139], v[176:179], v[24:27]
	v_mfma_f32_16x16x32_bf16 v[12:15], v[120:123], v[200:203], v[12:15]
	v_mfma_f32_16x16x32_bf16 v[8:11], v[136:139], v[200:203], v[8:11]
	v_mfma_f32_16x16x32_bf16 v[60:63], v[132:135], v[164:167], v[60:63]
	v_mfma_f32_16x16x32_bf16 v[56:59], v[140:143], v[164:167], v[56:59]
	v_mfma_f32_16x16x32_bf16 v[44:47], v[132:135], v[172:175], v[44:47]
	v_mfma_f32_16x16x32_bf16 v[40:43], v[140:143], v[172:175], v[40:43]
	v_mfma_f32_16x16x32_bf16 v[28:31], v[132:135], v[180:183], v[28:31]
	v_mfma_f32_16x16x32_bf16 v[24:27], v[140:143], v[180:183], v[24:27]
	v_mfma_f32_16x16x32_bf16 v[12:15], v[132:135], v[204:207], v[12:15]
	v_mfma_f32_16x16x32_bf16 v[8:11], v[140:143], v[204:207], v[8:11]
	s_setprio 0
	s_setprio 1
	v_mfma_f32_16x16x32_bf16 v[52:55], v[144:147], v[160:163], v[52:55]
	v_mfma_f32_16x16x32_bf16 v[48:51], v[152:155], v[160:163], v[48:51]
	v_mfma_f32_16x16x32_bf16 v[36:39], v[144:147], v[168:171], v[36:39]
	v_mfma_f32_16x16x32_bf16 v[32:35], v[152:155], v[168:171], v[32:35]
	v_mfma_f32_16x16x32_bf16 v[20:23], v[144:147], v[176:179], v[20:23]
	v_mfma_f32_16x16x32_bf16 v[16:19], v[152:155], v[176:179], v[16:19]
	v_mfma_f32_16x16x32_bf16 v[4:7], v[144:147], v[200:203], v[4:7]
	v_mfma_f32_16x16x32_bf16 v[0:3], v[152:155], v[200:203], v[0:3]
	v_mfma_f32_16x16x32_bf16 v[52:55], v[148:151], v[164:167], v[52:55]
	v_mfma_f32_16x16x32_bf16 v[48:51], v[156:159], v[164:167], v[48:51]
	v_mfma_f32_16x16x32_bf16 v[36:39], v[148:151], v[172:175], v[36:39]
	v_mfma_f32_16x16x32_bf16 v[32:35], v[156:159], v[172:175], v[32:35]
	s_setprio 2
	s_barrier
	v_mfma_f32_16x16x32_bf16 v[20:23], v[148:151], v[180:183], v[20:23]
	v_mfma_f32_16x16x32_bf16 v[16:19], v[156:159], v[180:183], v[16:19]
	v_mfma_f32_16x16x32_bf16 v[4:7], v[148:151], v[204:207], v[4:7]
	v_mfma_f32_16x16x32_bf16 v[0:3], v[156:159], v[204:207], v[0:3]
	s_setprio 0
	s_add_i32 s66, s66, 2
	s_add_u32 s38, s38, 0x100
	s_addc_u32 s39, s39, 0
	s_add_u32 s64, s64, 0x100
	s_addc_u32 s65, s65, 0
	s_cmp_gt_u32 s66, 13
.LBB0_1146:
	ds_read_b128 v[120:123], v233
	ds_read_b128 v[132:135], v233 offset:1024
	ds_read_b128 v[136:139], v233 offset:2048
	ds_read_b128 v[140:143], v233 offset:3072
	ds_read_b128 v[144:147], v234
	ds_read_b128 v[148:151], v234 offset:1024
	ds_read_b128 v[152:155], v234 offset:2048
	ds_read_b128 v[156:159], v234 offset:3072
	s_add_u32 s40, s38, 0xfffc0080
	s_addc_u32 s41, s39, -1
	s_cmp_eq_u32 s66, 12
	s_cselect_b32 s43, s23, s41
	s_cselect_b32 s42, s31, s40
	s_cselect_b32 s41, s25, s65
	s_cselect_b32 s40, s37, s64
	v_lshl_add_u64 v[208:209], s[38:39], 0, v[192:193]
	s_add_i32 m0, s50, 0xc000
	ds_read_b128 v[160:163], v235
	ds_read_b128 v[164:167], v235 offset:1024
	ds_read_b128 v[168:171], v235 offset:2048
	ds_read_b128 v[172:175], v235 offset:3072
	ds_read_b128 v[176:179], v235 offset:4096
	ds_read_b128 v[180:183], v235 offset:5120
	ds_read_b128 v[200:203], v235 offset:6144
	ds_read_b128 v[204:207], v235 offset:7168
	global_load_lds_dwordx4 v[208:209], off
	s_add_i32 m0, s50, 0xe000
	v_lshl_add_u64 v[208:209], s[38:39], 0, v[194:195]
	global_load_lds_dwordx4 v[208:209], off
	s_waitcnt vmcnt(8)
	s_waitcnt lgkmcnt(0)
	s_barrier
	s_setprio 1
	s_waitcnt lgkmcnt(0)
	v_mfma_f32_16x16x32_bf16 v[128:131], v[120:123], v[160:163], v[128:131]
	v_mfma_f32_16x16x32_bf16 v[124:127], v[136:139], v[160:163], v[124:127]
	v_mfma_f32_16x16x32_bf16 v[108:111], v[120:123], v[168:171], v[108:111]
	v_mfma_f32_16x16x32_bf16 v[104:107], v[136:139], v[168:171], v[104:107]
	v_mfma_f32_16x16x32_bf16 v[92:95], v[120:123], v[176:179], v[92:95]
	v_mfma_f32_16x16x32_bf16 v[88:91], v[136:139], v[176:179], v[88:91]
	v_mfma_f32_16x16x32_bf16 v[76:79], v[120:123], v[200:203], v[76:79]
	v_mfma_f32_16x16x32_bf16 v[72:75], v[136:139], v[200:203], v[72:75]
	v_mfma_f32_16x16x32_bf16 v[128:131], v[132:135], v[164:167], v[128:131]
	v_mfma_f32_16x16x32_bf16 v[124:127], v[140:143], v[164:167], v[124:127]
	v_mfma_f32_16x16x32_bf16 v[108:111], v[132:135], v[172:175], v[108:111]
	v_mfma_f32_16x16x32_bf16 v[104:107], v[140:143], v[172:175], v[104:107]
	v_mfma_f32_16x16x32_bf16 v[92:95], v[132:135], v[180:183], v[92:95]
	v_mfma_f32_16x16x32_bf16 v[88:91], v[140:143], v[180:183], v[88:91]
	v_mfma_f32_16x16x32_bf16 v[76:79], v[132:135], v[204:207], v[76:79]
	v_mfma_f32_16x16x32_bf16 v[72:75], v[140:143], v[204:207], v[72:75]
	s_setprio 0
	s_setprio 1
	v_mfma_f32_16x16x32_bf16 v[116:119], v[144:147], v[160:163], v[116:119]
	v_mfma_f32_16x16x32_bf16 v[112:115], v[152:155], v[160:163], v[112:115]
	v_mfma_f32_16x16x32_bf16 v[100:103], v[144:147], v[168:171], v[100:103]
	v_mfma_f32_16x16x32_bf16 v[96:99], v[152:155], v[168:171], v[96:99]
	v_mfma_f32_16x16x32_bf16 v[84:87], v[144:147], v[176:179], v[84:87]
	v_mfma_f32_16x16x32_bf16 v[80:83], v[152:155], v[176:179], v[80:83]
	v_mfma_f32_16x16x32_bf16 v[68:71], v[144:147], v[200:203], v[68:71]
	v_mfma_f32_16x16x32_bf16 v[64:67], v[152:155], v[200:203], v[64:67]
	v_mfma_f32_16x16x32_bf16 v[116:119], v[148:151], v[164:167], v[116:119]
	v_mfma_f32_16x16x32_bf16 v[112:115], v[156:159], v[164:167], v[112:115]
	v_mfma_f32_16x16x32_bf16 v[100:103], v[148:151], v[172:175], v[100:103]
	v_mfma_f32_16x16x32_bf16 v[96:99], v[156:159], v[172:175], v[96:99]
	s_setprio 2
	s_barrier
	v_mfma_f32_16x16x32_bf16 v[84:87], v[148:151], v[180:183], v[84:87]
	v_mfma_f32_16x16x32_bf16 v[80:83], v[156:159], v[180:183], v[80:83]
	v_mfma_f32_16x16x32_bf16 v[68:71], v[148:151], v[204:207], v[68:71]
	v_mfma_f32_16x16x32_bf16 v[64:67], v[156:159], v[204:207], v[64:67]
	s_setprio 2
	s_add_i32 s67, s62, s49
	v_lshl_add_u64 v[208:209], s[40:41], 0, v[186:187]
	s_mov_b32 m0, s67
	ds_read_b128 v[160:163], v235 offset:16384
	ds_read_b128 v[164:167], v235 offset:17408
	ds_read_b128 v[168:171], v235 offset:18432
	ds_read_b128 v[172:175], v235 offset:19456
	ds_read_b128 v[176:179], v235 offset:20480
	ds_read_b128 v[180:183], v235 offset:21504
	ds_read_b128 v[200:203], v235 offset:22528
	ds_read_b128 v[204:207], v235 offset:23552
	global_load_lds_dwordx4 v[208:209], off
	s_add_i32 m0, s67, 0x2000
	s_add_u32 s68, s40, 0x40000
	v_lshl_add_u64 v[210:211], s[40:41], 0, v[190:191]
	s_addc_u32 s69, s41, 0
	s_add_i32 s67, s63, s49
	global_load_lds_dwordx4 v[210:211], off
	v_lshl_add_u64 v[212:213], s[68:69], 0, v[186:187]
	s_mov_b32 m0, s67
	v_lshl_add_u64 v[214:215], s[42:43], 0, v[188:189]
	global_load_lds_dwordx4 v[212:213], off
	s_add_i32 m0, s67, 0x2000
	v_lshl_add_u64 v[212:213], s[68:69], 0, v[190:191]
	global_load_lds_dwordx4 v[212:213], off
	s_mov_b32 m0, s50
	v_lshl_add_u64 v[212:213], s[42:43], 0, v[184:185]
	global_load_lds_dwordx4 v[212:213], off
	s_mov_b32 m0, s51
	s_nop 0
	global_load_lds_dwordx4 v[214:215], off
	s_waitcnt vmcnt(8)
	s_waitcnt lgkmcnt(0)
	s_barrier
	s_setprio 1
	s_waitcnt lgkmcnt(0)
	v_mfma_f32_16x16x32_bf16 v[60:63], v[120:123], v[160:163], v[60:63]
	v_mfma_f32_16x16x32_bf16 v[56:59], v[136:139], v[160:163], v[56:59]
	v_mfma_f32_16x16x32_bf16 v[44:47], v[120:123], v[168:171], v[44:47]
	v_mfma_f32_16x16x32_bf16 v[40:43], v[136:139], v[168:171], v[40:43]
	v_mfma_f32_16x16x32_bf16 v[28:31], v[120:123], v[176:179], v[28:31]
	v_mfma_f32_16x16x32_bf16 v[24:27], v[136:139], v[176:179], v[24:27]
	v_mfma_f32_16x16x32_bf16 v[12:15], v[120:123], v[200:203], v[12:15]
	v_mfma_f32_16x16x32_bf16 v[8:11], v[136:139], v[200:203], v[8:11]
	v_mfma_f32_16x16x32_bf16 v[60:63], v[132:135], v[164:167], v[60:63]
	v_mfma_f32_16x16x32_bf16 v[56:59], v[140:143], v[164:167], v[56:59]
	v_mfma_f32_16x16x32_bf16 v[44:47], v[132:135], v[172:175], v[44:47]
	v_mfma_f32_16x16x32_bf16 v[40:43], v[140:143], v[172:175], v[40:43]
	v_mfma_f32_16x16x32_bf16 v[28:31], v[132:135], v[180:183], v[28:31]
	v_mfma_f32_16x16x32_bf16 v[24:27], v[140:143], v[180:183], v[24:27]
	v_mfma_f32_16x16x32_bf16 v[12:15], v[132:135], v[204:207], v[12:15]
	v_mfma_f32_16x16x32_bf16 v[8:11], v[140:143], v[204:207], v[8:11]
	s_setprio 0
	s_setprio 1
	v_mfma_f32_16x16x32_bf16 v[52:55], v[144:147], v[160:163], v[52:55]
	v_mfma_f32_16x16x32_bf16 v[48:51], v[152:155], v[160:163], v[48:51]
	v_mfma_f32_16x16x32_bf16 v[36:39], v[144:147], v[168:171], v[36:39]
	v_mfma_f32_16x16x32_bf16 v[32:35], v[152:155], v[168:171], v[32:35]
	v_mfma_f32_16x16x32_bf16 v[20:23], v[144:147], v[176:179], v[20:23]
	v_mfma_f32_16x16x32_bf16 v[16:19], v[152:155], v[176:179], v[16:19]
	v_mfma_f32_16x16x32_bf16 v[4:7], v[144:147], v[200:203], v[4:7]
	v_mfma_f32_16x16x32_bf16 v[0:3], v[152:155], v[200:203], v[0:3]
	v_mfma_f32_16x16x32_bf16 v[52:55], v[148:151], v[164:167], v[52:55]
	v_mfma_f32_16x16x32_bf16 v[48:51], v[156:159], v[164:167], v[48:51]
	v_mfma_f32_16x16x32_bf16 v[36:39], v[148:151], v[172:175], v[36:39]
	v_mfma_f32_16x16x32_bf16 v[32:35], v[156:159], v[172:175], v[32:35]
	s_setprio 2
	s_barrier
	v_mfma_f32_16x16x32_bf16 v[20:23], v[148:151], v[180:183], v[20:23]
	v_mfma_f32_16x16x32_bf16 v[16:19], v[156:159], v[180:183], v[16:19]
	v_mfma_f32_16x16x32_bf16 v[4:7], v[148:151], v[204:207], v[4:7]
	v_mfma_f32_16x16x32_bf16 v[0:3], v[156:159], v[204:207], v[0:3]
	s_setprio 0
	s_add_i32 s67, 0, 0x18000
	s_add_i32 s68, 0, 0x1c000
	v_add_u32_e32 v140, s67, v232
	v_add_u32_e32 v156, s68, v232
	ds_read_b128 v[120:123], v140
	ds_read_b128 v[132:135], v140 offset:1024
	ds_read_b128 v[136:139], v140 offset:2048
	ds_read_b128 v[140:143], v140 offset:3072
	ds_read_b128 v[144:147], v156
	ds_read_b128 v[148:151], v156 offset:1024
	ds_read_b128 v[152:155], v156 offset:2048
	ds_read_b128 v[156:159], v156 offset:3072
	s_add_u32 s42, s42, 0x40000
	s_addc_u32 s43, s43, 0
	s_mov_b32 m0, s54
	v_lshl_add_u64 v[216:217], s[42:43], 0, v[184:185]
	ds_read_b128 v[160:163], v235 offset:32768
	ds_read_b128 v[164:167], v235 offset:33792
	ds_read_b128 v[168:171], v235 offset:34816
	ds_read_b128 v[172:175], v235 offset:35840
	ds_read_b128 v[176:179], v235 offset:36864
	ds_read_b128 v[180:183], v235 offset:37888
	ds_read_b128 v[200:203], v235 offset:38912
	ds_read_b128 v[204:207], v235 offset:39936
	global_load_lds_dwordx4 v[216:217], off
	s_mov_b32 m0, s55
	v_lshl_add_u64 v[216:217], s[42:43], 0, v[188:189]
	global_load_lds_dwordx4 v[216:217], off
	s_waitcnt vmcnt(8)
	s_waitcnt lgkmcnt(0)
	s_barrier
	s_setprio 1
	s_waitcnt lgkmcnt(0)
	v_mfma_f32_16x16x32_bf16 v[128:131], v[120:123], v[160:163], v[128:131]
	v_mfma_f32_16x16x32_bf16 v[124:127], v[136:139], v[160:163], v[124:127]
	v_mfma_f32_16x16x32_bf16 v[108:111], v[120:123], v[168:171], v[108:111]
	v_mfma_f32_16x16x32_bf16 v[104:107], v[136:139], v[168:171], v[104:107]
	v_mfma_f32_16x16x32_bf16 v[92:95], v[120:123], v[176:179], v[92:95]
	v_mfma_f32_16x16x32_bf16 v[88:91], v[136:139], v[176:179], v[88:91]
	v_mfma_f32_16x16x32_bf16 v[76:79], v[120:123], v[200:203], v[76:79]
	v_mfma_f32_16x16x32_bf16 v[72:75], v[136:139], v[200:203], v[72:75]
	v_mfma_f32_16x16x32_bf16 v[128:131], v[132:135], v[164:167], v[128:131]
	v_mfma_f32_16x16x32_bf16 v[124:127], v[140:143], v[164:167], v[124:127]
	v_mfma_f32_16x16x32_bf16 v[108:111], v[132:135], v[172:175], v[108:111]
	v_mfma_f32_16x16x32_bf16 v[104:107], v[140:143], v[172:175], v[104:107]
	v_mfma_f32_16x16x32_bf16 v[92:95], v[132:135], v[180:183], v[92:95]
	v_mfma_f32_16x16x32_bf16 v[88:91], v[140:143], v[180:183], v[88:91]
	v_mfma_f32_16x16x32_bf16 v[76:79], v[132:135], v[204:207], v[76:79]
	v_mfma_f32_16x16x32_bf16 v[72:75], v[140:143], v[204:207], v[72:75]
	s_setprio 0
	s_setprio 1
	v_mfma_f32_16x16x32_bf16 v[116:119], v[144:147], v[160:163], v[116:119]
	v_mfma_f32_16x16x32_bf16 v[112:115], v[152:155], v[160:163], v[112:115]
	v_mfma_f32_16x16x32_bf16 v[100:103], v[144:147], v[168:171], v[100:103]
	v_mfma_f32_16x16x32_bf16 v[96:99], v[152:155], v[168:171], v[96:99]
	v_mfma_f32_16x16x32_bf16 v[84:87], v[144:147], v[176:179], v[84:87]
	v_mfma_f32_16x16x32_bf16 v[80:83], v[152:155], v[176:179], v[80:83]
	v_mfma_f32_16x16x32_bf16 v[68:71], v[144:147], v[200:203], v[68:71]
	v_mfma_f32_16x16x32_bf16 v[64:67], v[152:155], v[200:203], v[64:67]
	v_mfma_f32_16x16x32_bf16 v[116:119], v[148:151], v[164:167], v[116:119]
	v_mfma_f32_16x16x32_bf16 v[112:115], v[156:159], v[164:167], v[112:115]
	v_mfma_f32_16x16x32_bf16 v[100:103], v[148:151], v[172:175], v[100:103]
	v_mfma_f32_16x16x32_bf16 v[96:99], v[156:159], v[172:175], v[96:99]
	s_setprio 2
	s_barrier
	v_mfma_f32_16x16x32_bf16 v[84:87], v[148:151], v[180:183], v[84:87]
	v_mfma_f32_16x16x32_bf16 v[80:83], v[156:159], v[180:183], v[80:83]
	v_mfma_f32_16x16x32_bf16 v[68:71], v[148:151], v[204:207], v[68:71]
	v_mfma_f32_16x16x32_bf16 v[64:67], v[156:159], v[204:207], v[64:67]
	s_setprio 2
	s_add_i32 s42, s67, s49
	v_lshl_add_u64 v[208:209], v[208:209], 0, s[18:19]
	s_mov_b32 m0, s42
	ds_read_b128 v[160:163], v235 offset:49152
	ds_read_b128 v[164:167], v235 offset:50176
	ds_read_b128 v[168:171], v235 offset:51200
	ds_read_b128 v[172:175], v235 offset:52224
	ds_read_b128 v[176:179], v235 offset:53248
	ds_read_b128 v[180:183], v235 offset:54272
	ds_read_b128 v[200:203], v235 offset:55296
	ds_read_b128 v[204:207], v235 offset:56320
	global_load_lds_dwordx4 v[208:209], off
	s_add_i32 m0, s42, 0x2000
	s_add_u32 s40, s40, 0x40080
	v_lshl_add_u64 v[208:209], v[210:211], 0, s[18:19]
	s_addc_u32 s41, s41, 0
	s_add_i32 s42, s68, s49
	global_load_lds_dwordx4 v[208:209], off
	s_mov_b32 m0, s42
	v_lshl_add_u64 v[208:209], s[40:41], 0, v[186:187]
	global_load_lds_dwordx4 v[208:209], off
	s_add_i32 m0, s42, 0x2000
	v_lshl_add_u64 v[208:209], s[40:41], 0, v[190:191]
	global_load_lds_dwordx4 v[208:209], off
	s_mov_b32 m0, s57
	v_lshl_add_u64 v[208:209], v[212:213], 0, s[18:19]
	global_load_lds_dwordx4 v[208:209], off
	s_mov_b32 m0, s58
	v_lshl_add_u64 v[208:209], v[214:215], 0, s[18:19]
	global_load_lds_dwordx4 v[208:209], off
	s_waitcnt vmcnt(8)
	s_waitcnt lgkmcnt(0)
	s_barrier
	s_setprio 1
	s_waitcnt lgkmcnt(0)
	v_mfma_f32_16x16x32_bf16 v[60:63], v[120:123], v[160:163], v[60:63]
	v_mfma_f32_16x16x32_bf16 v[56:59], v[136:139], v[160:163], v[56:59]
	v_mfma_f32_16x16x32_bf16 v[44:47], v[120:123], v[168:171], v[44:47]
	v_mfma_f32_16x16x32_bf16 v[40:43], v[136:139], v[168:171], v[40:43]
	v_mfma_f32_16x16x32_bf16 v[28:31], v[120:123], v[176:179], v[28:31]
	v_mfma_f32_16x16x32_bf16 v[24:27], v[136:139], v[176:179], v[24:27]
	v_mfma_f32_16x16x32_bf16 v[12:15], v[120:123], v[200:203], v[12:15]
	v_mfma_f32_16x16x32_bf16 v[8:11], v[136:139], v[200:203], v[8:11]
	v_mfma_f32_16x16x32_bf16 v[60:63], v[132:135], v[164:167], v[60:63]
	v_mfma_f32_16x16x32_bf16 v[56:59], v[140:143], v[164:167], v[56:59]
	v_mfma_f32_16x16x32_bf16 v[44:47], v[132:135], v[172:175], v[44:47]
	v_mfma_f32_16x16x32_bf16 v[40:43], v[140:143], v[172:175], v[40:43]
	v_mfma_f32_16x16x32_bf16 v[28:31], v[132:135], v[180:183], v[28:31]
	v_mfma_f32_16x16x32_bf16 v[24:27], v[140:143], v[180:183], v[24:27]
	v_mfma_f32_16x16x32_bf16 v[12:15], v[132:135], v[204:207], v[12:15]
	v_mfma_f32_16x16x32_bf16 v[8:11], v[140:143], v[204:207], v[8:11]
	s_setprio 0
	s_setprio 1
	v_mfma_f32_16x16x32_bf16 v[52:55], v[144:147], v[160:163], v[52:55]
	v_mfma_f32_16x16x32_bf16 v[48:51], v[152:155], v[160:163], v[48:51]
	v_mfma_f32_16x16x32_bf16 v[36:39], v[144:147], v[168:171], v[36:39]
	v_mfma_f32_16x16x32_bf16 v[32:35], v[152:155], v[168:171], v[32:35]
	v_mfma_f32_16x16x32_bf16 v[20:23], v[144:147], v[176:179], v[20:23]
	v_mfma_f32_16x16x32_bf16 v[16:19], v[152:155], v[176:179], v[16:19]
	v_mfma_f32_16x16x32_bf16 v[4:7], v[144:147], v[200:203], v[4:7]
	v_mfma_f32_16x16x32_bf16 v[0:3], v[152:155], v[200:203], v[0:3]
	v_mfma_f32_16x16x32_bf16 v[52:55], v[148:151], v[164:167], v[52:55]
	v_mfma_f32_16x16x32_bf16 v[48:51], v[156:159], v[164:167], v[48:51]
	v_mfma_f32_16x16x32_bf16 v[36:39], v[148:151], v[172:175], v[36:39]
	v_mfma_f32_16x16x32_bf16 v[32:35], v[156:159], v[172:175], v[32:35]
	s_setprio 2
	s_barrier
	v_mfma_f32_16x16x32_bf16 v[20:23], v[148:151], v[180:183], v[20:23]
	v_mfma_f32_16x16x32_bf16 v[16:19], v[156:159], v[180:183], v[16:19]
	v_mfma_f32_16x16x32_bf16 v[4:7], v[148:151], v[204:207], v[4:7]
	v_mfma_f32_16x16x32_bf16 v[0:3], v[156:159], v[204:207], v[0:3]
	s_setprio 0
	s_add_i32 s66, s66, 2
	s_add_u32 s38, s38, 0x100
	s_addc_u32 s39, s39, 0
	s_add_u32 s64, s64, 0x100
	s_addc_u32 s65, s65, 0
	s_cmp_gt_u32 s66, 13
	s_cbranch_scc0 .LBB0_1146

.LBB0_1309:
	s_add_u32 s51, s26, 0x100
	s_addc_u32 s52, s27, 0
	s_mov_b32 s53, -2
	ds_read_b128 v[128:131], v197
	ds_read_b128 v[132:135], v197 offset:1024
	ds_read_b128 v[136:139], v197 offset:2048
	ds_read_b128 v[140:143], v197 offset:3072
	ds_read_b128 v[144:147], v198
	ds_read_b128 v[148:151], v198 offset:1024
	ds_read_b128 v[152:155], v198 offset:2048
	ds_read_b128 v[156:159], v198 offset:3072
	s_add_u32 s4, s24, 0x100
	s_addc_u32 s5, s25, 0
	s_cmp_eq_u32 s53, 40
	s_cselect_b32 s29, s21, s5
	s_cselect_b32 s28, s20, s4
	s_cselect_b32 s27, s23, s52
	s_cselect_b32 s26, s22, s51
	v_lshl_add_u64 v[212:213], s[24:25], 0, v[172:173]
	s_add_i32 m0, s36, 0xc000
	ds_read_b128 v[160:163], v199
	ds_read_b128 v[180:183], v199 offset:1024
	ds_read_b128 v[184:187], v199 offset:2048
	ds_read_b128 v[188:191], v199 offset:3072
	ds_read_b128 v[192:195], v199 offset:4096
	ds_read_b128 v[200:203], v199 offset:5120
	ds_read_b128 v[204:207], v199 offset:6144
	ds_read_b128 v[208:211], v199 offset:7168
	global_load_lds_dwordx4 v[212:213], off
	s_add_i32 m0, s36, 0xe000
	v_lshl_add_u64 v[212:213], s[24:25], 0, v[174:175]
	global_load_lds_dwordx4 v[212:213], off
	s_waitcnt vmcnt(8)
	s_waitcnt lgkmcnt(0)
	s_barrier
	s_setprio 1
	s_waitcnt lgkmcnt(0)
	v_mfma_f32_16x16x32_bf16 v[124:127], v[128:131], v[160:163], 0
	v_mfma_f32_16x16x32_bf16 v[120:123], v[136:139], v[160:163], 0
	v_mfma_f32_16x16x32_bf16 v[116:119], v[128:131], v[184:187], 0
	v_mfma_f32_16x16x32_bf16 v[108:111], v[136:139], v[184:187], 0
	v_mfma_f32_16x16x32_bf16 v[88:91], v[128:131], v[192:195], 0
	v_mfma_f32_16x16x32_bf16 v[100:103], v[136:139], v[192:195], 0
	v_mfma_f32_16x16x32_bf16 v[72:75], v[128:131], v[204:207], 0
	v_mfma_f32_16x16x32_bf16 v[76:79], v[136:139], v[204:207], 0
	v_mfma_f32_16x16x32_bf16 v[124:127], v[132:135], v[180:183], v[124:127]
	v_mfma_f32_16x16x32_bf16 v[120:123], v[140:143], v[180:183], v[120:123]
	v_mfma_f32_16x16x32_bf16 v[116:119], v[132:135], v[188:191], v[116:119]
	v_mfma_f32_16x16x32_bf16 v[108:111], v[140:143], v[188:191], v[108:111]
	v_mfma_f32_16x16x32_bf16 v[88:91], v[132:135], v[200:203], v[88:91]
	v_mfma_f32_16x16x32_bf16 v[100:103], v[140:143], v[200:203], v[100:103]
	v_mfma_f32_16x16x32_bf16 v[72:75], v[132:135], v[208:211], v[72:75]
	v_mfma_f32_16x16x32_bf16 v[76:79], v[140:143], v[208:211], v[76:79]
	s_setprio 0
	s_setprio 1
	v_mfma_f32_16x16x32_bf16 v[112:115], v[144:147], v[160:163], 0
	v_mfma_f32_16x16x32_bf16 v[104:107], v[152:155], v[160:163], 0
	v_mfma_f32_16x16x32_bf16 v[96:99], v[144:147], v[184:187], 0
	v_mfma_f32_16x16x32_bf16 v[92:95], v[152:155], v[184:187], 0
	v_mfma_f32_16x16x32_bf16 v[80:83], v[144:147], v[192:195], 0
	v_mfma_f32_16x16x32_bf16 v[84:87], v[152:155], v[192:195], 0
	v_mfma_f32_16x16x32_bf16 v[64:67], v[144:147], v[204:207], 0
	v_mfma_f32_16x16x32_bf16 v[68:71], v[152:155], v[204:207], 0
	v_mfma_f32_16x16x32_bf16 v[112:115], v[148:151], v[180:183], v[112:115]
	v_mfma_f32_16x16x32_bf16 v[104:107], v[156:159], v[180:183], v[104:107]
	v_mfma_f32_16x16x32_bf16 v[96:99], v[148:151], v[188:191], v[96:99]
	v_mfma_f32_16x16x32_bf16 v[92:95], v[156:159], v[188:191], v[92:95]
	s_setprio 2
	s_barrier
	v_mfma_f32_16x16x32_bf16 v[80:83], v[148:151], v[200:203], v[80:83]
	v_mfma_f32_16x16x32_bf16 v[84:87], v[156:159], v[200:203], v[84:87]
	v_mfma_f32_16x16x32_bf16 v[64:67], v[148:151], v[208:211], v[64:67]
	v_mfma_f32_16x16x32_bf16 v[68:71], v[156:159], v[208:211], v[68:71]
	s_setprio 2
	s_add_i32 s24, s45, s35
	v_lshl_add_u64 v[212:213], s[26:27], 0, v[166:167]
	s_mov_b32 m0, s24
	ds_read_b128 v[160:163], v199 offset:16384
	ds_read_b128 v[180:183], v199 offset:17408
	ds_read_b128 v[184:187], v199 offset:18432
	ds_read_b128 v[188:191], v199 offset:19456
	ds_read_b128 v[192:195], v199 offset:20480
	ds_read_b128 v[200:203], v199 offset:21504
	ds_read_b128 v[204:207], v199 offset:22528
	ds_read_b128 v[208:211], v199 offset:23552
	global_load_lds_dwordx4 v[212:213], off
	s_add_i32 m0, s24, 0x2000
	s_add_u32 s24, s26, 0xb0000
	v_lshl_add_u64 v[214:215], s[26:27], 0, v[170:171]
	s_addc_u32 s25, s27, 0
	s_add_i32 s54, s46, s35
	global_load_lds_dwordx4 v[214:215], off
	v_lshl_add_u64 v[216:217], s[24:25], 0, v[166:167]
	s_mov_b32 m0, s54
	v_lshl_add_u64 v[218:219], s[28:29], 0, v[168:169]
	global_load_lds_dwordx4 v[216:217], off
	s_add_i32 m0, s54, 0x2000
	v_lshl_add_u64 v[216:217], s[24:25], 0, v[170:171]
	global_load_lds_dwordx4 v[216:217], off
	s_mov_b32 m0, s36
	v_lshl_add_u64 v[216:217], s[28:29], 0, v[164:165]
	global_load_lds_dwordx4 v[216:217], off
	s_mov_b32 m0, s37
	s_nop 0
	global_load_lds_dwordx4 v[218:219], off
	s_waitcnt vmcnt(8)
	s_waitcnt lgkmcnt(0)
	s_barrier
	s_setprio 1
	s_waitcnt lgkmcnt(0)
	v_mfma_f32_16x16x32_bf16 v[56:59], v[128:131], v[160:163], 0
	v_mfma_f32_16x16x32_bf16 v[60:63], v[136:139], v[160:163], 0
	v_mfma_f32_16x16x32_bf16 v[40:43], v[128:131], v[184:187], 0
	v_mfma_f32_16x16x32_bf16 v[44:47], v[136:139], v[184:187], 0
	v_mfma_f32_16x16x32_bf16 v[24:27], v[128:131], v[192:195], 0
	v_mfma_f32_16x16x32_bf16 v[28:31], v[136:139], v[192:195], 0
	v_mfma_f32_16x16x32_bf16 v[8:11], v[128:131], v[204:207], 0
	v_mfma_f32_16x16x32_bf16 v[12:15], v[136:139], v[204:207], 0
	v_mfma_f32_16x16x32_bf16 v[56:59], v[132:135], v[180:183], v[56:59]
	v_mfma_f32_16x16x32_bf16 v[60:63], v[140:143], v[180:183], v[60:63]
	v_mfma_f32_16x16x32_bf16 v[40:43], v[132:135], v[188:191], v[40:43]
	v_mfma_f32_16x16x32_bf16 v[44:47], v[140:143], v[188:191], v[44:47]
	v_mfma_f32_16x16x32_bf16 v[24:27], v[132:135], v[200:203], v[24:27]
	v_mfma_f32_16x16x32_bf16 v[28:31], v[140:143], v[200:203], v[28:31]
	v_mfma_f32_16x16x32_bf16 v[8:11], v[132:135], v[208:211], v[8:11]
	v_mfma_f32_16x16x32_bf16 v[12:15], v[140:143], v[208:211], v[12:15]
	s_setprio 0
	s_setprio 1
	v_mfma_f32_16x16x32_bf16 v[48:51], v[144:147], v[160:163], 0
	v_mfma_f32_16x16x32_bf16 v[52:55], v[152:155], v[160:163], 0
	v_mfma_f32_16x16x32_bf16 v[32:35], v[144:147], v[184:187], 0
	v_mfma_f32_16x16x32_bf16 v[36:39], v[152:155], v[184:187], 0
	v_mfma_f32_16x16x32_bf16 v[16:19], v[144:147], v[192:195], 0
	v_mfma_f32_16x16x32_bf16 v[20:23], v[152:155], v[192:195], 0
	v_mfma_f32_16x16x32_bf16 v[0:3], v[144:147], v[204:207], 0
	v_mfma_f32_16x16x32_bf16 v[4:7], v[152:155], v[204:207], 0
	v_mfma_f32_16x16x32_bf16 v[48:51], v[148:151], v[180:183], v[48:51]
	v_mfma_f32_16x16x32_bf16 v[52:55], v[156:159], v[180:183], v[52:55]
	v_mfma_f32_16x16x32_bf16 v[32:35], v[148:151], v[188:191], v[32:35]
	v_mfma_f32_16x16x32_bf16 v[36:39], v[156:159], v[188:191], v[36:39]
	s_setprio 2
	s_barrier
	v_mfma_f32_16x16x32_bf16 v[16:19], v[148:151], v[200:203], v[16:19]
	v_mfma_f32_16x16x32_bf16 v[20:23], v[156:159], v[200:203], v[20:23]
	v_mfma_f32_16x16x32_bf16 v[0:3], v[148:151], v[208:211], v[0:3]
	v_mfma_f32_16x16x32_bf16 v[4:7], v[156:159], v[208:211], v[4:7]
	s_setprio 0
	s_add_i32 s54, 0, 0x18000
	s_add_i32 s55, 0, 0x1c000
	v_add_u32_e32 v140, s54, v196
	v_add_u32_e32 v156, s55, v196
	ds_read_b128 v[128:131], v140
	ds_read_b128 v[132:135], v140 offset:1024
	ds_read_b128 v[136:139], v140 offset:2048
	ds_read_b128 v[140:143], v140 offset:3072
	ds_read_b128 v[144:147], v156
	ds_read_b128 v[148:151], v156 offset:1024
	ds_read_b128 v[152:155], v156 offset:2048
	ds_read_b128 v[156:159], v156 offset:3072
	s_add_u32 s24, s28, 0xb0000
	s_addc_u32 s25, s29, 0
	s_mov_b32 m0, s38
	v_lshl_add_u64 v[220:221], s[24:25], 0, v[164:165]
	ds_read_b128 v[160:163], v199 offset:32768
	ds_read_b128 v[180:183], v199 offset:33792
	ds_read_b128 v[184:187], v199 offset:34816
	ds_read_b128 v[188:191], v199 offset:35840
	ds_read_b128 v[192:195], v199 offset:36864
	ds_read_b128 v[200:203], v199 offset:37888
	ds_read_b128 v[204:207], v199 offset:38912
	ds_read_b128 v[208:211], v199 offset:39936
	global_load_lds_dwordx4 v[220:221], off
	s_mov_b32 m0, s39
	v_lshl_add_u64 v[220:221], s[24:25], 0, v[168:169]
	global_load_lds_dwordx4 v[220:221], off
	s_waitcnt vmcnt(8)
	s_waitcnt lgkmcnt(0)
	s_barrier
	s_setprio 1
	s_waitcnt lgkmcnt(0)
	v_mfma_f32_16x16x32_bf16 v[124:127], v[128:131], v[160:163], v[124:127]
	v_mfma_f32_16x16x32_bf16 v[120:123], v[136:139], v[160:163], v[120:123]
	v_mfma_f32_16x16x32_bf16 v[116:119], v[128:131], v[184:187], v[116:119]
	v_mfma_f32_16x16x32_bf16 v[108:111], v[136:139], v[184:187], v[108:111]
	v_mfma_f32_16x16x32_bf16 v[88:91], v[128:131], v[192:195], v[88:91]
	v_mfma_f32_16x16x32_bf16 v[100:103], v[136:139], v[192:195], v[100:103]
	v_mfma_f32_16x16x32_bf16 v[72:75], v[128:131], v[204:207], v[72:75]
	v_mfma_f32_16x16x32_bf16 v[76:79], v[136:139], v[204:207], v[76:79]
	v_mfma_f32_16x16x32_bf16 v[124:127], v[132:135], v[180:183], v[124:127]
	v_mfma_f32_16x16x32_bf16 v[120:123], v[140:143], v[180:183], v[120:123]
	v_mfma_f32_16x16x32_bf16 v[116:119], v[132:135], v[188:191], v[116:119]
	v_mfma_f32_16x16x32_bf16 v[108:111], v[140:143], v[188:191], v[108:111]
	v_mfma_f32_16x16x32_bf16 v[88:91], v[132:135], v[200:203], v[88:91]
	v_mfma_f32_16x16x32_bf16 v[100:103], v[140:143], v[200:203], v[100:103]
	v_mfma_f32_16x16x32_bf16 v[72:75], v[132:135], v[208:211], v[72:75]
	v_mfma_f32_16x16x32_bf16 v[76:79], v[140:143], v[208:211], v[76:79]
	s_setprio 0
	s_setprio 1
	v_mfma_f32_16x16x32_bf16 v[112:115], v[144:147], v[160:163], v[112:115]
	v_mfma_f32_16x16x32_bf16 v[104:107], v[152:155], v[160:163], v[104:107]
	v_mfma_f32_16x16x32_bf16 v[96:99], v[144:147], v[184:187], v[96:99]
	v_mfma_f32_16x16x32_bf16 v[92:95], v[152:155], v[184:187], v[92:95]
	v_mfma_f32_16x16x32_bf16 v[80:83], v[144:147], v[192:195], v[80:83]
	v_mfma_f32_16x16x32_bf16 v[84:87], v[152:155], v[192:195], v[84:87]
	v_mfma_f32_16x16x32_bf16 v[64:67], v[144:147], v[204:207], v[64:67]
	v_mfma_f32_16x16x32_bf16 v[68:71], v[152:155], v[204:207], v[68:71]
	v_mfma_f32_16x16x32_bf16 v[112:115], v[148:151], v[180:183], v[112:115]
	v_mfma_f32_16x16x32_bf16 v[104:107], v[156:159], v[180:183], v[104:107]
	v_mfma_f32_16x16x32_bf16 v[96:99], v[148:151], v[188:191], v[96:99]
	v_mfma_f32_16x16x32_bf16 v[92:95], v[156:159], v[188:191], v[92:95]
	s_setprio 2
	s_barrier
	v_mfma_f32_16x16x32_bf16 v[80:83], v[148:151], v[200:203], v[80:83]
	v_mfma_f32_16x16x32_bf16 v[84:87], v[156:159], v[200:203], v[84:87]
	v_mfma_f32_16x16x32_bf16 v[64:67], v[148:151], v[208:211], v[64:67]
	v_mfma_f32_16x16x32_bf16 v[68:71], v[156:159], v[208:211], v[68:71]
	s_setprio 2
	s_add_i32 s24, s54, s35
	v_lshl_add_u64 v[212:213], v[212:213], 0, s[16:17]
	s_mov_b32 m0, s24
	ds_read_b128 v[160:163], v199 offset:49152
	ds_read_b128 v[180:183], v199 offset:50176
	ds_read_b128 v[184:187], v199 offset:51200
	ds_read_b128 v[188:191], v199 offset:52224
	ds_read_b128 v[192:195], v199 offset:53248
	ds_read_b128 v[200:203], v199 offset:54272
	ds_read_b128 v[204:207], v199 offset:55296
	ds_read_b128 v[208:211], v199 offset:56320
	global_load_lds_dwordx4 v[212:213], off
	s_add_i32 m0, s24, 0x2000
	s_add_u32 s24, s26, 0xb0080
	v_lshl_add_u64 v[212:213], v[214:215], 0, s[16:17]
	s_addc_u32 s25, s27, 0
	s_add_i32 s26, s55, s35
	global_load_lds_dwordx4 v[212:213], off
	s_mov_b32 m0, s26
	v_lshl_add_u64 v[212:213], s[24:25], 0, v[166:167]
	global_load_lds_dwordx4 v[212:213], off
	s_add_i32 m0, s26, 0x2000
	v_lshl_add_u64 v[212:213], s[24:25], 0, v[170:171]
	global_load_lds_dwordx4 v[212:213], off
	s_mov_b32 m0, s41
	v_lshl_add_u64 v[212:213], v[216:217], 0, s[16:17]
	global_load_lds_dwordx4 v[212:213], off
	s_mov_b32 m0, s42
	v_lshl_add_u64 v[212:213], v[218:219], 0, s[16:17]
	global_load_lds_dwordx4 v[212:213], off
	s_waitcnt vmcnt(8)
	s_waitcnt lgkmcnt(0)
	s_barrier
	s_setprio 1
	s_waitcnt lgkmcnt(0)
	v_mfma_f32_16x16x32_bf16 v[56:59], v[128:131], v[160:163], v[56:59]
	v_mfma_f32_16x16x32_bf16 v[60:63], v[136:139], v[160:163], v[60:63]
	v_mfma_f32_16x16x32_bf16 v[40:43], v[128:131], v[184:187], v[40:43]
	v_mfma_f32_16x16x32_bf16 v[44:47], v[136:139], v[184:187], v[44:47]
	v_mfma_f32_16x16x32_bf16 v[24:27], v[128:131], v[192:195], v[24:27]
	v_mfma_f32_16x16x32_bf16 v[28:31], v[136:139], v[192:195], v[28:31]
	v_mfma_f32_16x16x32_bf16 v[8:11], v[128:131], v[204:207], v[8:11]
	v_mfma_f32_16x16x32_bf16 v[12:15], v[136:139], v[204:207], v[12:15]
	v_mfma_f32_16x16x32_bf16 v[56:59], v[132:135], v[180:183], v[56:59]
	v_mfma_f32_16x16x32_bf16 v[60:63], v[140:143], v[180:183], v[60:63]
	v_mfma_f32_16x16x32_bf16 v[40:43], v[132:135], v[188:191], v[40:43]
	v_mfma_f32_16x16x32_bf16 v[44:47], v[140:143], v[188:191], v[44:47]
	v_mfma_f32_16x16x32_bf16 v[24:27], v[132:135], v[200:203], v[24:27]
	v_mfma_f32_16x16x32_bf16 v[28:31], v[140:143], v[200:203], v[28:31]
	v_mfma_f32_16x16x32_bf16 v[8:11], v[132:135], v[208:211], v[8:11]
	v_mfma_f32_16x16x32_bf16 v[12:15], v[140:143], v[208:211], v[12:15]
	s_setprio 0
	s_setprio 1
	v_mfma_f32_16x16x32_bf16 v[48:51], v[144:147], v[160:163], v[48:51]
	v_mfma_f32_16x16x32_bf16 v[52:55], v[152:155], v[160:163], v[52:55]
	v_mfma_f32_16x16x32_bf16 v[32:35], v[144:147], v[184:187], v[32:35]
	v_mfma_f32_16x16x32_bf16 v[36:39], v[152:155], v[184:187], v[36:39]
	v_mfma_f32_16x16x32_bf16 v[16:19], v[144:147], v[192:195], v[16:19]
	v_mfma_f32_16x16x32_bf16 v[20:23], v[152:155], v[192:195], v[20:23]
	v_mfma_f32_16x16x32_bf16 v[0:3], v[144:147], v[204:207], v[0:3]
	v_mfma_f32_16x16x32_bf16 v[4:7], v[152:155], v[204:207], v[4:7]
	v_mfma_f32_16x16x32_bf16 v[48:51], v[148:151], v[180:183], v[48:51]
	v_mfma_f32_16x16x32_bf16 v[52:55], v[156:159], v[180:183], v[52:55]
	v_mfma_f32_16x16x32_bf16 v[32:35], v[148:151], v[188:191], v[32:35]
	v_mfma_f32_16x16x32_bf16 v[36:39], v[156:159], v[188:191], v[36:39]
	s_setprio 2
	s_barrier
	v_mfma_f32_16x16x32_bf16 v[16:19], v[148:151], v[200:203], v[16:19]
	v_mfma_f32_16x16x32_bf16 v[20:23], v[156:159], v[200:203], v[20:23]
	v_mfma_f32_16x16x32_bf16 v[0:3], v[148:151], v[208:211], v[0:3]
	v_mfma_f32_16x16x32_bf16 v[4:7], v[156:159], v[208:211], v[4:7]
	s_setprio 0
	s_add_i32 s53, s53, 2
	s_add_u32 s51, s51, 0x100
	s_addc_u32 s52, s52, 0
	s_cmp_gt_u32 s53, 41
	s_mov_b64 s[24:25], s[4:5]
.LBB0_1310:
	ds_read_b128 v[128:131], v197
	ds_read_b128 v[132:135], v197 offset:1024
	ds_read_b128 v[136:139], v197 offset:2048
	ds_read_b128 v[140:143], v197 offset:3072
	ds_read_b128 v[144:147], v198
	ds_read_b128 v[148:151], v198 offset:1024
	ds_read_b128 v[152:155], v198 offset:2048
	ds_read_b128 v[156:159], v198 offset:3072
	s_add_u32 s4, s24, 0x100
	s_addc_u32 s5, s25, 0
	s_cmp_eq_u32 s53, 40
	s_cselect_b32 s29, s21, s5
	s_cselect_b32 s28, s20, s4
	s_cselect_b32 s27, s23, s52
	s_cselect_b32 s26, s22, s51
	v_lshl_add_u64 v[212:213], s[24:25], 0, v[172:173]
	s_add_i32 m0, s36, 0xc000
	ds_read_b128 v[160:163], v199
	ds_read_b128 v[180:183], v199 offset:1024
	ds_read_b128 v[184:187], v199 offset:2048
	ds_read_b128 v[188:191], v199 offset:3072
	ds_read_b128 v[192:195], v199 offset:4096
	ds_read_b128 v[200:203], v199 offset:5120
	ds_read_b128 v[204:207], v199 offset:6144
	ds_read_b128 v[208:211], v199 offset:7168
	global_load_lds_dwordx4 v[212:213], off
	s_add_i32 m0, s36, 0xe000
	v_lshl_add_u64 v[212:213], s[24:25], 0, v[174:175]
	global_load_lds_dwordx4 v[212:213], off
	s_waitcnt vmcnt(8)
	s_waitcnt lgkmcnt(0)
	s_barrier
	s_setprio 1
	s_waitcnt lgkmcnt(0)
	v_mfma_f32_16x16x32_bf16 v[124:127], v[128:131], v[160:163], v[124:127]
	v_mfma_f32_16x16x32_bf16 v[120:123], v[136:139], v[160:163], v[120:123]
	v_mfma_f32_16x16x32_bf16 v[116:119], v[128:131], v[184:187], v[116:119]
	v_mfma_f32_16x16x32_bf16 v[108:111], v[136:139], v[184:187], v[108:111]
	v_mfma_f32_16x16x32_bf16 v[88:91], v[128:131], v[192:195], v[88:91]
	v_mfma_f32_16x16x32_bf16 v[100:103], v[136:139], v[192:195], v[100:103]
	v_mfma_f32_16x16x32_bf16 v[72:75], v[128:131], v[204:207], v[72:75]
	v_mfma_f32_16x16x32_bf16 v[76:79], v[136:139], v[204:207], v[76:79]
	v_mfma_f32_16x16x32_bf16 v[124:127], v[132:135], v[180:183], v[124:127]
	v_mfma_f32_16x16x32_bf16 v[120:123], v[140:143], v[180:183], v[120:123]
	v_mfma_f32_16x16x32_bf16 v[116:119], v[132:135], v[188:191], v[116:119]
	v_mfma_f32_16x16x32_bf16 v[108:111], v[140:143], v[188:191], v[108:111]
	v_mfma_f32_16x16x32_bf16 v[88:91], v[132:135], v[200:203], v[88:91]
	v_mfma_f32_16x16x32_bf16 v[100:103], v[140:143], v[200:203], v[100:103]
	v_mfma_f32_16x16x32_bf16 v[72:75], v[132:135], v[208:211], v[72:75]
	v_mfma_f32_16x16x32_bf16 v[76:79], v[140:143], v[208:211], v[76:79]
	s_setprio 0
	s_setprio 1
	v_mfma_f32_16x16x32_bf16 v[112:115], v[144:147], v[160:163], v[112:115]
	v_mfma_f32_16x16x32_bf16 v[104:107], v[152:155], v[160:163], v[104:107]
	v_mfma_f32_16x16x32_bf16 v[96:99], v[144:147], v[184:187], v[96:99]
	v_mfma_f32_16x16x32_bf16 v[92:95], v[152:155], v[184:187], v[92:95]
	v_mfma_f32_16x16x32_bf16 v[80:83], v[144:147], v[192:195], v[80:83]
	v_mfma_f32_16x16x32_bf16 v[84:87], v[152:155], v[192:195], v[84:87]
	v_mfma_f32_16x16x32_bf16 v[64:67], v[144:147], v[204:207], v[64:67]
	v_mfma_f32_16x16x32_bf16 v[68:71], v[152:155], v[204:207], v[68:71]
	v_mfma_f32_16x16x32_bf16 v[112:115], v[148:151], v[180:183], v[112:115]
	v_mfma_f32_16x16x32_bf16 v[104:107], v[156:159], v[180:183], v[104:107]
	v_mfma_f32_16x16x32_bf16 v[96:99], v[148:151], v[188:191], v[96:99]
	v_mfma_f32_16x16x32_bf16 v[92:95], v[156:159], v[188:191], v[92:95]
	s_setprio 2
	s_barrier
	v_mfma_f32_16x16x32_bf16 v[80:83], v[148:151], v[200:203], v[80:83]
	v_mfma_f32_16x16x32_bf16 v[84:87], v[156:159], v[200:203], v[84:87]
	v_mfma_f32_16x16x32_bf16 v[64:67], v[148:151], v[208:211], v[64:67]
	v_mfma_f32_16x16x32_bf16 v[68:71], v[156:159], v[208:211], v[68:71]
	s_setprio 2
	s_add_i32 s24, s45, s35
	v_lshl_add_u64 v[212:213], s[26:27], 0, v[166:167]
	s_mov_b32 m0, s24
	ds_read_b128 v[160:163], v199 offset:16384
	ds_read_b128 v[180:183], v199 offset:17408
	ds_read_b128 v[184:187], v199 offset:18432
	ds_read_b128 v[188:191], v199 offset:19456
	ds_read_b128 v[192:195], v199 offset:20480
	ds_read_b128 v[200:203], v199 offset:21504
	ds_read_b128 v[204:207], v199 offset:22528
	ds_read_b128 v[208:211], v199 offset:23552
	global_load_lds_dwordx4 v[212:213], off
	s_add_i32 m0, s24, 0x2000
	s_add_u32 s24, s26, 0xb0000
	v_lshl_add_u64 v[214:215], s[26:27], 0, v[170:171]
	s_addc_u32 s25, s27, 0
	s_add_i32 s54, s46, s35
	global_load_lds_dwordx4 v[214:215], off
	v_lshl_add_u64 v[216:217], s[24:25], 0, v[166:167]
	s_mov_b32 m0, s54
	v_lshl_add_u64 v[218:219], s[28:29], 0, v[168:169]
	global_load_lds_dwordx4 v[216:217], off
	s_add_i32 m0, s54, 0x2000
	v_lshl_add_u64 v[216:217], s[24:25], 0, v[170:171]
	global_load_lds_dwordx4 v[216:217], off
	s_mov_b32 m0, s36
	v_lshl_add_u64 v[216:217], s[28:29], 0, v[164:165]
	global_load_lds_dwordx4 v[216:217], off
	s_mov_b32 m0, s37
	s_nop 0
	global_load_lds_dwordx4 v[218:219], off
	s_waitcnt vmcnt(8)
	s_waitcnt lgkmcnt(0)
	s_barrier
	s_setprio 1
	s_waitcnt lgkmcnt(0)
	v_mfma_f32_16x16x32_bf16 v[56:59], v[128:131], v[160:163], v[56:59]
	v_mfma_f32_16x16x32_bf16 v[60:63], v[136:139], v[160:163], v[60:63]
	v_mfma_f32_16x16x32_bf16 v[40:43], v[128:131], v[184:187], v[40:43]
	v_mfma_f32_16x16x32_bf16 v[44:47], v[136:139], v[184:187], v[44:47]
	v_mfma_f32_16x16x32_bf16 v[24:27], v[128:131], v[192:195], v[24:27]
	v_mfma_f32_16x16x32_bf16 v[28:31], v[136:139], v[192:195], v[28:31]
	v_mfma_f32_16x16x32_bf16 v[8:11], v[128:131], v[204:207], v[8:11]
	v_mfma_f32_16x16x32_bf16 v[12:15], v[136:139], v[204:207], v[12:15]
	v_mfma_f32_16x16x32_bf16 v[56:59], v[132:135], v[180:183], v[56:59]
	v_mfma_f32_16x16x32_bf16 v[60:63], v[140:143], v[180:183], v[60:63]
	v_mfma_f32_16x16x32_bf16 v[40:43], v[132:135], v[188:191], v[40:43]
	v_mfma_f32_16x16x32_bf16 v[44:47], v[140:143], v[188:191], v[44:47]
	v_mfma_f32_16x16x32_bf16 v[24:27], v[132:135], v[200:203], v[24:27]
	v_mfma_f32_16x16x32_bf16 v[28:31], v[140:143], v[200:203], v[28:31]
	v_mfma_f32_16x16x32_bf16 v[8:11], v[132:135], v[208:211], v[8:11]
	v_mfma_f32_16x16x32_bf16 v[12:15], v[140:143], v[208:211], v[12:15]
	s_setprio 0
	s_setprio 1
	v_mfma_f32_16x16x32_bf16 v[48:51], v[144:147], v[160:163], v[48:51]
	v_mfma_f32_16x16x32_bf16 v[52:55], v[152:155], v[160:163], v[52:55]
	v_mfma_f32_16x16x32_bf16 v[32:35], v[144:147], v[184:187], v[32:35]
	v_mfma_f32_16x16x32_bf16 v[36:39], v[152:155], v[184:187], v[36:39]
	v_mfma_f32_16x16x32_bf16 v[16:19], v[144:147], v[192:195], v[16:19]
	v_mfma_f32_16x16x32_bf16 v[20:23], v[152:155], v[192:195], v[20:23]
	v_mfma_f32_16x16x32_bf16 v[0:3], v[144:147], v[204:207], v[0:3]
	v_mfma_f32_16x16x32_bf16 v[4:7], v[152:155], v[204:207], v[4:7]
	v_mfma_f32_16x16x32_bf16 v[48:51], v[148:151], v[180:183], v[48:51]
	v_mfma_f32_16x16x32_bf16 v[52:55], v[156:159], v[180:183], v[52:55]
	v_mfma_f32_16x16x32_bf16 v[32:35], v[148:151], v[188:191], v[32:35]
	v_mfma_f32_16x16x32_bf16 v[36:39], v[156:159], v[188:191], v[36:39]
	s_setprio 2
	s_barrier
	v_mfma_f32_16x16x32_bf16 v[16:19], v[148:151], v[200:203], v[16:19]
	v_mfma_f32_16x16x32_bf16 v[20:23], v[156:159], v[200:203], v[20:23]
	v_mfma_f32_16x16x32_bf16 v[0:3], v[148:151], v[208:211], v[0:3]
	v_mfma_f32_16x16x32_bf16 v[4:7], v[156:159], v[208:211], v[4:7]
	s_setprio 0
	s_add_i32 s54, 0, 0x18000
	s_add_i32 s55, 0, 0x1c000
	v_add_u32_e32 v140, s54, v196
	v_add_u32_e32 v156, s55, v196
	ds_read_b128 v[128:131], v140
	ds_read_b128 v[132:135], v140 offset:1024
	ds_read_b128 v[136:139], v140 offset:2048
	ds_read_b128 v[140:143], v140 offset:3072
	ds_read_b128 v[144:147], v156
	ds_read_b128 v[148:151], v156 offset:1024
	ds_read_b128 v[152:155], v156 offset:2048
	ds_read_b128 v[156:159], v156 offset:3072
	s_add_u32 s24, s28, 0xb0000
	s_addc_u32 s25, s29, 0
	s_mov_b32 m0, s38
	v_lshl_add_u64 v[220:221], s[24:25], 0, v[164:165]
	ds_read_b128 v[160:163], v199 offset:32768
	ds_read_b128 v[180:183], v199 offset:33792
	ds_read_b128 v[184:187], v199 offset:34816
	ds_read_b128 v[188:191], v199 offset:35840
	ds_read_b128 v[192:195], v199 offset:36864
	ds_read_b128 v[200:203], v199 offset:37888
	ds_read_b128 v[204:207], v199 offset:38912
	ds_read_b128 v[208:211], v199 offset:39936
	global_load_lds_dwordx4 v[220:221], off
	s_mov_b32 m0, s39
	v_lshl_add_u64 v[220:221], s[24:25], 0, v[168:169]
	global_load_lds_dwordx4 v[220:221], off
	s_waitcnt vmcnt(8)
	s_waitcnt lgkmcnt(0)
	s_barrier
	s_setprio 1
	s_waitcnt lgkmcnt(0)
	v_mfma_f32_16x16x32_bf16 v[124:127], v[128:131], v[160:163], v[124:127]
	v_mfma_f32_16x16x32_bf16 v[120:123], v[136:139], v[160:163], v[120:123]
	v_mfma_f32_16x16x32_bf16 v[116:119], v[128:131], v[184:187], v[116:119]
	v_mfma_f32_16x16x32_bf16 v[108:111], v[136:139], v[184:187], v[108:111]
	v_mfma_f32_16x16x32_bf16 v[88:91], v[128:131], v[192:195], v[88:91]
	v_mfma_f32_16x16x32_bf16 v[100:103], v[136:139], v[192:195], v[100:103]
	v_mfma_f32_16x16x32_bf16 v[72:75], v[128:131], v[204:207], v[72:75]
	v_mfma_f32_16x16x32_bf16 v[76:79], v[136:139], v[204:207], v[76:79]
	v_mfma_f32_16x16x32_bf16 v[124:127], v[132:135], v[180:183], v[124:127]
	v_mfma_f32_16x16x32_bf16 v[120:123], v[140:143], v[180:183], v[120:123]
	v_mfma_f32_16x16x32_bf16 v[116:119], v[132:135], v[188:191], v[116:119]
	v_mfma_f32_16x16x32_bf16 v[108:111], v[140:143], v[188:191], v[108:111]
	v_mfma_f32_16x16x32_bf16 v[88:91], v[132:135], v[200:203], v[88:91]
	v_mfma_f32_16x16x32_bf16 v[100:103], v[140:143], v[200:203], v[100:103]
	v_mfma_f32_16x16x32_bf16 v[72:75], v[132:135], v[208:211], v[72:75]
	v_mfma_f32_16x16x32_bf16 v[76:79], v[140:143], v[208:211], v[76:79]
	s_setprio 0
	s_setprio 1
	v_mfma_f32_16x16x32_bf16 v[112:115], v[144:147], v[160:163], v[112:115]
	v_mfma_f32_16x16x32_bf16 v[104:107], v[152:155], v[160:163], v[104:107]
	v_mfma_f32_16x16x32_bf16 v[96:99], v[144:147], v[184:187], v[96:99]
	v_mfma_f32_16x16x32_bf16 v[92:95], v[152:155], v[184:187], v[92:95]
	v_mfma_f32_16x16x32_bf16 v[80:83], v[144:147], v[192:195], v[80:83]
	v_mfma_f32_16x16x32_bf16 v[84:87], v[152:155], v[192:195], v[84:87]
	v_mfma_f32_16x16x32_bf16 v[64:67], v[144:147], v[204:207], v[64:67]
	v_mfma_f32_16x16x32_bf16 v[68:71], v[152:155], v[204:207], v[68:71]
	v_mfma_f32_16x16x32_bf16 v[112:115], v[148:151], v[180:183], v[112:115]
	v_mfma_f32_16x16x32_bf16 v[104:107], v[156:159], v[180:183], v[104:107]
	v_mfma_f32_16x16x32_bf16 v[96:99], v[148:151], v[188:191], v[96:99]
	v_mfma_f32_16x16x32_bf16 v[92:95], v[156:159], v[188:191], v[92:95]
	s_setprio 2
	s_barrier
	v_mfma_f32_16x16x32_bf16 v[80:83], v[148:151], v[200:203], v[80:83]
	v_mfma_f32_16x16x32_bf16 v[84:87], v[156:159], v[200:203], v[84:87]
	v_mfma_f32_16x16x32_bf16 v[64:67], v[148:151], v[208:211], v[64:67]
	v_mfma_f32_16x16x32_bf16 v[68:71], v[156:159], v[208:211], v[68:71]
	s_setprio 2
	s_add_i32 s24, s54, s35
	v_lshl_add_u64 v[212:213], v[212:213], 0, s[16:17]
	s_mov_b32 m0, s24
	ds_read_b128 v[160:163], v199 offset:49152
	ds_read_b128 v[180:183], v199 offset:50176
	ds_read_b128 v[184:187], v199 offset:51200
	ds_read_b128 v[188:191], v199 offset:52224
	ds_read_b128 v[192:195], v199 offset:53248
	ds_read_b128 v[200:203], v199 offset:54272
	ds_read_b128 v[204:207], v199 offset:55296
	ds_read_b128 v[208:211], v199 offset:56320
	global_load_lds_dwordx4 v[212:213], off
	s_add_i32 m0, s24, 0x2000
	s_add_u32 s24, s26, 0xb0080
	v_lshl_add_u64 v[212:213], v[214:215], 0, s[16:17]
	s_addc_u32 s25, s27, 0
	s_add_i32 s26, s55, s35
	global_load_lds_dwordx4 v[212:213], off
	s_mov_b32 m0, s26
	v_lshl_add_u64 v[212:213], s[24:25], 0, v[166:167]
	global_load_lds_dwordx4 v[212:213], off
	s_add_i32 m0, s26, 0x2000
	v_lshl_add_u64 v[212:213], s[24:25], 0, v[170:171]
	global_load_lds_dwordx4 v[212:213], off
	s_mov_b32 m0, s41
	v_lshl_add_u64 v[212:213], v[216:217], 0, s[16:17]
	global_load_lds_dwordx4 v[212:213], off
	s_mov_b32 m0, s42
	v_lshl_add_u64 v[212:213], v[218:219], 0, s[16:17]
	global_load_lds_dwordx4 v[212:213], off
	s_waitcnt vmcnt(8)
	s_waitcnt lgkmcnt(0)
	s_barrier
	s_setprio 1
	s_waitcnt lgkmcnt(0)
	v_mfma_f32_16x16x32_bf16 v[56:59], v[128:131], v[160:163], v[56:59]
	v_mfma_f32_16x16x32_bf16 v[60:63], v[136:139], v[160:163], v[60:63]
	v_mfma_f32_16x16x32_bf16 v[40:43], v[128:131], v[184:187], v[40:43]
	v_mfma_f32_16x16x32_bf16 v[44:47], v[136:139], v[184:187], v[44:47]
	v_mfma_f32_16x16x32_bf16 v[24:27], v[128:131], v[192:195], v[24:27]
	v_mfma_f32_16x16x32_bf16 v[28:31], v[136:139], v[192:195], v[28:31]
	v_mfma_f32_16x16x32_bf16 v[8:11], v[128:131], v[204:207], v[8:11]
	v_mfma_f32_16x16x32_bf16 v[12:15], v[136:139], v[204:207], v[12:15]
	v_mfma_f32_16x16x32_bf16 v[56:59], v[132:135], v[180:183], v[56:59]
	v_mfma_f32_16x16x32_bf16 v[60:63], v[140:143], v[180:183], v[60:63]
	v_mfma_f32_16x16x32_bf16 v[40:43], v[132:135], v[188:191], v[40:43]
	v_mfma_f32_16x16x32_bf16 v[44:47], v[140:143], v[188:191], v[44:47]
	v_mfma_f32_16x16x32_bf16 v[24:27], v[132:135], v[200:203], v[24:27]
	v_mfma_f32_16x16x32_bf16 v[28:31], v[140:143], v[200:203], v[28:31]
	v_mfma_f32_16x16x32_bf16 v[8:11], v[132:135], v[208:211], v[8:11]
	v_mfma_f32_16x16x32_bf16 v[12:15], v[140:143], v[208:211], v[12:15]
	s_setprio 0
	s_setprio 1
	v_mfma_f32_16x16x32_bf16 v[48:51], v[144:147], v[160:163], v[48:51]
	v_mfma_f32_16x16x32_bf16 v[52:55], v[152:155], v[160:163], v[52:55]
	v_mfma_f32_16x16x32_bf16 v[32:35], v[144:147], v[184:187], v[32:35]
	v_mfma_f32_16x16x32_bf16 v[36:39], v[152:155], v[184:187], v[36:39]
	v_mfma_f32_16x16x32_bf16 v[16:19], v[144:147], v[192:195], v[16:19]
	v_mfma_f32_16x16x32_bf16 v[20:23], v[152:155], v[192:195], v[20:23]
	v_mfma_f32_16x16x32_bf16 v[0:3], v[144:147], v[204:207], v[0:3]
	v_mfma_f32_16x16x32_bf16 v[4:7], v[152:155], v[204:207], v[4:7]
	v_mfma_f32_16x16x32_bf16 v[48:51], v[148:151], v[180:183], v[48:51]
	v_mfma_f32_16x16x32_bf16 v[52:55], v[156:159], v[180:183], v[52:55]
	v_mfma_f32_16x16x32_bf16 v[32:35], v[148:151], v[188:191], v[32:35]
	v_mfma_f32_16x16x32_bf16 v[36:39], v[156:159], v[188:191], v[36:39]
	s_setprio 2
	s_barrier
	v_mfma_f32_16x16x32_bf16 v[16:19], v[148:151], v[200:203], v[16:19]
	v_mfma_f32_16x16x32_bf16 v[20:23], v[156:159], v[200:203], v[20:23]
	v_mfma_f32_16x16x32_bf16 v[0:3], v[148:151], v[208:211], v[0:3]
	v_mfma_f32_16x16x32_bf16 v[4:7], v[156:159], v[208:211], v[4:7]
	s_setprio 0
	s_add_i32 s53, s53, 2
	s_add_u32 s51, s51, 0x100
	s_addc_u32 s52, s52, 0
	s_cmp_gt_u32 s53, 41
	s_mov_b64 s[24:25], s[4:5]
	s_cbranch_scc0 .LBB0_1310
